# stack on v2: loop back-edge rotation in all K-loops, LDS read-address adds hoisted out of loops, W1 epilogue rewritten with row-scale loads issued before the K-loop
# baseline (speedup 1.0000x reference)
; #define PG8_STAGE(bufoff, gbase, voff) do { _Pragma("unroll") for (int _i = 0; _i < 2; ++_i) \
;         __builtin_amdgcn_global_load_lds((const unsigned*)((const char*)(gbase) + (voff)[_i]), (LAS unsigned*)(lds + (bufoff) + ldsw + _i * 8192), 16, 0, 0); } while (0)
; #define PG8_LDA(dst, b, h) do { _Pragma("unroll") for (int m = 0; m < 4; ++m) _Pragma("unroll") for (int k = 0; k < 2; ++k) dst[m][k] = *(const LAS bf16x8*)(lds + PG8_SA(b, h) + aoff + m * 2048 + k * 1024); } while (0)
; #define PG8_LDB(dst, b, h) do { _Pragma("unroll") for (int n = 0; n < 2; ++n) _Pragma("unroll") for (int k = 0; k < 2; ++k) dst[n][k] = *(const LAS bf16x8*)(lds + PG8_SB(b, h) + boff + n * 2048 + k * 1024); } while (0)
; #define PG8_MMA(ai, bj, At, Bt) do { __builtin_amdgcn_s_setprio(1); _Pragma("unroll") for (int m = 0; m < 4; ++m) _Pragma("unroll") for (int n = 0; n < 2; ++n) _Pragma("unroll") for (int k = 0; k < 2; ++k) \
;         acc[ai][bj][m][n] = __builtin_amdgcn_mfma_f32_16x16x32_bf16(Bt[n][k], At[m][k], acc[ai][bj][m][n], 0, 0, 0); __builtin_amdgcn_s_setprio(0); } while (0)
; #define PG8_WAIT_V(n) asm volatile("s_waitcnt vmcnt(" #n ")" ::: "memory")
; #define PG8_WAIT_L(n) asm volatile("s_waitcnt lgkmcnt(" #n ")" ::: "memory")
; #define PG8_BAR __builtin_amdgcn_s_barrier()
; #define PG8_SCHED __builtin_amdgcn_sched_barrier(0)
; template <class Epi, class Sched>
; __device__ __forceinline__ void gemm_phase(LAS unsigned char* lds_in, const int lda, const int ldb, const Sched& S, const Epi& E, const int WID) {
;     ...
;             PG8_LDB(B0, 0, 0); PG8_SCHED; PG8_LDA(At, 0, 0); PG8_STAGE(PG8_SA(1, 1), a1 + hstepA, voffA);
;             PG8_WAIT_L(8); PG8_BAR; PG8_WAIT_L(0); PG8_MMA(0, 0, At, B0); PG8_BAR; PG8_SCHED;
;             PG8_LDB(B1, 0, 1); PG8_STAGE(PG8_SB(0, 0), b2, voffB);
;             PG8_BAR; PG8_WAIT_L(0); PG8_MMA(0, 1, At, B1); PG8_BAR;
;             PG8_LDA(At, 0, 1); PG8_STAGE(PG8_SA(0, 0), a2, voffA);
;             PG8_BAR; PG8_WAIT_L(0); PG8_MMA(1, 0, At, B0); PG8_BAR; PG8_SCHED;
;             PG8_STAGE(PG8_SB(0, 1), b2 + hstepB, voffB);
;             PG8_WAIT_V(6); PG8_BAR; PG8_MMA(1, 1, At, B1); PG8_BAR;
.LBB0_151:
	s_barrier
	ds_read_b128 v[66:69], v227
	ds_read_b128 v[70:73], v227 offset:1024
	ds_read_b128 v[82:85], v227 offset:2048
	ds_read_b128 v[94:97], v227 offset:3072
	s_add_u32 s20, s6, 0xffe00080
	s_addc_u32 s21, s7, -1
	s_cmpk_eq_i32 vcc_lo, 0x7c
	s_cselect_b32 s23, s17, s21
	s_cselect_b32 s22, s16, s20
	s_cselect_b32 s21, s19, s15
	s_cselect_b32 s20, s18, s5
	s_add_i32 m0, s50, 0xc000
	ds_read_b128 v[106:109], v228
	ds_read_b128 v[118:121], v228 offset:1024
	ds_read_b128 v[130:133], v228 offset:2048
	ds_read_b128 v[142:145], v228 offset:3072
	ds_read_b128 v[154:157], v228 offset:4096
	ds_read_b128 v[166:169], v228 offset:5120
	ds_read_b128 v[170:173], v228 offset:6144
	ds_read_b128 v[174:177], v228 offset:7168
	global_load_lds_dwordx4 v198, s[6:7]
	s_add_i32 m0, s50, 0xe000
	s_nop 0
	global_load_lds_dwordx4 v200, s[6:7]
	s_waitcnt lgkmcnt(8)
	s_barrier
	s_waitcnt lgkmcnt(0)
	s_setprio 1
	s_waitcnt lgkmcnt(0)
	v_mfma_f32_16x16x32_bf16 v[162:165], v[66:69], v[106:109], v[162:165]
	v_mfma_f32_16x16x32_bf16 v[158:161], v[82:85], v[106:109], v[158:161]
	v_mfma_f32_16x16x32_bf16 v[138:141], v[66:69], v[130:133], v[138:141]
	v_mfma_f32_16x16x32_bf16 v[134:137], v[82:85], v[130:133], v[134:137]
	v_mfma_f32_16x16x32_bf16 v[114:117], v[66:69], v[154:157], v[114:117]
	v_mfma_f32_16x16x32_bf16 v[110:113], v[82:85], v[154:157], v[110:113]
	v_mfma_f32_16x16x32_bf16 v[90:93], v[66:69], v[170:173], v[90:93]
	v_mfma_f32_16x16x32_bf16 v[86:89], v[82:85], v[170:173], v[86:89]
	v_mfma_f32_16x16x32_bf16 v[162:165], v[70:73], v[118:121], v[162:165]
	v_mfma_f32_16x16x32_bf16 v[158:161], v[94:97], v[118:121], v[158:161]
	v_mfma_f32_16x16x32_bf16 v[138:141], v[70:73], v[142:145], v[138:141]
	v_mfma_f32_16x16x32_bf16 v[134:137], v[94:97], v[142:145], v[134:137]
	v_mfma_f32_16x16x32_bf16 v[114:117], v[70:73], v[166:169], v[114:117]
	v_mfma_f32_16x16x32_bf16 v[110:113], v[94:97], v[166:169], v[110:113]
	v_mfma_f32_16x16x32_bf16 v[90:93], v[70:73], v[174:177], v[90:93]
	v_mfma_f32_16x16x32_bf16 v[86:89], v[94:97], v[174:177], v[86:89]
	s_setprio 0
	s_barrier
	s_mov_b32 m0, s48
	ds_read_b128 v[178:181], v229
	ds_read_b128 v[182:185], v229 offset:1024
	ds_read_b128 v[186:189], v229 offset:2048
	ds_read_b128 v[202:205], v229 offset:3072
	global_load_lds_dwordx4 v192, s[20:21]
	s_mov_b32 m0, s49
	s_nop 0
	global_load_lds_dwordx4 v196, s[20:21]
	s_barrier
	s_waitcnt lgkmcnt(0)
	s_setprio 1
	s_waitcnt lgkmcnt(0)
	v_mfma_f32_16x16x32_bf16 v[150:153], v[178:181], v[106:109], v[150:153]
	v_mfma_f32_16x16x32_bf16 v[106:109], v[186:189], v[106:109], v[146:149]
	v_mfma_f32_16x16x32_bf16 v[122:125], v[186:189], v[130:133], v[122:125]
	v_mfma_f32_16x16x32_bf16 v[102:105], v[178:181], v[154:157], v[102:105]
	v_mfma_f32_16x16x32_bf16 v[98:101], v[186:189], v[154:157], v[98:101]
	v_mfma_f32_16x16x32_bf16 v[78:81], v[178:181], v[170:173], v[78:81]
	v_mfma_f32_16x16x32_bf16 v[74:77], v[186:189], v[170:173], v[74:77]
	v_mfma_f32_16x16x32_bf16 v[150:153], v[182:185], v[118:121], v[150:153]
	v_mfma_f32_16x16x32_bf16 v[106:109], v[202:205], v[118:121], v[106:109]
	v_mfma_f32_16x16x32_bf16 v[118:121], v[178:181], v[130:133], v[126:129]
	v_mfma_f32_16x16x32_bf16 v[122:125], v[202:205], v[142:145], v[122:125]
	v_mfma_f32_16x16x32_bf16 v[102:105], v[182:185], v[166:169], v[102:105]
	v_mfma_f32_16x16x32_bf16 v[98:101], v[202:205], v[166:169], v[98:101]
	v_mfma_f32_16x16x32_bf16 v[78:81], v[182:185], v[174:177], v[78:81]
	v_mfma_f32_16x16x32_bf16 v[74:77], v[202:205], v[174:177], v[74:77]
	v_mfma_f32_16x16x32_bf16 v[118:121], v[182:185], v[142:145], v[118:121]
	s_setprio 0
	s_mov_b32 m0, s50
	s_barrier
	ds_read_b128 v[126:129], v228 offset:16384
	ds_read_b128 v[130:133], v228 offset:17408
	ds_read_b128 v[142:145], v228 offset:18432
	ds_read_b128 v[146:149], v228 offset:19456
	ds_read_b128 v[154:157], v228 offset:20480
	ds_read_b128 v[166:169], v228 offset:21504
	ds_read_b128 v[170:173], v228 offset:22528
	ds_read_b128 v[174:177], v228 offset:23552
	global_load_lds_dwordx4 v190, s[22:23]
	s_mov_b32 m0, s51
	s_nop 0
	global_load_lds_dwordx4 v194, s[22:23]
	s_barrier
	s_waitcnt lgkmcnt(0)
	s_setprio 1
	s_waitcnt lgkmcnt(0)
	v_mfma_f32_16x16x32_bf16 v[62:65], v[66:69], v[126:129], v[62:65]
	v_mfma_f32_16x16x32_bf16 v[58:61], v[82:85], v[126:129], v[58:61]
	v_mfma_f32_16x16x32_bf16 v[46:49], v[66:69], v[142:145], v[46:49]
	v_mfma_f32_16x16x32_bf16 v[42:45], v[82:85], v[142:145], v[42:45]
	v_mfma_f32_16x16x32_bf16 v[30:33], v[66:69], v[154:157], v[30:33]
	v_mfma_f32_16x16x32_bf16 v[26:29], v[82:85], v[154:157], v[26:29]
	v_mfma_f32_16x16x32_bf16 v[14:17], v[66:69], v[170:173], v[14:17]
	v_mfma_f32_16x16x32_bf16 v[10:13], v[82:85], v[170:173], v[10:13]
	v_mfma_f32_16x16x32_bf16 v[62:65], v[70:73], v[130:133], v[62:65]
	v_mfma_f32_16x16x32_bf16 v[58:61], v[94:97], v[130:133], v[58:61]
	v_mfma_f32_16x16x32_bf16 v[46:49], v[70:73], v[146:149], v[46:49]
	v_mfma_f32_16x16x32_bf16 v[42:45], v[94:97], v[146:149], v[42:45]
	v_mfma_f32_16x16x32_bf16 v[30:33], v[70:73], v[166:169], v[30:33]
	v_mfma_f32_16x16x32_bf16 v[26:29], v[94:97], v[166:169], v[26:29]
	v_mfma_f32_16x16x32_bf16 v[14:17], v[70:73], v[174:177], v[14:17]
	v_mfma_f32_16x16x32_bf16 v[10:13], v[94:97], v[174:177], v[10:13]
	s_setprio 0
	s_barrier
	s_add_u32 s66, s20, 0x200000
	s_addc_u32 s67, s21, 0
	s_mov_b32 m0, s65
	s_nop 0
	global_load_lds_dwordx4 v192, s[66:67]
	s_mov_b32 m0, s70
	s_nop 0
	global_load_lds_dwordx4 v196, s[66:67]
	s_waitcnt vmcnt(6)
	s_barrier
; #define PG8_STAGE(bufoff, gbase, voff) do { _Pragma("unroll") for (int _i = 0; _i < 2; ++_i) \
;         __builtin_amdgcn_global_load_lds((const unsigned*)((const char*)(gbase) + (voff)[_i]), (LAS unsigned*)(lds + (bufoff) + ldsw + _i * 8192), 16, 0, 0); } while (0)
; #define PG8_LDA(dst, b, h) do { _Pragma("unroll") for (int m = 0; m < 4; ++m) _Pragma("unroll") for (int k = 0; k < 2; ++k) dst[m][k] = *(const LAS bf16x8*)(lds + PG8_SA(b, h) + aoff + m * 2048 + k * 1024); } while (0)
; #define PG8_LDB(dst, b, h) do { _Pragma("unroll") for (int n = 0; n < 2; ++n) _Pragma("unroll") for (int k = 0; k < 2; ++k) dst[n][k] = *(const LAS bf16x8*)(lds + PG8_SB(b, h) + boff + n * 2048 + k * 1024); } while (0)
; #define PG8_MMA(ai, bj, At, Bt) do { __builtin_amdgcn_s_setprio(1); _Pragma("unroll") for (int m = 0; m < 4; ++m) _Pragma("unroll") for (int n = 0; n < 2; ++n) _Pragma("unroll") for (int k = 0; k < 2; ++k) \
;         acc[ai][bj][m][n] = __builtin_amdgcn_mfma_f32_16x16x32_bf16(Bt[n][k], At[m][k], acc[ai][bj][m][n], 0, 0, 0); __builtin_amdgcn_s_setprio(0); } while (0)
; #define PG8_WAIT_V(n) asm volatile("s_waitcnt vmcnt(" #n ")" ::: "memory")
; #define PG8_WAIT_L(n) asm volatile("s_waitcnt lgkmcnt(" #n ")" ::: "memory")
; #define PG8_BAR __builtin_amdgcn_s_barrier()
; #define PG8_SCHED __builtin_amdgcn_sched_barrier(0)
; template <class Epi, class Sched>
; __device__ __forceinline__ void gemm_phase(LAS unsigned char* lds_in, const int lda, const int ldb, const Sched& S, const Epi& E, const int WID) {
;     ...
;             PG8_WAIT_V(6); PG8_BAR; PG8_MMA(1, 1, At, B1); PG8_BAR;
;             PG8_LDB(B0, 1, 0); PG8_SCHED; PG8_LDA(At, 1, 0); PG8_STAGE(PG8_SA(0, 1), a2 + hstepA, voffA);
;             PG8_WAIT_L(8); PG8_BAR; PG8_WAIT_L(0); PG8_MMA(0, 0, At, B0); PG8_BAR; PG8_SCHED;
;             PG8_LDB(B1, 1, 1); PG8_STAGE(PG8_SB(1, 0), b3, voffB);
;             PG8_BAR; PG8_WAIT_L(0); PG8_MMA(0, 1, At, B1); PG8_BAR;
;             PG8_LDA(At, 1, 1); PG8_STAGE(PG8_SA(1, 0), a3, voffA);
;             PG8_BAR; PG8_WAIT_L(0); PG8_MMA(1, 0, At, B0); PG8_BAR; PG8_SCHED;
	s_setprio 1
	v_mfma_f32_16x16x32_bf16 v[54:57], v[178:181], v[126:129], v[54:57]
	v_mfma_f32_16x16x32_bf16 v[50:53], v[186:189], v[126:129], v[50:53]
	v_mfma_f32_16x16x32_bf16 v[38:41], v[178:181], v[142:145], v[38:41]
	v_mfma_f32_16x16x32_bf16 v[34:37], v[186:189], v[142:145], v[34:37]
	v_mfma_f32_16x16x32_bf16 v[22:25], v[178:181], v[154:157], v[22:25]
	v_mfma_f32_16x16x32_bf16 v[18:21], v[186:189], v[154:157], v[18:21]
	v_mfma_f32_16x16x32_bf16 v[6:9], v[178:181], v[170:173], v[6:9]
	v_mfma_f32_16x16x32_bf16 v[2:5], v[186:189], v[170:173], v[2:5]
	v_mfma_f32_16x16x32_bf16 v[54:57], v[182:185], v[130:133], v[54:57]
	v_mfma_f32_16x16x32_bf16 v[50:53], v[202:205], v[130:133], v[50:53]
	v_mfma_f32_16x16x32_bf16 v[38:41], v[182:185], v[146:149], v[38:41]
	v_mfma_f32_16x16x32_bf16 v[34:37], v[202:205], v[146:149], v[34:37]
	v_mfma_f32_16x16x32_bf16 v[22:25], v[182:185], v[166:169], v[22:25]
	v_mfma_f32_16x16x32_bf16 v[18:21], v[202:205], v[166:169], v[18:21]
	v_mfma_f32_16x16x32_bf16 v[6:9], v[182:185], v[174:177], v[6:9]
	v_mfma_f32_16x16x32_bf16 v[2:5], v[202:205], v[174:177], v[2:5]
	s_setprio 0
	s_barrier
	ds_read_b128 v[66:69], v230
	ds_read_b128 v[70:73], v230 offset:1024
	ds_read_b128 v[82:85], v230 offset:2048
	ds_read_b128 v[94:97], v230 offset:3072
	s_add_u32 s22, s22, 0x200000
	s_addc_u32 s23, s23, 0
	s_mov_b32 m0, s78
	ds_read_b128 v[126:129], v228 offset:32768
	ds_read_b128 v[130:133], v228 offset:33792
	ds_read_b128 v[142:145], v228 offset:34816
	ds_read_b128 v[154:157], v228 offset:35840
	ds_read_b128 v[166:169], v228 offset:36864
	ds_read_b128 v[170:173], v228 offset:37888
	ds_read_b128 v[174:177], v228 offset:38912
	ds_read_b128 v[178:181], v228 offset:39936
	global_load_lds_dwordx4 v190, s[22:23]
	s_mov_b32 m0, s79
	s_nop 0
	global_load_lds_dwordx4 v194, s[22:23]
	s_waitcnt lgkmcnt(8)
	s_barrier
	s_waitcnt lgkmcnt(0)
	s_setprio 1
	s_waitcnt lgkmcnt(0)
	v_mfma_f32_16x16x32_bf16 v[146:149], v[66:69], v[126:129], v[162:165]
	v_mfma_f32_16x16x32_bf16 v[162:165], v[70:73], v[130:133], v[146:149]
	v_mfma_f32_16x16x32_bf16 v[146:149], v[82:85], v[126:129], v[158:161]
	v_mfma_f32_16x16x32_bf16 v[138:141], v[66:69], v[142:145], v[138:141]
	v_mfma_f32_16x16x32_bf16 v[134:137], v[82:85], v[142:145], v[134:137]
	v_mfma_f32_16x16x32_bf16 v[114:117], v[66:69], v[166:169], v[114:117]
	v_mfma_f32_16x16x32_bf16 v[110:113], v[82:85], v[166:169], v[110:113]
	v_mfma_f32_16x16x32_bf16 v[90:93], v[66:69], v[174:177], v[90:93]
	v_mfma_f32_16x16x32_bf16 v[86:89], v[82:85], v[174:177], v[86:89]
	v_mfma_f32_16x16x32_bf16 v[158:161], v[94:97], v[130:133], v[146:149]
	v_mfma_f32_16x16x32_bf16 v[138:141], v[70:73], v[154:157], v[138:141]
	v_mfma_f32_16x16x32_bf16 v[134:137], v[94:97], v[154:157], v[134:137]
	v_mfma_f32_16x16x32_bf16 v[114:117], v[70:73], v[170:173], v[114:117]
	v_mfma_f32_16x16x32_bf16 v[110:113], v[94:97], v[170:173], v[110:113]
	v_mfma_f32_16x16x32_bf16 v[90:93], v[70:73], v[178:181], v[90:93]
	v_mfma_f32_16x16x32_bf16 v[86:89], v[94:97], v[178:181], v[86:89]
	s_setprio 0
	s_barrier
	s_mov_b32 m0, s91
	s_add_u32 s100, s20, 0x80
	s_addc_u32 s101, s21, 0
	ds_read_b128 v[182:185], v231
	ds_read_b128 v[186:189], v231 offset:1024
	ds_read_b128 v[202:205], v231 offset:2048
	ds_read_b128 v[206:209], v231 offset:3072
	global_load_lds_dwordx4 v192, s[100:101]
	s_add_u32 s100, s20, 0x80
	s_addc_u32 s101, s21, 0
	s_mov_b32 m0, s92
	s_nop 0
	global_load_lds_dwordx4 v196, s[100:101]
	s_barrier
	s_waitcnt lgkmcnt(0)
	s_setprio 1
	s_waitcnt lgkmcnt(0)
	v_mfma_f32_16x16x32_bf16 v[146:149], v[182:185], v[126:129], v[150:153]
	v_mfma_f32_16x16x32_bf16 v[106:109], v[202:205], v[126:129], v[106:109]
	v_mfma_f32_16x16x32_bf16 v[150:153], v[186:189], v[130:133], v[146:149]
	v_mfma_f32_16x16x32_bf16 v[146:149], v[206:209], v[130:133], v[106:109]
	v_mfma_f32_16x16x32_bf16 v[106:109], v[182:185], v[142:145], v[118:121]
	v_mfma_f32_16x16x32_bf16 v[126:129], v[186:189], v[154:157], v[106:109]
	v_mfma_f32_16x16x32_bf16 v[106:109], v[202:205], v[142:145], v[122:125]
	v_mfma_f32_16x16x32_bf16 v[102:105], v[182:185], v[166:169], v[102:105]
	v_mfma_f32_16x16x32_bf16 v[98:101], v[202:205], v[166:169], v[98:101]
	v_mfma_f32_16x16x32_bf16 v[78:81], v[182:185], v[174:177], v[78:81]
	v_mfma_f32_16x16x32_bf16 v[74:77], v[202:205], v[174:177], v[74:77]
	v_mfma_f32_16x16x32_bf16 v[122:125], v[206:209], v[154:157], v[106:109]
	v_mfma_f32_16x16x32_bf16 v[102:105], v[186:189], v[170:173], v[102:105]
	v_mfma_f32_16x16x32_bf16 v[98:101], v[206:209], v[170:173], v[98:101]
	v_mfma_f32_16x16x32_bf16 v[78:81], v[186:189], v[178:181], v[78:81]
	v_mfma_f32_16x16x32_bf16 v[74:77], v[206:209], v[178:181], v[74:77]
	s_setprio 0
	s_mov_b32 m0, s93
	s_add_u32 s100, s22, 0xffe00080
	s_addc_u32 s101, s23, -1
	s_barrier
	ds_read_b128 v[106:109], v228 offset:49152
	ds_read_b128 v[118:121], v228 offset:50176
	ds_read_b128 v[130:133], v228 offset:51200
	ds_read_b128 v[142:145], v228 offset:52224
	ds_read_b128 v[154:157], v228 offset:53248
	ds_read_b128 v[166:169], v228 offset:54272
	ds_read_b128 v[170:173], v228 offset:55296
	ds_read_b128 v[174:177], v228 offset:56320
	global_load_lds_dwordx4 v190, s[100:101]
	s_add_u32 s100, s22, 0xffe00080
	s_addc_u32 s101, s23, -1
	s_mov_b32 m0, s94
	s_nop 0
	global_load_lds_dwordx4 v194, s[100:101]
	s_barrier
; __device__ __forceinline__ u32x4 pack8(const f32x4 a, const f32x4 b) { u32x4 w; w.x = cvt_pk_bf16(a[0], a[1]); w.y = cvt_pk_bf16(a[2], a[3]); w.z = cvt_pk_bf16(b[0], b[1]); w.w = cvt_pk_bf16(b[2], b[3]); return w; }
; __device__ __forceinline__ void unpack8(const u32x4 w, f32x4& a, f32x4& b) { a[0] = bf_lo(w.x); a[1] = bf_hi(w.x); a[2] = bf_lo(w.y); a[3] = bf_hi(w.y); b[0] = bf_lo(w.z); b[1] = bf_hi(w.z); b[2] = bf_lo(w.w); b[3] = bf_hi(w.w); }
; #define PG8_STAGE(bufoff, gbase, voff) do { _Pragma("unroll") for (int _i = 0; _i < 2; ++_i) \
;         __builtin_amdgcn_global_load_lds((const unsigned*)((const char*)(gbase) + (voff)[_i]), (LAS unsigned*)(lds + (bufoff) + ldsw + _i * 8192), 16, 0, 0); } while (0)
; #define PG8_BAR __builtin_amdgcn_s_barrier()
; template <class Epi, class Sched>
; __device__ __forceinline__ void gemm_phase(LAS unsigned char* lds_in, const int lda, const int ldb, const Sched& S, const Epi& E, const int WID) {
;     ...
;             PG8_BAR; PG8_WAIT_L(0); PG8_MMA(1, 0, At, B0); PG8_BAR; PG8_SCHED;
;             PG8_STAGE(PG8_SB(1, 1), b3 + hstepB, voffB);
;             PG8_WAIT_V(6); PG8_BAR; PG8_MMA(1, 1, At, B1); PG8_BAR;
;     __device__ __forceinline__ void operator()(const AccT& acc, const Unit& u, int wr, int wc, int fr, int fq) const {
;         int row0 = u.pm * 256 + wr * 64 + fr, col0 = u.pn * 256 + wc * 32 + 8 * fq;
;         asm volatile("" : "+v"(row0), "+v"(col0));
;         u32x4 bw[2][4][2];
; #pragma unroll
;         for (int ai = 0; ai < 2; ++ai)
; #pragma unroll
;             for (int m = 0; m < 4; ++m)
; #pragma unroll
;                 for (int bj = 0; bj < 2; ++bj) bw[ai][m][bj] = *(const u32x4*)(Hb + (size_t)(row0 + ai * 128 + m * 16) * 2048 + col0 + bj * 128);
; #pragma unroll
;         for (int ai = 0; ai < 2; ++ai) {
; #pragma unroll
;             for (int m = 0; m < 4; ++m) {
;                 const int row = row0 + ai * 128 + m * 16; const size_t off = (size_t)row * 2048 + col0; float ss = 0.f;
; #pragma unroll
;                 for (int bj = 0; bj < 2; ++bj) {
;                     f32x4 b0, b1; unpack8(bw[ai][m][bj], b0, b1);
;                     const f32x4 o0 = b0 + acc[ai][bj][m][0], o1 = b1 + acc[ai][bj][m][1];
;                     if (outF) { *(f32x4*)(outF + off + bj * 128) = o0; *(f32x4*)(outF + off + bj * 128 + 4) = o1; }
;                     else { *(u32x4*)(Hb + off + bj * 128) = pack8(o0, o1);
	s_waitcnt lgkmcnt(0)
	s_setprio 1
	s_waitcnt lgkmcnt(0)
	v_mfma_f32_16x16x32_bf16 v[62:65], v[66:69], v[106:109], v[62:65]
	v_mfma_f32_16x16x32_bf16 v[58:61], v[82:85], v[106:109], v[58:61]
	v_mfma_f32_16x16x32_bf16 v[46:49], v[66:69], v[130:133], v[46:49]
	v_mfma_f32_16x16x32_bf16 v[42:45], v[82:85], v[130:133], v[42:45]
	v_mfma_f32_16x16x32_bf16 v[30:33], v[66:69], v[154:157], v[30:33]
	v_mfma_f32_16x16x32_bf16 v[26:29], v[82:85], v[154:157], v[26:29]
	v_mfma_f32_16x16x32_bf16 v[14:17], v[66:69], v[170:173], v[14:17]
	v_mfma_f32_16x16x32_bf16 v[10:13], v[82:85], v[170:173], v[10:13]
	v_mfma_f32_16x16x32_bf16 v[62:65], v[70:73], v[118:121], v[62:65]
	v_mfma_f32_16x16x32_bf16 v[58:61], v[94:97], v[118:121], v[58:61]
	v_mfma_f32_16x16x32_bf16 v[46:49], v[70:73], v[142:145], v[46:49]
	v_mfma_f32_16x16x32_bf16 v[42:45], v[94:97], v[142:145], v[42:45]
	v_mfma_f32_16x16x32_bf16 v[30:33], v[70:73], v[166:169], v[30:33]
	v_mfma_f32_16x16x32_bf16 v[26:29], v[94:97], v[166:169], v[26:29]
	v_mfma_f32_16x16x32_bf16 v[14:17], v[70:73], v[174:177], v[14:17]
	v_mfma_f32_16x16x32_bf16 v[10:13], v[94:97], v[174:177], v[10:13]
	s_setprio 0
	s_barrier
	s_add_u32 s20, s20, 0x200080
	s_addc_u32 s21, s21, 0
	s_mov_b32 m0, s95
	s_nop 0
	global_load_lds_dwordx4 v192, s[20:21]
	s_mov_b32 m0, s96
	s_nop 0
	global_load_lds_dwordx4 v196, s[20:21]
	s_waitcnt vmcnt(6)
	s_barrier
	s_setprio 1
	v_mfma_f32_16x16x32_bf16 v[54:57], v[182:185], v[106:109], v[54:57]
	v_mfma_f32_16x16x32_bf16 v[50:53], v[202:205], v[106:109], v[50:53]
	v_mfma_f32_16x16x32_bf16 v[38:41], v[182:185], v[130:133], v[38:41]
	v_mfma_f32_16x16x32_bf16 v[34:37], v[202:205], v[130:133], v[34:37]
	v_mfma_f32_16x16x32_bf16 v[22:25], v[182:185], v[154:157], v[22:25]
	v_mfma_f32_16x16x32_bf16 v[18:21], v[202:205], v[154:157], v[18:21]
	v_mfma_f32_16x16x32_bf16 v[6:9], v[182:185], v[170:173], v[6:9]
	v_mfma_f32_16x16x32_bf16 v[2:5], v[202:205], v[170:173], v[2:5]
	v_mfma_f32_16x16x32_bf16 v[54:57], v[186:189], v[118:121], v[54:57]
	v_mfma_f32_16x16x32_bf16 v[50:53], v[206:209], v[118:121], v[50:53]
	v_mfma_f32_16x16x32_bf16 v[38:41], v[186:189], v[142:145], v[38:41]
	v_mfma_f32_16x16x32_bf16 v[34:37], v[206:209], v[142:145], v[34:37]
	v_mfma_f32_16x16x32_bf16 v[22:25], v[186:189], v[166:169], v[22:25]
	v_mfma_f32_16x16x32_bf16 v[18:21], v[206:209], v[166:169], v[18:21]
	v_mfma_f32_16x16x32_bf16 v[6:9], v[186:189], v[174:177], v[6:9]
	v_mfma_f32_16x16x32_bf16 v[2:5], v[206:209], v[174:177], v[2:5]
	s_setprio 0
	s_add_i32 vcc_lo, vcc_lo, 2
	s_add_u32 s6, s6, 0x100
	s_addc_u32 s7, s7, 0
	s_add_u32 s5, s5, 0x100
	s_addc_u32 s15, s15, 0
	s_cmpk_gt_u32 vcc_lo, 0x7d
	s_cbranch_scc0 .LBB0_151
	v_lshl_add_u32 v220, s4, 8, v1
	v_lshl_or_b32 v206, s97, 8, v226
	v_cndmask_b32_e64 v222, 0, 1, s[10:11]
	v_ashrrev_i32_e32 v207, 31, v206
	v_ashrrev_i32_e32 v221, 31, v220
	v_lshl_add_u64 v[204:205], v[206:207], 1, s[28:29]
	v_lshlrev_b64 v[66:67], 12, v[220:221]
	v_add_u32_e32 v218, 16, v220
	v_lshl_add_u64 v[66:67], v[204:205], 0, v[66:67]
	v_ashrrev_i32_e32 v219, 31, v218
	global_load_dwordx4 v[232:235], v[66:67], off
	global_load_dwordx4 v[186:189], v[66:67], off offset:256
	v_lshlrev_b64 v[66:67], 12, v[218:219]
	v_add_u32_e32 v216, 32, v220
	v_lshl_add_u64 v[66:67], v[204:205], 0, v[66:67]
	v_ashrrev_i32_e32 v217, 31, v216
	global_load_dwordx4 v[182:185], v[66:67], off
	global_load_dwordx4 v[178:181], v[66:67], off offset:256
	v_lshlrev_b64 v[66:67], 12, v[216:217]
	v_add_u32_e32 v214, 48, v220
	v_lshl_add_u64 v[66:67], v[204:205], 0, v[66:67]
	v_ashrrev_i32_e32 v215, 31, v214
	global_load_dwordx4 v[174:177], v[66:67], off
	global_load_dwordx4 v[170:173], v[66:67], off offset:256
	v_lshlrev_b64 v[66:67], 12, v[214:215]
	v_add_u32_e32 v212, 0x80, v220
	v_lshl_add_u64 v[66:67], v[204:205], 0, v[66:67]
	v_ashrrev_i32_e32 v213, 31, v212
	global_load_dwordx4 v[166:169], v[66:67], off
	global_load_dwordx4 v[154:157], v[66:67], off offset:256
	v_lshlrev_b64 v[66:67], 12, v[212:213]
	v_add_u32_e32 v210, 0x90, v220
	v_lshl_add_u64 v[66:67], v[204:205], 0, v[66:67]
	v_ashrrev_i32_e32 v211, 31, v210
	global_load_dwordx4 v[142:145], v[66:67], off
	global_load_dwordx4 v[130:133], v[66:67], off offset:256
	v_lshlrev_b64 v[66:67], 12, v[210:211]
	v_add_u32_e32 v208, 0xa0, v220
	v_lshl_add_u64 v[66:67], v[204:205], 0, v[66:67]
	v_ashrrev_i32_e32 v209, 31, v208
	global_load_dwordx4 v[118:121], v[66:67], off
	global_load_dwordx4 v[106:109], v[66:67], off offset:256
	v_lshlrev_b64 v[66:67], 12, v[208:209]
	v_add_u32_e32 v202, 0xb0, v220
	v_lshl_add_u64 v[66:67], v[204:205], 0, v[66:67]
	v_ashrrev_i32_e32 v203, 31, v202
	global_load_dwordx4 v[94:97], v[66:67], off
	global_load_dwordx4 v[82:85], v[66:67], off offset:256
	v_lshlrev_b64 v[66:67], 12, v[202:203]
	v_lshl_add_u64 v[66:67], v[204:205], 0, v[66:67]
	global_load_dwordx4 v[70:73], v[66:67], off
	s_nop 0
	global_load_dwordx4 v[66:69], v[66:67], off offset:256
	v_cmp_ne_u32_e64 s[6:7], 1, v222
	v_lshlrev_b64 v[222:223], 11, v[220:221]
	v_lshl_add_u64 v[224:225], v[222:223], 0, v[206:207]
	s_mov_b64 s[4:5], -1
	s_andn2_b64 vcc, exec, s[10:11]
	v_lshl_add_u64 v[224:225], v[224:225], 2, s[2:3]
	s_waitcnt vmcnt(0)
	v_lshlrev_b32_e32 v236, 16, v232
	v_and_b32_e32 v237, 0xffff0000, v232
	v_lshlrev_b32_e32 v232, 16, v233
	v_and_b32_e32 v233, 0xffff0000, v233
	v_lshlrev_b32_e32 v238, 16, v234
	v_and_b32_e32 v239, 0xffff0000, v234
	v_lshlrev_b32_e32 v234, 16, v235
	v_and_b32_e32 v235, 0xffff0000, v235
	v_pk_add_f32 v[164:165], v[164:165], v[232:233]
	v_pk_add_f32 v[162:163], v[162:163], v[236:237]
	v_pk_add_f32 v[160:161], v[160:161], v[234:235]
	v_pk_add_f32 v[158:159], v[158:159], v[238:239]
	s_cbranch_vccnz .LBB0_154
	s_mov_b64 s[4:5], 0
	global_store_dwordx4 v[224:225], v[162:165], off
	global_store_dwordx4 v[224:225], v[158:161], off offset:16

; #define PG8_STAGE(bufoff, gbase, voff) do { _Pragma("unroll") for (int _i = 0; _i < 2; ++_i) \
;         __builtin_amdgcn_global_load_lds((const unsigned*)((const char*)(gbase) + (voff)[_i]), (LAS unsigned*)(lds + (bufoff) + ldsw + _i * 8192), 16, 0, 0); } while (0)
; #define PG8_LDA(dst, b, h) do { _Pragma("unroll") for (int m = 0; m < 4; ++m) _Pragma("unroll") for (int k = 0; k < 2; ++k) dst[m][k] = *(const LAS bf16x8*)(lds + PG8_SA(b, h) + aoff + m * 2048 + k * 1024); } while (0)
; #define PG8_LDB(dst, b, h) do { _Pragma("unroll") for (int n = 0; n < 2; ++n) _Pragma("unroll") for (int k = 0; k < 2; ++k) dst[n][k] = *(const LAS bf16x8*)(lds + PG8_SB(b, h) + boff + n * 2048 + k * 1024); } while (0)
; #define PG8_MMA(ai, bj, At, Bt) do { __builtin_amdgcn_s_setprio(1); _Pragma("unroll") for (int m = 0; m < 4; ++m) _Pragma("unroll") for (int n = 0; n < 2; ++n) _Pragma("unroll") for (int k = 0; k < 2; ++k) \
;         acc[ai][bj][m][n] = __builtin_amdgcn_mfma_f32_16x16x32_bf16(Bt[n][k], At[m][k], acc[ai][bj][m][n], 0, 0, 0); __builtin_amdgcn_s_setprio(0); } while (0)
; #define PG8_WAIT_L(n) asm volatile("s_waitcnt lgkmcnt(" #n ")" ::: "memory")
; #define PG8_BAR __builtin_amdgcn_s_barrier()
; #define PG8_SCHED __builtin_amdgcn_sched_barrier(0)
; template <class Epi, class Sched>
; __device__ __forceinline__ void gemm_phase(LAS unsigned char* lds_in, const int lda, const int ldb, const Sched& S, const Epi& E, const int WID) {
;     ...
;             PG8_LDB(B0, 0, 0); PG8_SCHED; PG8_LDA(At, 0, 0); PG8_STAGE(PG8_SA(1, 1), a1 + hstepA, voffA);
;             PG8_WAIT_L(8); PG8_BAR; PG8_WAIT_L(0); PG8_MMA(0, 0, At, B0); PG8_BAR; PG8_SCHED;
;     ...
; #pragma unroll
;         for (int a = 0; a < 2; ++a)
; #pragma unroll
;             for (int b = 0; b < 2; ++b)
; #pragma unroll
;                 for (int m = 0; m < 4; ++m)
; #pragma unroll
;                     for (int n = 0; n < 2; ++n) acc[a][b][m][n] = (f32x4){0.f, 0.f, 0.f, 0.f};
.LBB0_266:
	s_add_u32 s10, s10, 0x80080
	s_addc_u32 s11, s11, 0
	s_add_u32 s3, s12, 0x100
	v_mov_b32_e32 v2, 0
	s_addc_u32 s94, s13, 0
	s_mov_b32 s95, -2
	v_mov_b32_e32 v3, v2
	v_mov_b32_e32 v4, v2
	v_mov_b32_e32 v5, v2
	v_mov_b32_e32 v6, v2
	v_mov_b32_e32 v7, v2
	v_mov_b32_e32 v8, v2
	v_mov_b32_e32 v9, v2
	v_mov_b32_e32 v18, v2
	v_mov_b32_e32 v19, v2
	v_mov_b32_e32 v20, v2
	v_mov_b32_e32 v21, v2
	v_mov_b32_e32 v22, v2
	v_mov_b32_e32 v23, v2
	v_mov_b32_e32 v24, v2
	v_mov_b32_e32 v25, v2
	v_mov_b32_e32 v34, v2
	v_mov_b32_e32 v35, v2
	v_mov_b32_e32 v36, v2
	v_mov_b32_e32 v37, v2
	v_mov_b32_e32 v38, v2
	v_mov_b32_e32 v39, v2
	v_mov_b32_e32 v40, v2
	v_mov_b32_e32 v41, v2
	v_mov_b32_e32 v50, v2
	v_mov_b32_e32 v51, v2
	v_mov_b32_e32 v52, v2
	v_mov_b32_e32 v53, v2
	v_mov_b32_e32 v54, v2
	v_mov_b32_e32 v55, v2
	v_mov_b32_e32 v56, v2
	v_mov_b32_e32 v57, v2
	v_mov_b32_e32 v10, v2
	v_mov_b32_e32 v11, v2
	v_mov_b32_e32 v12, v2
	v_mov_b32_e32 v13, v2
	v_mov_b32_e32 v14, v2
	v_mov_b32_e32 v15, v2
	v_mov_b32_e32 v16, v2
	v_mov_b32_e32 v17, v2
	v_mov_b32_e32 v26, v2
	v_mov_b32_e32 v27, v2
	v_mov_b32_e32 v28, v2
	v_mov_b32_e32 v29, v2
	v_mov_b32_e32 v30, v2
	v_mov_b32_e32 v31, v2
	v_mov_b32_e32 v32, v2
	v_mov_b32_e32 v33, v2
	v_mov_b32_e32 v42, v2
	v_mov_b32_e32 v43, v2
	v_mov_b32_e32 v44, v2
	v_mov_b32_e32 v45, v2
	v_mov_b32_e32 v46, v2
	v_mov_b32_e32 v47, v2
	v_mov_b32_e32 v48, v2
	v_mov_b32_e32 v49, v2
	v_mov_b32_e32 v58, v2
	v_mov_b32_e32 v59, v2
	v_mov_b32_e32 v60, v2
	v_mov_b32_e32 v61, v2
	v_mov_b32_e32 v62, v2
	v_mov_b32_e32 v63, v2
	v_mov_b32_e32 v64, v2
	v_mov_b32_e32 v65, v2
	v_mov_b32_e32 v66, v2
	v_mov_b32_e32 v67, v2
	v_mov_b32_e32 v68, v2
	v_mov_b32_e32 v69, v2
	v_mov_b32_e32 v70, v2
	v_mov_b32_e32 v71, v2
	v_mov_b32_e32 v72, v2
	v_mov_b32_e32 v73, v2
	v_mov_b32_e32 v82, v2
	v_mov_b32_e32 v83, v2
	v_mov_b32_e32 v84, v2
	v_mov_b32_e32 v85, v2
	v_mov_b32_e32 v86, v2
	v_mov_b32_e32 v87, v2
	v_mov_b32_e32 v88, v2
	v_mov_b32_e32 v89, v2
	v_mov_b32_e32 v98, v2
	v_mov_b32_e32 v99, v2
	v_mov_b32_e32 v100, v2
	v_mov_b32_e32 v101, v2
	v_mov_b32_e32 v102, v2
	v_mov_b32_e32 v103, v2
	v_mov_b32_e32 v104, v2
	v_mov_b32_e32 v105, v2
	v_mov_b32_e32 v114, v2
	v_mov_b32_e32 v115, v2
	v_mov_b32_e32 v116, v2
	v_mov_b32_e32 v117, v2
	v_mov_b32_e32 v118, v2
	v_mov_b32_e32 v119, v2
	v_mov_b32_e32 v120, v2
	v_mov_b32_e32 v121, v2
	v_mov_b32_e32 v74, v2
	v_mov_b32_e32 v75, v2
	v_mov_b32_e32 v76, v2
	v_mov_b32_e32 v77, v2
	v_mov_b32_e32 v78, v2
	v_mov_b32_e32 v79, v2
	v_mov_b32_e32 v80, v2
	v_mov_b32_e32 v81, v2
	v_mov_b32_e32 v90, v2
	v_mov_b32_e32 v91, v2
	v_mov_b32_e32 v92, v2
	v_mov_b32_e32 v93, v2
	v_mov_b32_e32 v94, v2
	v_mov_b32_e32 v95, v2
	v_mov_b32_e32 v96, v2
	v_mov_b32_e32 v97, v2
	v_mov_b32_e32 v106, v2
	v_mov_b32_e32 v107, v2
	v_mov_b32_e32 v108, v2
	v_mov_b32_e32 v109, v2
	v_mov_b32_e32 v110, v2
	v_mov_b32_e32 v111, v2
	v_mov_b32_e32 v112, v2
	v_mov_b32_e32 v113, v2
	v_mov_b32_e32 v122, v2
	v_mov_b32_e32 v123, v2
	v_mov_b32_e32 v124, v2
	v_mov_b32_e32 v125, v2
	v_mov_b32_e32 v126, v2
	v_mov_b32_e32 v127, v2
	v_mov_b32_e32 v128, v2
	v_mov_b32_e32 v129, v2
	v_readlane_b32 s14, v254, 42
	v_readlane_b32 s15, v254, 43
	v_lshl_add_u32 v236, s8, 8, v1
	v_lshlrev_b32_e32 v236, 2, v236
	s_nop 2
	global_load_dword v228, v236, s[14:15] offset:0
	global_load_dword v229, v236, s[14:15] offset:64
	global_load_dword v230, v236, s[14:15] offset:128
	global_load_dword v231, v236, s[14:15] offset:192
	global_load_dword v232, v236, s[14:15] offset:512
	global_load_dword v233, v236, s[14:15] offset:576
	global_load_dword v234, v236, s[14:15] offset:640
	global_load_dword v235, v236, s[14:15] offset:704
	v_add_u32_e32 v220, s9, v148
	v_add_u32_e32 v221, s23, v148
	v_add_u32_e32 v222, s49, v148
	v_add_u32_e32 v223, s78, v148
.LBB0_267:
	s_barrier
	ds_read_b128 v[142:145], v220
	ds_read_b128 v[152:155], v220 offset:1024
	ds_read_b128 v[156:159], v220 offset:2048
	ds_read_b128 v[160:163], v220 offset:3072
	s_add_u32 s12, s10, 0xfff80080
	s_addc_u32 s13, s11, -1
	s_cmp_eq_u32 s95, 28
	s_cselect_b32 s15, s5, s13
	s_cselect_b32 s14, s4, s12
	s_cselect_b32 s13, s7, s94
	s_cselect_b32 s12, s6, s3
	s_add_i32 m0, s21, 0xc000
	ds_read_b128 v[164:167], v150
	ds_read_b128 v[168:171], v150 offset:1024
	ds_read_b128 v[172:175], v150 offset:2048
	ds_read_b128 v[176:179], v150 offset:3072
	ds_read_b128 v[180:183], v150 offset:4096
	ds_read_b128 v[184:187], v150 offset:5120
	ds_read_b128 v[188:191], v150 offset:6144
	ds_read_b128 v[192:195], v150 offset:7168
	global_load_lds_dwordx4 v138, s[10:11]
	s_add_i32 m0, s21, 0xe000
	s_nop 0
	global_load_lds_dwordx4 v140, s[10:11]
	s_waitcnt lgkmcnt(8)
	s_barrier
	s_waitcnt lgkmcnt(0)
	s_setprio 1
	s_waitcnt lgkmcnt(0)
	v_mfma_f32_16x16x32_bf16 v[126:129], v[142:145], v[164:167], v[126:129]
	v_mfma_f32_16x16x32_bf16 v[122:125], v[156:159], v[164:167], v[122:125]
	v_mfma_f32_16x16x32_bf16 v[110:113], v[142:145], v[172:175], v[110:113]
	v_mfma_f32_16x16x32_bf16 v[106:109], v[156:159], v[172:175], v[106:109]
	v_mfma_f32_16x16x32_bf16 v[94:97], v[142:145], v[180:183], v[94:97]
	v_mfma_f32_16x16x32_bf16 v[90:93], v[156:159], v[180:183], v[90:93]
	v_mfma_f32_16x16x32_bf16 v[78:81], v[142:145], v[188:191], v[78:81]
	v_mfma_f32_16x16x32_bf16 v[74:77], v[156:159], v[188:191], v[74:77]
	v_mfma_f32_16x16x32_bf16 v[126:129], v[152:155], v[168:171], v[126:129]
	v_mfma_f32_16x16x32_bf16 v[122:125], v[160:163], v[168:171], v[122:125]
	v_mfma_f32_16x16x32_bf16 v[110:113], v[152:155], v[176:179], v[110:113]
	v_mfma_f32_16x16x32_bf16 v[106:109], v[160:163], v[176:179], v[106:109]
	v_mfma_f32_16x16x32_bf16 v[94:97], v[152:155], v[184:187], v[94:97]
	v_mfma_f32_16x16x32_bf16 v[90:93], v[160:163], v[184:187], v[90:93]
	v_mfma_f32_16x16x32_bf16 v[78:81], v[152:155], v[192:195], v[78:81]
	v_mfma_f32_16x16x32_bf16 v[74:77], v[160:163], v[192:195], v[74:77]
	s_setprio 0
	s_barrier
; #define PG8_STAGE(bufoff, gbase, voff) do { _Pragma("unroll") for (int _i = 0; _i < 2; ++_i) \
;         __builtin_amdgcn_global_load_lds((const unsigned*)((const char*)(gbase) + (voff)[_i]), (LAS unsigned*)(lds + (bufoff) + ldsw + _i * 8192), 16, 0, 0); } while (0)
; #define PG8_LDA(dst, b, h) do { _Pragma("unroll") for (int m = 0; m < 4; ++m) _Pragma("unroll") for (int k = 0; k < 2; ++k) dst[m][k] = *(const LAS bf16x8*)(lds + PG8_SA(b, h) + aoff + m * 2048 + k * 1024); } while (0)
; #define PG8_LDB(dst, b, h) do { _Pragma("unroll") for (int n = 0; n < 2; ++n) _Pragma("unroll") for (int k = 0; k < 2; ++k) dst[n][k] = *(const LAS bf16x8*)(lds + PG8_SB(b, h) + boff + n * 2048 + k * 1024); } while (0)
; #define PG8_MMA(ai, bj, At, Bt) do { __builtin_amdgcn_s_setprio(1); _Pragma("unroll") for (int m = 0; m < 4; ++m) _Pragma("unroll") for (int n = 0; n < 2; ++n) _Pragma("unroll") for (int k = 0; k < 2; ++k) \
;         acc[ai][bj][m][n] = __builtin_amdgcn_mfma_f32_16x16x32_bf16(Bt[n][k], At[m][k], acc[ai][bj][m][n], 0, 0, 0); __builtin_amdgcn_s_setprio(0); } while (0)
; #define PG8_WAIT_V(n) asm volatile("s_waitcnt vmcnt(" #n ")" ::: "memory")
; #define PG8_WAIT_L(n) asm volatile("s_waitcnt lgkmcnt(" #n ")" ::: "memory")
; #define PG8_BAR __builtin_amdgcn_s_barrier()
; #define PG8_SCHED __builtin_amdgcn_sched_barrier(0)
; template <class Epi, class Sched>
; __device__ __forceinline__ void gemm_phase(LAS unsigned char* lds_in, const int lda, const int ldb, const Sched& S, const Epi& E, const int WID) {
;     ...
;             PG8_LDB(B1, 0, 1); PG8_STAGE(PG8_SB(0, 0), b2, voffB);
;             PG8_BAR; PG8_WAIT_L(0); PG8_MMA(0, 1, At, B1); PG8_BAR;
;             PG8_LDA(At, 0, 1); PG8_STAGE(PG8_SA(0, 0), a2, voffA);
;             PG8_BAR; PG8_WAIT_L(0); PG8_MMA(1, 0, At, B0); PG8_BAR; PG8_SCHED;
;             PG8_STAGE(PG8_SB(0, 1), b2 + hstepB, voffB);
;             PG8_WAIT_V(6); PG8_BAR; PG8_MMA(1, 1, At, B1); PG8_BAR;
;             PG8_LDB(B0, 1, 0); PG8_SCHED; PG8_LDA(At, 1, 0); PG8_STAGE(PG8_SA(0, 1), a2 + hstepA, voffA);
;             PG8_WAIT_L(8); PG8_BAR; PG8_WAIT_L(0); PG8_MMA(0, 0, At, B0); PG8_BAR; PG8_SCHED;
	s_mov_b32 m0, s19
	ds_read_b128 v[196:199], v221
	ds_read_b128 v[200:203], v221 offset:1024
	ds_read_b128 v[204:207], v221 offset:2048
	ds_read_b128 v[208:211], v221 offset:3072
	global_load_lds_dwordx4 v132, s[12:13]
	s_mov_b32 m0, s20
	s_nop 0
	global_load_lds_dwordx4 v136, s[12:13]
	s_barrier
	s_waitcnt lgkmcnt(0)
	s_setprio 1
	s_waitcnt lgkmcnt(0)
	v_mfma_f32_16x16x32_bf16 v[118:121], v[196:199], v[164:167], v[118:121]
	v_mfma_f32_16x16x32_bf16 v[114:117], v[204:207], v[164:167], v[114:117]
	v_mfma_f32_16x16x32_bf16 v[102:105], v[196:199], v[172:175], v[102:105]
	v_mfma_f32_16x16x32_bf16 v[98:101], v[204:207], v[172:175], v[98:101]
	v_mfma_f32_16x16x32_bf16 v[86:89], v[196:199], v[180:183], v[86:89]
	v_mfma_f32_16x16x32_bf16 v[82:85], v[204:207], v[180:183], v[82:85]
	v_mfma_f32_16x16x32_bf16 v[70:73], v[196:199], v[188:191], v[70:73]
	v_mfma_f32_16x16x32_bf16 v[66:69], v[204:207], v[188:191], v[66:69]
	v_mfma_f32_16x16x32_bf16 v[118:121], v[200:203], v[168:171], v[118:121]
	v_mfma_f32_16x16x32_bf16 v[114:117], v[208:211], v[168:171], v[114:117]
	v_mfma_f32_16x16x32_bf16 v[102:105], v[200:203], v[176:179], v[102:105]
	v_mfma_f32_16x16x32_bf16 v[98:101], v[208:211], v[176:179], v[98:101]
	v_mfma_f32_16x16x32_bf16 v[86:89], v[200:203], v[184:187], v[86:89]
	v_mfma_f32_16x16x32_bf16 v[82:85], v[208:211], v[184:187], v[82:85]
	v_mfma_f32_16x16x32_bf16 v[70:73], v[200:203], v[192:195], v[70:73]
	v_mfma_f32_16x16x32_bf16 v[66:69], v[208:211], v[192:195], v[66:69]
	s_setprio 0
	s_mov_b32 m0, s21
	s_barrier
	ds_read_b128 v[164:167], v150 offset:16384
	ds_read_b128 v[168:171], v150 offset:17408
	ds_read_b128 v[172:175], v150 offset:18432
	ds_read_b128 v[176:179], v150 offset:19456
	ds_read_b128 v[180:183], v150 offset:20480
	ds_read_b128 v[184:187], v150 offset:21504
	ds_read_b128 v[188:191], v150 offset:22528
	ds_read_b128 v[192:195], v150 offset:23552
	global_load_lds_dwordx4 v130, s[14:15]
	s_mov_b32 m0, s22
	s_nop 0
	global_load_lds_dwordx4 v134, s[14:15]
	s_barrier
	s_waitcnt lgkmcnt(0)
	s_setprio 1
	s_waitcnt lgkmcnt(0)
	v_mfma_f32_16x16x32_bf16 v[62:65], v[142:145], v[164:167], v[62:65]
	v_mfma_f32_16x16x32_bf16 v[58:61], v[156:159], v[164:167], v[58:61]
	v_mfma_f32_16x16x32_bf16 v[46:49], v[142:145], v[172:175], v[46:49]
	v_mfma_f32_16x16x32_bf16 v[42:45], v[156:159], v[172:175], v[42:45]
	v_mfma_f32_16x16x32_bf16 v[30:33], v[142:145], v[180:183], v[30:33]
	v_mfma_f32_16x16x32_bf16 v[26:29], v[156:159], v[180:183], v[26:29]
	v_mfma_f32_16x16x32_bf16 v[14:17], v[142:145], v[188:191], v[14:17]
	v_mfma_f32_16x16x32_bf16 v[10:13], v[156:159], v[188:191], v[10:13]
	v_mfma_f32_16x16x32_bf16 v[62:65], v[152:155], v[168:171], v[62:65]
	v_mfma_f32_16x16x32_bf16 v[58:61], v[160:163], v[168:171], v[58:61]
	v_mfma_f32_16x16x32_bf16 v[46:49], v[152:155], v[176:179], v[46:49]
	v_mfma_f32_16x16x32_bf16 v[42:45], v[160:163], v[176:179], v[42:45]
	v_mfma_f32_16x16x32_bf16 v[30:33], v[152:155], v[184:187], v[30:33]
	v_mfma_f32_16x16x32_bf16 v[26:29], v[160:163], v[184:187], v[26:29]
	v_mfma_f32_16x16x32_bf16 v[14:17], v[152:155], v[192:195], v[14:17]
	v_mfma_f32_16x16x32_bf16 v[10:13], v[160:163], v[192:195], v[10:13]
	s_setprio 0
	s_barrier
	s_add_u32 s66, s12, 0x80000
	s_addc_u32 s67, s13, 0
	s_mov_b32 m0, s35
	s_nop 0
	global_load_lds_dwordx4 v132, s[66:67]
	s_mov_b32 m0, s46
	s_nop 0
	global_load_lds_dwordx4 v136, s[66:67]
	s_waitcnt vmcnt(6)
	s_barrier
	s_setprio 1
	v_mfma_f32_16x16x32_bf16 v[54:57], v[196:199], v[164:167], v[54:57]
	v_mfma_f32_16x16x32_bf16 v[50:53], v[204:207], v[164:167], v[50:53]
	v_mfma_f32_16x16x32_bf16 v[38:41], v[196:199], v[172:175], v[38:41]
	v_mfma_f32_16x16x32_bf16 v[34:37], v[204:207], v[172:175], v[34:37]
	v_mfma_f32_16x16x32_bf16 v[22:25], v[196:199], v[180:183], v[22:25]
	v_mfma_f32_16x16x32_bf16 v[18:21], v[204:207], v[180:183], v[18:21]
	v_mfma_f32_16x16x32_bf16 v[6:9], v[196:199], v[188:191], v[6:9]
	v_mfma_f32_16x16x32_bf16 v[2:5], v[204:207], v[188:191], v[2:5]
	v_mfma_f32_16x16x32_bf16 v[54:57], v[200:203], v[168:171], v[54:57]
	v_mfma_f32_16x16x32_bf16 v[50:53], v[208:211], v[168:171], v[50:53]
	v_mfma_f32_16x16x32_bf16 v[38:41], v[200:203], v[176:179], v[38:41]
	v_mfma_f32_16x16x32_bf16 v[34:37], v[208:211], v[176:179], v[34:37]
	v_mfma_f32_16x16x32_bf16 v[22:25], v[200:203], v[184:187], v[22:25]
	v_mfma_f32_16x16x32_bf16 v[18:21], v[208:211], v[184:187], v[18:21]
	v_mfma_f32_16x16x32_bf16 v[6:9], v[200:203], v[192:195], v[6:9]
	v_mfma_f32_16x16x32_bf16 v[2:5], v[208:211], v[192:195], v[2:5]
	s_setprio 0
	s_barrier
	ds_read_b128 v[142:145], v222
	ds_read_b128 v[152:155], v222 offset:1024
	ds_read_b128 v[156:159], v222 offset:2048
	ds_read_b128 v[160:163], v222 offset:3072
	s_add_u32 s14, s14, 0x80000
	s_addc_u32 s15, s15, 0
	s_mov_b32 m0, s47
	ds_read_b128 v[164:167], v150 offset:32768
	ds_read_b128 v[168:171], v150 offset:33792
	ds_read_b128 v[172:175], v150 offset:34816
	ds_read_b128 v[176:179], v150 offset:35840
	ds_read_b128 v[180:183], v150 offset:36864
	ds_read_b128 v[184:187], v150 offset:37888
	ds_read_b128 v[188:191], v150 offset:38912
	ds_read_b128 v[192:195], v150 offset:39936
	global_load_lds_dwordx4 v130, s[14:15]
	s_mov_b32 m0, s48
	s_nop 0
	global_load_lds_dwordx4 v134, s[14:15]
	s_waitcnt lgkmcnt(8)
	s_barrier
; #define PG8_STAGE(bufoff, gbase, voff) do { _Pragma("unroll") for (int _i = 0; _i < 2; ++_i) \
;         __builtin_amdgcn_global_load_lds((const unsigned*)((const char*)(gbase) + (voff)[_i]), (LAS unsigned*)(lds + (bufoff) + ldsw + _i * 8192), 16, 0, 0); } while (0)
; #define PG8_LDA(dst, b, h) do { _Pragma("unroll") for (int m = 0; m < 4; ++m) _Pragma("unroll") for (int k = 0; k < 2; ++k) dst[m][k] = *(const LAS bf16x8*)(lds + PG8_SA(b, h) + aoff + m * 2048 + k * 1024); } while (0)
; #define PG8_LDB(dst, b, h) do { _Pragma("unroll") for (int n = 0; n < 2; ++n) _Pragma("unroll") for (int k = 0; k < 2; ++k) dst[n][k] = *(const LAS bf16x8*)(lds + PG8_SB(b, h) + boff + n * 2048 + k * 1024); } while (0)
; #define PG8_MMA(ai, bj, At, Bt) do { __builtin_amdgcn_s_setprio(1); _Pragma("unroll") for (int m = 0; m < 4; ++m) _Pragma("unroll") for (int n = 0; n < 2; ++n) _Pragma("unroll") for (int k = 0; k < 2; ++k) \
;         acc[ai][bj][m][n] = __builtin_amdgcn_mfma_f32_16x16x32_bf16(Bt[n][k], At[m][k], acc[ai][bj][m][n], 0, 0, 0); __builtin_amdgcn_s_setprio(0); } while (0)
; #define PG8_WAIT_V(n) asm volatile("s_waitcnt vmcnt(" #n ")" ::: "memory")
; #define PG8_WAIT_L(n) asm volatile("s_waitcnt lgkmcnt(" #n ")" ::: "memory")
; #define PG8_BAR __builtin_amdgcn_s_barrier()
; #define PG8_SCHED __builtin_amdgcn_sched_barrier(0)
; template <class Epi, class Sched>
; __device__ __forceinline__ void gemm_phase(LAS unsigned char* lds_in, const int lda, const int ldb, const Sched& S, const Epi& E, const int WID) {
;     ...
;             PG8_WAIT_L(8); PG8_BAR; PG8_WAIT_L(0); PG8_MMA(0, 0, At, B0); PG8_BAR; PG8_SCHED;
;             PG8_LDB(B1, 1, 1); PG8_STAGE(PG8_SB(1, 0), b3, voffB);
;             PG8_BAR; PG8_WAIT_L(0); PG8_MMA(0, 1, At, B1); PG8_BAR;
;             PG8_LDA(At, 1, 1); PG8_STAGE(PG8_SA(1, 0), a3, voffA);
;             PG8_BAR; PG8_WAIT_L(0); PG8_MMA(1, 0, At, B0); PG8_BAR; PG8_SCHED;
;             PG8_STAGE(PG8_SB(1, 1), b3 + hstepB, voffB);
;             PG8_WAIT_V(6); PG8_BAR; PG8_MMA(1, 1, At, B1); PG8_BAR;
	s_waitcnt lgkmcnt(0)
	s_setprio 1
	s_waitcnt lgkmcnt(0)
	v_mfma_f32_16x16x32_bf16 v[126:129], v[142:145], v[164:167], v[126:129]
	v_mfma_f32_16x16x32_bf16 v[122:125], v[156:159], v[164:167], v[122:125]
	v_mfma_f32_16x16x32_bf16 v[110:113], v[142:145], v[172:175], v[110:113]
	v_mfma_f32_16x16x32_bf16 v[106:109], v[156:159], v[172:175], v[106:109]
	v_mfma_f32_16x16x32_bf16 v[94:97], v[142:145], v[180:183], v[94:97]
	v_mfma_f32_16x16x32_bf16 v[90:93], v[156:159], v[180:183], v[90:93]
	v_mfma_f32_16x16x32_bf16 v[78:81], v[142:145], v[188:191], v[78:81]
	v_mfma_f32_16x16x32_bf16 v[74:77], v[156:159], v[188:191], v[74:77]
	v_mfma_f32_16x16x32_bf16 v[126:129], v[152:155], v[168:171], v[126:129]
	v_mfma_f32_16x16x32_bf16 v[122:125], v[160:163], v[168:171], v[122:125]
	v_mfma_f32_16x16x32_bf16 v[110:113], v[152:155], v[176:179], v[110:113]
	v_mfma_f32_16x16x32_bf16 v[106:109], v[160:163], v[176:179], v[106:109]
	v_mfma_f32_16x16x32_bf16 v[94:97], v[152:155], v[184:187], v[94:97]
	v_mfma_f32_16x16x32_bf16 v[90:93], v[160:163], v[184:187], v[90:93]
	v_mfma_f32_16x16x32_bf16 v[78:81], v[152:155], v[192:195], v[78:81]
	v_mfma_f32_16x16x32_bf16 v[74:77], v[160:163], v[192:195], v[74:77]
	s_setprio 0
	s_barrier
	s_mov_b32 m0, s50
	s_add_u32 s100, s12, 0x80
	s_addc_u32 s101, s13, 0
	ds_read_b128 v[196:199], v223
	ds_read_b128 v[200:203], v223 offset:1024
	ds_read_b128 v[204:207], v223 offset:2048
	ds_read_b128 v[208:211], v223 offset:3072
	global_load_lds_dwordx4 v132, s[100:101]
	s_add_u32 s100, s12, 0x80
	s_addc_u32 s101, s13, 0
	s_mov_b32 m0, s51
	s_nop 0
	global_load_lds_dwordx4 v136, s[100:101]
	s_barrier
	s_waitcnt lgkmcnt(0)
	s_setprio 1
	s_waitcnt lgkmcnt(0)
	v_mfma_f32_16x16x32_bf16 v[118:121], v[196:199], v[164:167], v[118:121]
	v_mfma_f32_16x16x32_bf16 v[114:117], v[204:207], v[164:167], v[114:117]
	v_mfma_f32_16x16x32_bf16 v[102:105], v[196:199], v[172:175], v[102:105]
	v_mfma_f32_16x16x32_bf16 v[98:101], v[204:207], v[172:175], v[98:101]
	v_mfma_f32_16x16x32_bf16 v[86:89], v[196:199], v[180:183], v[86:89]
	v_mfma_f32_16x16x32_bf16 v[82:85], v[204:207], v[180:183], v[82:85]
	v_mfma_f32_16x16x32_bf16 v[70:73], v[196:199], v[188:191], v[70:73]
	v_mfma_f32_16x16x32_bf16 v[66:69], v[204:207], v[188:191], v[66:69]
	v_mfma_f32_16x16x32_bf16 v[118:121], v[200:203], v[168:171], v[118:121]
	v_mfma_f32_16x16x32_bf16 v[114:117], v[208:211], v[168:171], v[114:117]
	v_mfma_f32_16x16x32_bf16 v[102:105], v[200:203], v[176:179], v[102:105]
	v_mfma_f32_16x16x32_bf16 v[98:101], v[208:211], v[176:179], v[98:101]
	v_mfma_f32_16x16x32_bf16 v[86:89], v[200:203], v[184:187], v[86:89]
	v_mfma_f32_16x16x32_bf16 v[82:85], v[208:211], v[184:187], v[82:85]
	v_mfma_f32_16x16x32_bf16 v[70:73], v[200:203], v[192:195], v[70:73]
	v_mfma_f32_16x16x32_bf16 v[66:69], v[208:211], v[192:195], v[66:69]
	s_setprio 0
	s_mov_b32 m0, s65
	s_add_u32 s100, s14, 0xfff80080
	s_addc_u32 s101, s15, -1
	s_barrier
	ds_read_b128 v[164:167], v150 offset:49152
	ds_read_b128 v[168:171], v150 offset:50176
	ds_read_b128 v[172:175], v150 offset:51200
	ds_read_b128 v[176:179], v150 offset:52224
	ds_read_b128 v[180:183], v150 offset:53248
	ds_read_b128 v[184:187], v150 offset:54272
	ds_read_b128 v[188:191], v150 offset:55296
	ds_read_b128 v[192:195], v150 offset:56320
	global_load_lds_dwordx4 v130, s[100:101]
	s_add_u32 s100, s14, 0xfff80080
	s_addc_u32 s101, s15, -1
	s_mov_b32 m0, s70
	s_nop 0
	global_load_lds_dwordx4 v134, s[100:101]
	s_barrier
	s_waitcnt lgkmcnt(0)
	s_setprio 1
	s_waitcnt lgkmcnt(0)
	v_mfma_f32_16x16x32_bf16 v[62:65], v[142:145], v[164:167], v[62:65]
	v_mfma_f32_16x16x32_bf16 v[58:61], v[156:159], v[164:167], v[58:61]
	v_mfma_f32_16x16x32_bf16 v[46:49], v[142:145], v[172:175], v[46:49]
	v_mfma_f32_16x16x32_bf16 v[42:45], v[156:159], v[172:175], v[42:45]
	v_mfma_f32_16x16x32_bf16 v[30:33], v[142:145], v[180:183], v[30:33]
	v_mfma_f32_16x16x32_bf16 v[26:29], v[156:159], v[180:183], v[26:29]
	v_mfma_f32_16x16x32_bf16 v[14:17], v[142:145], v[188:191], v[14:17]
	v_mfma_f32_16x16x32_bf16 v[10:13], v[156:159], v[188:191], v[10:13]
	v_mfma_f32_16x16x32_bf16 v[62:65], v[152:155], v[168:171], v[62:65]
	v_mfma_f32_16x16x32_bf16 v[58:61], v[160:163], v[168:171], v[58:61]
	v_mfma_f32_16x16x32_bf16 v[46:49], v[152:155], v[176:179], v[46:49]
	v_mfma_f32_16x16x32_bf16 v[42:45], v[160:163], v[176:179], v[42:45]
	v_mfma_f32_16x16x32_bf16 v[30:33], v[152:155], v[184:187], v[30:33]
	v_mfma_f32_16x16x32_bf16 v[26:29], v[160:163], v[184:187], v[26:29]
	v_mfma_f32_16x16x32_bf16 v[14:17], v[152:155], v[192:195], v[14:17]
	v_mfma_f32_16x16x32_bf16 v[10:13], v[160:163], v[192:195], v[10:13]
	s_setprio 0
	s_barrier
	s_add_u32 s12, s12, 0x80080
	s_addc_u32 s13, s13, 0
	s_mov_b32 m0, s79
	s_nop 0
	global_load_lds_dwordx4 v132, s[12:13]
	s_mov_b32 m0, s90
	s_nop 0
	global_load_lds_dwordx4 v136, s[12:13]
	s_waitcnt vmcnt(6)
	s_barrier
	s_setprio 1
	v_mfma_f32_16x16x32_bf16 v[54:57], v[196:199], v[164:167], v[54:57]
	v_mfma_f32_16x16x32_bf16 v[50:53], v[204:207], v[164:167], v[50:53]
	v_mfma_f32_16x16x32_bf16 v[38:41], v[196:199], v[172:175], v[38:41]
	v_mfma_f32_16x16x32_bf16 v[34:37], v[204:207], v[172:175], v[34:37]
	v_mfma_f32_16x16x32_bf16 v[22:25], v[196:199], v[180:183], v[22:25]
	v_mfma_f32_16x16x32_bf16 v[18:21], v[204:207], v[180:183], v[18:21]
	v_mfma_f32_16x16x32_bf16 v[6:9], v[196:199], v[188:191], v[6:9]
	v_mfma_f32_16x16x32_bf16 v[2:5], v[204:207], v[188:191], v[2:5]
	v_mfma_f32_16x16x32_bf16 v[54:57], v[200:203], v[168:171], v[54:57]
	v_mfma_f32_16x16x32_bf16 v[50:53], v[208:211], v[168:171], v[50:53]
	v_mfma_f32_16x16x32_bf16 v[38:41], v[200:203], v[176:179], v[38:41]
	v_mfma_f32_16x16x32_bf16 v[34:37], v[208:211], v[176:179], v[34:37]
	v_mfma_f32_16x16x32_bf16 v[22:25], v[200:203], v[184:187], v[22:25]
	v_mfma_f32_16x16x32_bf16 v[18:21], v[208:211], v[184:187], v[18:21]
	v_mfma_f32_16x16x32_bf16 v[6:9], v[200:203], v[192:195], v[6:9]
	v_mfma_f32_16x16x32_bf16 v[2:5], v[208:211], v[192:195], v[2:5]
	s_setprio 0
	s_add_i32 s95, s95, 2
	s_add_u32 s10, s10, 0x100
	s_addc_u32 s11, s11, 0
	s_add_u32 s3, s3, 0x100
	s_addc_u32 s94, s94, 0
	s_cmp_gt_u32 s95, 29
	s_cbranch_scc0 .LBB0_267
; __device__ __forceinline__ float rstd_of(float ss) { return rsqrtf(ss * (1.0f / DM) + EPS); }
; __device__ __forceinline__ u32x4 pack8(const f32x4 a, const f32x4 b) { u32x4 w; w.x = cvt_pk_bf16(a[0], a[1]); w.y = cvt_pk_bf16(a[2], a[3]); w.z = cvt_pk_bf16(b[0], b[1]); w.w = cvt_pk_bf16(b[2], b[3]); return w; }
;     __device__ __forceinline__ void operator()(const AccT& acc, const Unit& u, int wr, int wc, int fr, int fq) const {
;         const int row0 = u.pm * 256 + wr * 64 + fr, col0 = u.pn * 256 + wc * 32 + 8 * fq;
;         float rsv[2][4];
; #pragma unroll
;         for (int ai = 0; ai < 2; ++ai)
; #pragma unroll
;             for (int m = 0; m < 4; ++m) rsv[ai][m] = SS[row0 + ai * 128 + m * 16];
; #pragma unroll
;         for (int ai = 0; ai < 2; ++ai)
; #pragma unroll
;             for (int m = 0; m < 4; ++m) {
;                 const float rs = rstd_of(rsv[ai][m]);
; #pragma unroll
;                 for (int bj = 0; bj < 2; ++bj) {
;                     f32x4 v0 = acc[ai][bj][m][0] * rs, v1 = acc[ai][bj][m][1] * rs;
; #pragma unroll
;                     for (int j = 0; j < 4; ++j) { const float a = fmaxf(v0[j], 0.f), b = fmaxf(v1[j], 0.f); v0[j] = a * a; v1[j] = b * b; }
;                     *(u32x4*)(Hd + (size_t)(row0 + ai * 128 + m * 16) * DFF + col0 + bj * 128) = pack8(v0, v1);
;                 }
;             }
	v_lshl_add_u32 v159, s8, 8, v1
	v_lshl_or_b32 v160, s93, 8, v149
	v_lshlrev_b32_e32 v160, 1, v160
	v_lshl_add_u32 v160, v159, 14, v160
	s_mov_b32 s93, s92
	s_mov_b32 s8, s2
	s_mov_b64 s[12:13], s[6:7]
	s_mov_b32 s3, 0x2c0000
	v_fmamk_f32 v142, v228, 0x3a000000, v251
	v_rsq_f32_e32 v142, v142
	v_mov_b32_e32 v161, v160
	v_pk_mul_f32 v[126:127], v[126:127], v[142:143] op_sel_hi:[1,0]
	v_pk_mul_f32 v[128:129], v[128:129], v[142:143] op_sel_hi:[1,0]
	v_pk_mul_f32 v[122:123], v[122:123], v[142:143] op_sel_hi:[1,0]
	v_pk_mul_f32 v[124:125], v[124:125], v[142:143] op_sel_hi:[1,0]
	v_max_f32_e32 v126, 0, v126
	v_max_f32_e32 v127, 0, v127
	v_max_f32_e32 v128, 0, v128
	v_max_f32_e32 v129, 0, v129
	v_max_f32_e32 v122, 0, v122
	v_max_f32_e32 v123, 0, v123
	v_max_f32_e32 v124, 0, v124
	v_max_f32_e32 v125, 0, v125
	v_pk_mul_f32 v[126:127], v[126:127], v[126:127]
	v_pk_mul_f32 v[128:129], v[128:129], v[128:129]
	v_pk_mul_f32 v[122:123], v[122:123], v[122:123]
	v_pk_mul_f32 v[124:125], v[124:125], v[124:125]
	v_cvt_pk_bf16_f32 v126, v126, v127
	v_cvt_pk_bf16_f32 v127, v128, v129
	v_cvt_pk_bf16_f32 v128, v122, v123
	v_cvt_pk_bf16_f32 v129, v124, v125
	global_store_dwordx4 v161, v[126:129], s[30:31]
	v_pk_mul_f32 v[118:119], v[118:119], v[142:143] op_sel_hi:[1,0]
	v_pk_mul_f32 v[120:121], v[120:121], v[142:143] op_sel_hi:[1,0]
	v_pk_mul_f32 v[114:115], v[114:115], v[142:143] op_sel_hi:[1,0]
	v_pk_mul_f32 v[116:117], v[116:117], v[142:143] op_sel_hi:[1,0]
	v_max_f32_e32 v118, 0, v118
	v_max_f32_e32 v119, 0, v119
	v_max_f32_e32 v120, 0, v120
	v_max_f32_e32 v121, 0, v121
	v_max_f32_e32 v114, 0, v114
	v_max_f32_e32 v115, 0, v115
	v_max_f32_e32 v116, 0, v116
	v_max_f32_e32 v117, 0, v117
	v_pk_mul_f32 v[118:119], v[118:119], v[118:119]
	v_pk_mul_f32 v[120:121], v[120:121], v[120:121]
	v_pk_mul_f32 v[114:115], v[114:115], v[114:115]
	v_pk_mul_f32 v[116:117], v[116:117], v[116:117]
	v_cvt_pk_bf16_f32 v118, v118, v119
	v_cvt_pk_bf16_f32 v119, v120, v121
	v_cvt_pk_bf16_f32 v120, v114, v115
	v_cvt_pk_bf16_f32 v121, v116, v117
	global_store_dwordx4 v161, v[118:121], s[30:31] offset:256
	v_fmamk_f32 v144, v229, 0x3a000000, v251
	v_rsq_f32_e32 v144, v144
	v_add_u32_e32 v161, 0x40000, v160
	v_pk_mul_f32 v[110:111], v[110:111], v[144:145] op_sel_hi:[1,0]
	v_pk_mul_f32 v[112:113], v[112:113], v[144:145] op_sel_hi:[1,0]
	v_pk_mul_f32 v[106:107], v[106:107], v[144:145] op_sel_hi:[1,0]
	v_pk_mul_f32 v[108:109], v[108:109], v[144:145] op_sel_hi:[1,0]
	v_max_f32_e32 v110, 0, v110
	v_max_f32_e32 v111, 0, v111
	v_max_f32_e32 v112, 0, v112
	v_max_f32_e32 v113, 0, v113
	v_max_f32_e32 v106, 0, v106
	v_max_f32_e32 v107, 0, v107
	v_max_f32_e32 v108, 0, v108
	v_max_f32_e32 v109, 0, v109
	v_pk_mul_f32 v[110:111], v[110:111], v[110:111]
	v_pk_mul_f32 v[112:113], v[112:113], v[112:113]
	v_pk_mul_f32 v[106:107], v[106:107], v[106:107]
	v_pk_mul_f32 v[108:109], v[108:109], v[108:109]
	v_cvt_pk_bf16_f32 v110, v110, v111
	v_cvt_pk_bf16_f32 v111, v112, v113
	v_cvt_pk_bf16_f32 v112, v106, v107
	v_cvt_pk_bf16_f32 v113, v108, v109
	global_store_dwordx4 v161, v[110:113], s[30:31]
	v_pk_mul_f32 v[102:103], v[102:103], v[144:145] op_sel_hi:[1,0]
	v_pk_mul_f32 v[104:105], v[104:105], v[144:145] op_sel_hi:[1,0]
	v_pk_mul_f32 v[98:99], v[98:99], v[144:145] op_sel_hi:[1,0]
	v_pk_mul_f32 v[100:101], v[100:101], v[144:145] op_sel_hi:[1,0]
	v_max_f32_e32 v102, 0, v102
	v_max_f32_e32 v103, 0, v103
	v_max_f32_e32 v104, 0, v104
	v_max_f32_e32 v105, 0, v105
	v_max_f32_e32 v98, 0, v98
	v_max_f32_e32 v99, 0, v99
	v_max_f32_e32 v100, 0, v100
	v_max_f32_e32 v101, 0, v101
	v_pk_mul_f32 v[102:103], v[102:103], v[102:103]
	v_pk_mul_f32 v[104:105], v[104:105], v[104:105]
	v_pk_mul_f32 v[98:99], v[98:99], v[98:99]
	v_pk_mul_f32 v[100:101], v[100:101], v[100:101]
	v_cvt_pk_bf16_f32 v102, v102, v103
	v_cvt_pk_bf16_f32 v103, v104, v105
	v_cvt_pk_bf16_f32 v104, v98, v99
	v_cvt_pk_bf16_f32 v105, v100, v101
	global_store_dwordx4 v161, v[102:105], s[30:31] offset:256
	v_fmamk_f32 v146, v230, 0x3a000000, v251
	v_rsq_f32_e32 v146, v146
	v_add_u32_e32 v161, 0x80000, v160
	v_pk_mul_f32 v[94:95], v[94:95], v[146:147] op_sel_hi:[1,0]
	v_pk_mul_f32 v[96:97], v[96:97], v[146:147] op_sel_hi:[1,0]
	v_pk_mul_f32 v[90:91], v[90:91], v[146:147] op_sel_hi:[1,0]
	v_pk_mul_f32 v[92:93], v[92:93], v[146:147] op_sel_hi:[1,0]
	v_max_f32_e32 v94, 0, v94
	v_max_f32_e32 v95, 0, v95
	v_max_f32_e32 v96, 0, v96
	v_max_f32_e32 v97, 0, v97
	v_max_f32_e32 v90, 0, v90
	v_max_f32_e32 v91, 0, v91
	v_max_f32_e32 v92, 0, v92
	v_max_f32_e32 v93, 0, v93
	v_pk_mul_f32 v[94:95], v[94:95], v[94:95]
	v_pk_mul_f32 v[96:97], v[96:97], v[96:97]
	v_pk_mul_f32 v[90:91], v[90:91], v[90:91]
	v_pk_mul_f32 v[92:93], v[92:93], v[92:93]
	v_cvt_pk_bf16_f32 v94, v94, v95
	v_cvt_pk_bf16_f32 v95, v96, v97
	v_cvt_pk_bf16_f32 v96, v90, v91
	v_cvt_pk_bf16_f32 v97, v92, v93
	global_store_dwordx4 v161, v[94:97], s[30:31]
	v_pk_mul_f32 v[86:87], v[86:87], v[146:147] op_sel_hi:[1,0]
	v_pk_mul_f32 v[88:89], v[88:89], v[146:147] op_sel_hi:[1,0]
	v_pk_mul_f32 v[82:83], v[82:83], v[146:147] op_sel_hi:[1,0]
	v_pk_mul_f32 v[84:85], v[84:85], v[146:147] op_sel_hi:[1,0]
	v_max_f32_e32 v86, 0, v86
	v_max_f32_e32 v87, 0, v87
	v_max_f32_e32 v88, 0, v88
	v_max_f32_e32 v89, 0, v89
	v_max_f32_e32 v82, 0, v82
	v_max_f32_e32 v83, 0, v83
	v_max_f32_e32 v84, 0, v84
	v_max_f32_e32 v85, 0, v85
	v_pk_mul_f32 v[86:87], v[86:87], v[86:87]
	v_pk_mul_f32 v[88:89], v[88:89], v[88:89]
	v_pk_mul_f32 v[82:83], v[82:83], v[82:83]
	v_pk_mul_f32 v[84:85], v[84:85], v[84:85]
	v_cvt_pk_bf16_f32 v86, v86, v87
	v_cvt_pk_bf16_f32 v87, v88, v89
	v_cvt_pk_bf16_f32 v88, v82, v83
	v_cvt_pk_bf16_f32 v89, v84, v85
; __device__ __forceinline__ float rstd_of(float ss) { return rsqrtf(ss * (1.0f / DM) + EPS); }
; __device__ __forceinline__ u32x4 pack8(const f32x4 a, const f32x4 b) { u32x4 w; w.x = cvt_pk_bf16(a[0], a[1]); w.y = cvt_pk_bf16(a[2], a[3]); w.z = cvt_pk_bf16(b[0], b[1]); w.w = cvt_pk_bf16(b[2], b[3]); return w; }
;     __device__ __forceinline__ void operator()(const AccT& acc, const Unit& u, int wr, int wc, int fr, int fq) const {
;     ...
;         for (int ai = 0; ai < 2; ++ai)
; #pragma unroll
;             for (int m = 0; m < 4; ++m) {
;                 const float rs = rstd_of(rsv[ai][m]);
; #pragma unroll
;                 for (int bj = 0; bj < 2; ++bj) {
;                     f32x4 v0 = acc[ai][bj][m][0] * rs, v1 = acc[ai][bj][m][1] * rs;
; #pragma unroll
;                     for (int j = 0; j < 4; ++j) { const float a = fmaxf(v0[j], 0.f), b = fmaxf(v1[j], 0.f); v0[j] = a * a; v1[j] = b * b; }
;                     *(u32x4*)(Hd + (size_t)(row0 + ai * 128 + m * 16) * DFF + col0 + bj * 128) = pack8(v0, v1);
;                 }
;             }
	global_store_dwordx4 v161, v[86:89], s[30:31] offset:256
	v_fmamk_f32 v162, v231, 0x3a000000, v251
	v_rsq_f32_e32 v162, v162
	v_add_u32_e32 v161, 0xc0000, v160
	v_pk_mul_f32 v[78:79], v[78:79], v[162:163] op_sel_hi:[1,0]
	v_pk_mul_f32 v[80:81], v[80:81], v[162:163] op_sel_hi:[1,0]
	v_pk_mul_f32 v[74:75], v[74:75], v[162:163] op_sel_hi:[1,0]
	v_pk_mul_f32 v[76:77], v[76:77], v[162:163] op_sel_hi:[1,0]
	v_max_f32_e32 v78, 0, v78
	v_max_f32_e32 v79, 0, v79
	v_max_f32_e32 v80, 0, v80
	v_max_f32_e32 v81, 0, v81
	v_max_f32_e32 v74, 0, v74
	v_max_f32_e32 v75, 0, v75
	v_max_f32_e32 v76, 0, v76
	v_max_f32_e32 v77, 0, v77
	v_pk_mul_f32 v[78:79], v[78:79], v[78:79]
	v_pk_mul_f32 v[80:81], v[80:81], v[80:81]
	v_pk_mul_f32 v[74:75], v[74:75], v[74:75]
	v_pk_mul_f32 v[76:77], v[76:77], v[76:77]
	v_cvt_pk_bf16_f32 v78, v78, v79
	v_cvt_pk_bf16_f32 v79, v80, v81
	v_cvt_pk_bf16_f32 v80, v74, v75
	v_cvt_pk_bf16_f32 v81, v76, v77
	global_store_dwordx4 v161, v[78:81], s[30:31]
	v_pk_mul_f32 v[70:71], v[70:71], v[162:163] op_sel_hi:[1,0]
	v_pk_mul_f32 v[72:73], v[72:73], v[162:163] op_sel_hi:[1,0]
	v_pk_mul_f32 v[66:67], v[66:67], v[162:163] op_sel_hi:[1,0]
	v_pk_mul_f32 v[68:69], v[68:69], v[162:163] op_sel_hi:[1,0]
	v_max_f32_e32 v70, 0, v70
	v_max_f32_e32 v71, 0, v71
	v_max_f32_e32 v72, 0, v72
	v_max_f32_e32 v73, 0, v73
	v_max_f32_e32 v66, 0, v66
	v_max_f32_e32 v67, 0, v67
	v_max_f32_e32 v68, 0, v68
	v_max_f32_e32 v69, 0, v69
	v_pk_mul_f32 v[70:71], v[70:71], v[70:71]
	v_pk_mul_f32 v[72:73], v[72:73], v[72:73]
	v_pk_mul_f32 v[66:67], v[66:67], v[66:67]
	v_pk_mul_f32 v[68:69], v[68:69], v[68:69]
	v_cvt_pk_bf16_f32 v70, v70, v71
	v_cvt_pk_bf16_f32 v71, v72, v73
	v_cvt_pk_bf16_f32 v72, v66, v67
	v_cvt_pk_bf16_f32 v73, v68, v69
	global_store_dwordx4 v161, v[70:73], s[30:31] offset:256
	v_fmamk_f32 v142, v232, 0x3a000000, v251
	v_rsq_f32_e32 v142, v142
	v_add_u32_e32 v161, 0x200000, v160
	v_pk_mul_f32 v[62:63], v[62:63], v[142:143] op_sel_hi:[1,0]
	v_pk_mul_f32 v[64:65], v[64:65], v[142:143] op_sel_hi:[1,0]
	v_pk_mul_f32 v[58:59], v[58:59], v[142:143] op_sel_hi:[1,0]
	v_pk_mul_f32 v[60:61], v[60:61], v[142:143] op_sel_hi:[1,0]
	v_max_f32_e32 v62, 0, v62
	v_max_f32_e32 v63, 0, v63
	v_max_f32_e32 v64, 0, v64
	v_max_f32_e32 v65, 0, v65
	v_max_f32_e32 v58, 0, v58
	v_max_f32_e32 v59, 0, v59
	v_max_f32_e32 v60, 0, v60
	v_max_f32_e32 v61, 0, v61
	v_pk_mul_f32 v[62:63], v[62:63], v[62:63]
	v_pk_mul_f32 v[64:65], v[64:65], v[64:65]
	v_pk_mul_f32 v[58:59], v[58:59], v[58:59]
	v_pk_mul_f32 v[60:61], v[60:61], v[60:61]
	v_cvt_pk_bf16_f32 v62, v62, v63
	v_cvt_pk_bf16_f32 v63, v64, v65
	v_cvt_pk_bf16_f32 v64, v58, v59
	v_cvt_pk_bf16_f32 v65, v60, v61
	global_store_dwordx4 v161, v[62:65], s[30:31]
	v_pk_mul_f32 v[54:55], v[54:55], v[142:143] op_sel_hi:[1,0]
	v_pk_mul_f32 v[56:57], v[56:57], v[142:143] op_sel_hi:[1,0]
	v_pk_mul_f32 v[50:51], v[50:51], v[142:143] op_sel_hi:[1,0]
	v_pk_mul_f32 v[52:53], v[52:53], v[142:143] op_sel_hi:[1,0]
	v_max_f32_e32 v54, 0, v54
	v_max_f32_e32 v55, 0, v55
	v_max_f32_e32 v56, 0, v56
	v_max_f32_e32 v57, 0, v57
	v_max_f32_e32 v50, 0, v50
	v_max_f32_e32 v51, 0, v51
	v_max_f32_e32 v52, 0, v52
	v_max_f32_e32 v53, 0, v53
	v_pk_mul_f32 v[54:55], v[54:55], v[54:55]
	v_pk_mul_f32 v[56:57], v[56:57], v[56:57]
	v_pk_mul_f32 v[50:51], v[50:51], v[50:51]
	v_pk_mul_f32 v[52:53], v[52:53], v[52:53]
	v_cvt_pk_bf16_f32 v54, v54, v55
	v_cvt_pk_bf16_f32 v55, v56, v57
	v_cvt_pk_bf16_f32 v56, v50, v51
	v_cvt_pk_bf16_f32 v57, v52, v53
	global_store_dwordx4 v161, v[54:57], s[30:31] offset:256
	v_fmamk_f32 v144, v233, 0x3a000000, v251
	v_rsq_f32_e32 v144, v144
	v_add_u32_e32 v161, 0x240000, v160
	v_pk_mul_f32 v[46:47], v[46:47], v[144:145] op_sel_hi:[1,0]
	v_pk_mul_f32 v[48:49], v[48:49], v[144:145] op_sel_hi:[1,0]
	v_pk_mul_f32 v[42:43], v[42:43], v[144:145] op_sel_hi:[1,0]
	v_pk_mul_f32 v[44:45], v[44:45], v[144:145] op_sel_hi:[1,0]
	v_max_f32_e32 v46, 0, v46
	v_max_f32_e32 v47, 0, v47
	v_max_f32_e32 v48, 0, v48
	v_max_f32_e32 v49, 0, v49
	v_max_f32_e32 v42, 0, v42
	v_max_f32_e32 v43, 0, v43
	v_max_f32_e32 v44, 0, v44
	v_max_f32_e32 v45, 0, v45
	v_pk_mul_f32 v[46:47], v[46:47], v[46:47]
	v_pk_mul_f32 v[48:49], v[48:49], v[48:49]
	v_pk_mul_f32 v[42:43], v[42:43], v[42:43]
	v_pk_mul_f32 v[44:45], v[44:45], v[44:45]
	v_cvt_pk_bf16_f32 v46, v46, v47
	v_cvt_pk_bf16_f32 v47, v48, v49
	v_cvt_pk_bf16_f32 v48, v42, v43
	v_cvt_pk_bf16_f32 v49, v44, v45
; __device__ __forceinline__ float rstd_of(float ss) { return rsqrtf(ss * (1.0f / DM) + EPS); }
; __device__ __forceinline__ u32x4 pack8(const f32x4 a, const f32x4 b) { u32x4 w; w.x = cvt_pk_bf16(a[0], a[1]); w.y = cvt_pk_bf16(a[2], a[3]); w.z = cvt_pk_bf16(b[0], b[1]); w.w = cvt_pk_bf16(b[2], b[3]); return w; }
;     __device__ __forceinline__ void operator()(const AccT& acc, const Unit& u, int wr, int wc, int fr, int fq) const {
;     ...
;         for (int ai = 0; ai < 2; ++ai)
; #pragma unroll
;             for (int m = 0; m < 4; ++m) {
;                 const float rs = rstd_of(rsv[ai][m]);
; #pragma unroll
;                 for (int bj = 0; bj < 2; ++bj) {
;                     f32x4 v0 = acc[ai][bj][m][0] * rs, v1 = acc[ai][bj][m][1] * rs;
; #pragma unroll
;                     for (int j = 0; j < 4; ++j) { const float a = fmaxf(v0[j], 0.f), b = fmaxf(v1[j], 0.f); v0[j] = a * a; v1[j] = b * b; }
;                     *(u32x4*)(Hd + (size_t)(row0 + ai * 128 + m * 16) * DFF + col0 + bj * 128) = pack8(v0, v1);
;                 }
;             }
	global_store_dwordx4 v161, v[46:49], s[30:31]
	v_pk_mul_f32 v[38:39], v[38:39], v[144:145] op_sel_hi:[1,0]
	v_pk_mul_f32 v[40:41], v[40:41], v[144:145] op_sel_hi:[1,0]
	v_pk_mul_f32 v[34:35], v[34:35], v[144:145] op_sel_hi:[1,0]
	v_pk_mul_f32 v[36:37], v[36:37], v[144:145] op_sel_hi:[1,0]
	v_max_f32_e32 v38, 0, v38
	v_max_f32_e32 v39, 0, v39
	v_max_f32_e32 v40, 0, v40
	v_max_f32_e32 v41, 0, v41
	v_max_f32_e32 v34, 0, v34
	v_max_f32_e32 v35, 0, v35
	v_max_f32_e32 v36, 0, v36
	v_max_f32_e32 v37, 0, v37
	v_pk_mul_f32 v[38:39], v[38:39], v[38:39]
	v_pk_mul_f32 v[40:41], v[40:41], v[40:41]
	v_pk_mul_f32 v[34:35], v[34:35], v[34:35]
	v_pk_mul_f32 v[36:37], v[36:37], v[36:37]
	v_cvt_pk_bf16_f32 v38, v38, v39
	v_cvt_pk_bf16_f32 v39, v40, v41
	v_cvt_pk_bf16_f32 v40, v34, v35
	v_cvt_pk_bf16_f32 v41, v36, v37
	global_store_dwordx4 v161, v[38:41], s[30:31] offset:256
	v_fmamk_f32 v146, v234, 0x3a000000, v251
	v_rsq_f32_e32 v146, v146
	v_add_u32_e32 v161, 0x280000, v160
	v_pk_mul_f32 v[30:31], v[30:31], v[146:147] op_sel_hi:[1,0]
	v_pk_mul_f32 v[32:33], v[32:33], v[146:147] op_sel_hi:[1,0]
	v_pk_mul_f32 v[26:27], v[26:27], v[146:147] op_sel_hi:[1,0]
	v_pk_mul_f32 v[28:29], v[28:29], v[146:147] op_sel_hi:[1,0]
	v_max_f32_e32 v30, 0, v30
	v_max_f32_e32 v31, 0, v31
	v_max_f32_e32 v32, 0, v32
	v_max_f32_e32 v33, 0, v33
	v_max_f32_e32 v26, 0, v26
	v_max_f32_e32 v27, 0, v27
	v_max_f32_e32 v28, 0, v28
	v_max_f32_e32 v29, 0, v29
	v_pk_mul_f32 v[30:31], v[30:31], v[30:31]
	v_pk_mul_f32 v[32:33], v[32:33], v[32:33]
	v_pk_mul_f32 v[26:27], v[26:27], v[26:27]
	v_pk_mul_f32 v[28:29], v[28:29], v[28:29]
	v_cvt_pk_bf16_f32 v30, v30, v31
	v_cvt_pk_bf16_f32 v31, v32, v33
	v_cvt_pk_bf16_f32 v32, v26, v27
	v_cvt_pk_bf16_f32 v33, v28, v29
	global_store_dwordx4 v161, v[30:33], s[30:31]
	v_pk_mul_f32 v[22:23], v[22:23], v[146:147] op_sel_hi:[1,0]
	v_pk_mul_f32 v[24:25], v[24:25], v[146:147] op_sel_hi:[1,0]
	v_pk_mul_f32 v[18:19], v[18:19], v[146:147] op_sel_hi:[1,0]
	v_pk_mul_f32 v[20:21], v[20:21], v[146:147] op_sel_hi:[1,0]
	v_max_f32_e32 v22, 0, v22
	v_max_f32_e32 v23, 0, v23
	v_max_f32_e32 v24, 0, v24
	v_max_f32_e32 v25, 0, v25
	v_max_f32_e32 v18, 0, v18
	v_max_f32_e32 v19, 0, v19
	v_max_f32_e32 v20, 0, v20
	v_max_f32_e32 v21, 0, v21
	v_pk_mul_f32 v[22:23], v[22:23], v[22:23]
	v_pk_mul_f32 v[24:25], v[24:25], v[24:25]
	v_pk_mul_f32 v[18:19], v[18:19], v[18:19]
	v_pk_mul_f32 v[20:21], v[20:21], v[20:21]
	v_cvt_pk_bf16_f32 v22, v22, v23
	v_cvt_pk_bf16_f32 v23, v24, v25
	v_cvt_pk_bf16_f32 v24, v18, v19
	v_cvt_pk_bf16_f32 v25, v20, v21
	global_store_dwordx4 v161, v[22:25], s[30:31] offset:256
	v_fmamk_f32 v162, v235, 0x3a000000, v251
	v_rsq_f32_e32 v162, v162
	v_add_u32_e32 v161, 0x2c0000, v160
	v_pk_mul_f32 v[14:15], v[14:15], v[162:163] op_sel_hi:[1,0]
	v_pk_mul_f32 v[16:17], v[16:17], v[162:163] op_sel_hi:[1,0]
	v_pk_mul_f32 v[10:11], v[10:11], v[162:163] op_sel_hi:[1,0]
	v_pk_mul_f32 v[12:13], v[12:13], v[162:163] op_sel_hi:[1,0]
	v_max_f32_e32 v14, 0, v14
	v_max_f32_e32 v15, 0, v15
	v_max_f32_e32 v16, 0, v16
	v_max_f32_e32 v17, 0, v17
	v_max_f32_e32 v10, 0, v10
	v_max_f32_e32 v11, 0, v11
	v_max_f32_e32 v12, 0, v12
	v_max_f32_e32 v13, 0, v13
	v_pk_mul_f32 v[14:15], v[14:15], v[14:15]
	v_pk_mul_f32 v[16:17], v[16:17], v[16:17]
	v_pk_mul_f32 v[10:11], v[10:11], v[10:11]
	v_pk_mul_f32 v[12:13], v[12:13], v[12:13]
	v_cvt_pk_bf16_f32 v14, v14, v15
	v_cvt_pk_bf16_f32 v15, v16, v17
	v_cvt_pk_bf16_f32 v16, v10, v11
	v_cvt_pk_bf16_f32 v17, v12, v13
	global_store_dwordx4 v161, v[14:17], s[30:31]
	v_pk_mul_f32 v[6:7], v[6:7], v[162:163] op_sel_hi:[1,0]
	v_pk_mul_f32 v[8:9], v[8:9], v[162:163] op_sel_hi:[1,0]
	v_pk_mul_f32 v[2:3], v[2:3], v[162:163] op_sel_hi:[1,0]
	v_pk_mul_f32 v[4:5], v[4:5], v[162:163] op_sel_hi:[1,0]
	v_max_f32_e32 v6, 0, v6
	v_max_f32_e32 v7, 0, v7
	v_max_f32_e32 v8, 0, v8
	v_max_f32_e32 v9, 0, v9
	v_max_f32_e32 v2, 0, v2
	v_max_f32_e32 v3, 0, v3
	v_max_f32_e32 v4, 0, v4
	v_max_f32_e32 v5, 0, v5
	v_pk_mul_f32 v[6:7], v[6:7], v[6:7]
	v_pk_mul_f32 v[8:9], v[8:9], v[8:9]
	v_pk_mul_f32 v[2:3], v[2:3], v[2:3]
	v_pk_mul_f32 v[4:5], v[4:5], v[4:5]
	v_cvt_pk_bf16_f32 v6, v6, v7
	v_cvt_pk_bf16_f32 v7, v8, v9
	v_cvt_pk_bf16_f32 v8, v2, v3
	v_cvt_pk_bf16_f32 v9, v4, v5
	global_store_dwordx4 v161, v[6:9], s[30:31] offset:256
	s_and_b64 vcc, exec, s[0:1]
	s_mov_b64 s[10:11], s[4:5]
	s_cbranch_vccz .LBB0_260
	s_waitcnt vmcnt(0)
	s_cmpk_gt_u32 s16, 0xff
	s_cbranch_scc1 .LBB0_271
	s_barrier

; #define PG8_STAGE(bufoff, gbase, voff) do { _Pragma("unroll") for (int _i = 0; _i < 2; ++_i) \
;         __builtin_amdgcn_global_load_lds((const unsigned*)((const char*)(gbase) + (voff)[_i]), (LAS unsigned*)(lds + (bufoff) + ldsw + _i * 8192), 16, 0, 0); } while (0)
; #define PG8_LDA(dst, b, h) do { _Pragma("unroll") for (int m = 0; m < 4; ++m) _Pragma("unroll") for (int k = 0; k < 2; ++k) dst[m][k] = *(const LAS bf16x8*)(lds + PG8_SA(b, h) + aoff + m * 2048 + k * 1024); } while (0)
; #define PG8_LDB(dst, b, h) do { _Pragma("unroll") for (int n = 0; n < 2; ++n) _Pragma("unroll") for (int k = 0; k < 2; ++k) dst[n][k] = *(const LAS bf16x8*)(lds + PG8_SB(b, h) + boff + n * 2048 + k * 1024); } while (0)
; #define PG8_MMA(ai, bj, At, Bt) do { __builtin_amdgcn_s_setprio(1); _Pragma("unroll") for (int m = 0; m < 4; ++m) _Pragma("unroll") for (int n = 0; n < 2; ++n) _Pragma("unroll") for (int k = 0; k < 2; ++k) \
;         acc[ai][bj][m][n] = __builtin_amdgcn_mfma_f32_16x16x32_bf16(Bt[n][k], At[m][k], acc[ai][bj][m][n], 0, 0, 0); __builtin_amdgcn_s_setprio(0); } while (0)
; #define PG8_WAIT_L(n) asm volatile("s_waitcnt lgkmcnt(" #n ")" ::: "memory")
; #define PG8_BAR __builtin_amdgcn_s_barrier()
; #define PG8_SCHED __builtin_amdgcn_sched_barrier(0)
; template <class Epi, class Sched>
; __device__ __forceinline__ void gemm_phase(LAS unsigned char* lds_in, const int lda, const int ldb, const Sched& S, const Epi& E, const int WID) {
;     ...
;             PG8_LDB(B0, 0, 0); PG8_SCHED; PG8_LDA(At, 0, 0); PG8_STAGE(PG8_SA(1, 1), a1 + hstepA, voffA);
;             PG8_WAIT_L(8); PG8_BAR; PG8_WAIT_L(0); PG8_MMA(0, 0, At, B0); PG8_BAR; PG8_SCHED;
;             PG8_LDB(B1, 0, 1); PG8_STAGE(PG8_SB(0, 0), b2, voffB);
;             PG8_BAR; PG8_WAIT_L(0); PG8_MMA(0, 1, At, B1); PG8_BAR;
;     ...
; #pragma unroll
;         for (int a = 0; a < 2; ++a)
; #pragma unroll
;             for (int b = 0; b < 2; ++b)
; #pragma unroll
;                 for (int m = 0; m < 4; ++m)
; #pragma unroll
;                     for (int n = 0; n < 2; ++n) acc[a][b][m][n] = (f32x4){0.f, 0.f, 0.f, 0.f};
.LBB0_300:
	s_add_u32 s12, s12, 0x80080
	s_addc_u32 s13, s13, 0
	s_add_u32 s5, s14, 0x100
	v_mov_b32_e32 v2, 0
	s_addc_u32 s11, s15, 0
	s_mov_b32 s97, -2
	s_waitcnt lgkmcnt(0)
	v_mov_b32_e32 v3, v2
	v_mov_b32_e32 v4, v2
	v_mov_b32_e32 v5, v2
	v_mov_b32_e32 v6, v2
	v_mov_b32_e32 v7, v2
	v_mov_b32_e32 v8, v2
	v_mov_b32_e32 v9, v2
	v_mov_b32_e32 v18, v2
	v_mov_b32_e32 v19, v2
	v_mov_b32_e32 v20, v2
	v_mov_b32_e32 v21, v2
	v_mov_b32_e32 v22, v2
	v_mov_b32_e32 v23, v2
	v_mov_b32_e32 v24, v2
	v_mov_b32_e32 v25, v2
	v_mov_b32_e32 v34, v2
	v_mov_b32_e32 v35, v2
	v_mov_b32_e32 v36, v2
	v_mov_b32_e32 v37, v2
	v_mov_b32_e32 v38, v2
	v_mov_b32_e32 v39, v2
	v_mov_b32_e32 v40, v2
	v_mov_b32_e32 v41, v2
	v_mov_b32_e32 v50, v2
	v_mov_b32_e32 v51, v2
	v_mov_b32_e32 v52, v2
	v_mov_b32_e32 v53, v2
	v_mov_b32_e32 v54, v2
	v_mov_b32_e32 v55, v2
	v_mov_b32_e32 v56, v2
	v_mov_b32_e32 v57, v2
	v_mov_b32_e32 v10, v2
	v_mov_b32_e32 v11, v2
	v_mov_b32_e32 v12, v2
	v_mov_b32_e32 v13, v2
	v_mov_b32_e32 v14, v2
	v_mov_b32_e32 v15, v2
	v_mov_b32_e32 v16, v2
	v_mov_b32_e32 v17, v2
	v_mov_b32_e32 v26, v2
	v_mov_b32_e32 v27, v2
	v_mov_b32_e32 v28, v2
	v_mov_b32_e32 v29, v2
	v_mov_b32_e32 v30, v2
	v_mov_b32_e32 v31, v2
	v_mov_b32_e32 v32, v2
	v_mov_b32_e32 v33, v2
	v_mov_b32_e32 v42, v2
	v_mov_b32_e32 v43, v2
	v_mov_b32_e32 v44, v2
	v_mov_b32_e32 v45, v2
	v_mov_b32_e32 v46, v2
	v_mov_b32_e32 v47, v2
	v_mov_b32_e32 v48, v2
	v_mov_b32_e32 v49, v2
	v_mov_b32_e32 v58, v2
	v_mov_b32_e32 v59, v2
	v_mov_b32_e32 v60, v2
	v_mov_b32_e32 v61, v2
	v_mov_b32_e32 v62, v2
	v_mov_b32_e32 v63, v2
	v_mov_b32_e32 v64, v2
	v_mov_b32_e32 v65, v2
	v_mov_b32_e32 v66, v2
	v_mov_b32_e32 v67, v2
	v_mov_b32_e32 v68, v2
	v_mov_b32_e32 v69, v2
	v_mov_b32_e32 v70, v2
	v_mov_b32_e32 v71, v2
	v_mov_b32_e32 v72, v2
	v_mov_b32_e32 v73, v2
	v_mov_b32_e32 v82, v2
	v_mov_b32_e32 v83, v2
	v_mov_b32_e32 v84, v2
	v_mov_b32_e32 v85, v2
	v_mov_b32_e32 v86, v2
	v_mov_b32_e32 v87, v2
	v_mov_b32_e32 v88, v2
	v_mov_b32_e32 v89, v2
	v_mov_b32_e32 v98, v2
	v_mov_b32_e32 v99, v2
	v_mov_b32_e32 v100, v2
	v_mov_b32_e32 v101, v2
	v_mov_b32_e32 v102, v2
	v_mov_b32_e32 v103, v2
	v_mov_b32_e32 v104, v2
	v_mov_b32_e32 v105, v2
	v_mov_b32_e32 v122, v2
	v_mov_b32_e32 v123, v2
	v_mov_b32_e32 v124, v2
	v_mov_b32_e32 v125, v2
	v_mov_b32_e32 v126, v2
	v_mov_b32_e32 v127, v2
	v_mov_b32_e32 v128, v2
	v_mov_b32_e32 v129, v2
	v_mov_b32_e32 v74, v2
	v_mov_b32_e32 v75, v2
	v_mov_b32_e32 v76, v2
	v_mov_b32_e32 v77, v2
	v_mov_b32_e32 v78, v2
	v_mov_b32_e32 v79, v2
	v_mov_b32_e32 v80, v2
	v_mov_b32_e32 v81, v2
	v_mov_b32_e32 v90, v2
	v_mov_b32_e32 v91, v2
	v_mov_b32_e32 v92, v2
	v_mov_b32_e32 v93, v2
	v_mov_b32_e32 v94, v2
	v_mov_b32_e32 v95, v2
	v_mov_b32_e32 v96, v2
	v_mov_b32_e32 v97, v2
	v_mov_b32_e32 v106, v2
	v_mov_b32_e32 v107, v2
	v_mov_b32_e32 v108, v2
	v_mov_b32_e32 v109, v2
	v_mov_b32_e32 v110, v2
	v_mov_b32_e32 v111, v2
	v_mov_b32_e32 v112, v2
	v_mov_b32_e32 v113, v2
	v_mov_b32_e32 v150, v2
	v_mov_b32_e32 v151, v2
	v_mov_b32_e32 v152, v2
	v_mov_b32_e32 v153, v2
	v_mov_b32_e32 v154, v2
	v_mov_b32_e32 v155, v2
	v_mov_b32_e32 v156, v2
	v_mov_b32_e32 v157, v2
	v_add_u32_e32 v236, s21, v251
	v_add_u32_e32 v237, s47, v251
	v_add_u32_e32 v238, s65, v251
	v_add_u32_e32 v239, s91, v251
.LBB0_301:
	s_barrier
	ds_read_b128 v[114:117], v236
	ds_read_b128 v[118:121], v236 offset:1024
	ds_read_b128 v[130:133], v236 offset:2048
	ds_read_b128 v[134:137], v236 offset:3072
	s_add_u32 s14, s12, 0xfff80080
	s_addc_u32 s15, s13, -1
	s_cmp_eq_u32 s97, 28
	s_cselect_b32 s17, s7, s15
	s_cselect_b32 s16, s6, s14
	s_cselect_b32 s15, s9, s11
	s_cselect_b32 s14, s8, s5
	s_add_i32 m0, s35, 0xc000
	ds_read_b128 v[138:141], v253
	ds_read_b128 v[142:145], v253 offset:1024
	ds_read_b128 v[146:149], v253 offset:2048
	ds_read_b128 v[158:161], v253 offset:3072
	ds_read_b128 v[162:165], v253 offset:4096
	ds_read_b128 v[166:169], v253 offset:5120
	ds_read_b128 v[170:173], v253 offset:6144
	ds_read_b128 v[174:177], v253 offset:7168
	global_load_lds_dwordx4 v202, s[12:13]
	s_add_i32 m0, s35, 0xe000
	s_nop 0
	global_load_lds_dwordx4 v204, s[12:13]
	s_waitcnt lgkmcnt(8)
	s_barrier
	s_waitcnt lgkmcnt(0)
	s_setprio 1
	s_waitcnt lgkmcnt(0)
	v_mfma_f32_16x16x32_bf16 v[154:157], v[114:117], v[138:141], v[154:157]
	v_mfma_f32_16x16x32_bf16 v[150:153], v[130:133], v[138:141], v[150:153]
	v_mfma_f32_16x16x32_bf16 v[110:113], v[114:117], v[146:149], v[110:113]
	v_mfma_f32_16x16x32_bf16 v[106:109], v[130:133], v[146:149], v[106:109]
	v_mfma_f32_16x16x32_bf16 v[94:97], v[114:117], v[162:165], v[94:97]
	v_mfma_f32_16x16x32_bf16 v[90:93], v[130:133], v[162:165], v[90:93]
	v_mfma_f32_16x16x32_bf16 v[78:81], v[114:117], v[170:173], v[78:81]
	v_mfma_f32_16x16x32_bf16 v[74:77], v[130:133], v[170:173], v[74:77]
	v_mfma_f32_16x16x32_bf16 v[154:157], v[118:121], v[142:145], v[154:157]
	v_mfma_f32_16x16x32_bf16 v[150:153], v[134:137], v[142:145], v[150:153]
	v_mfma_f32_16x16x32_bf16 v[110:113], v[118:121], v[158:161], v[110:113]
	v_mfma_f32_16x16x32_bf16 v[106:109], v[134:137], v[158:161], v[106:109]
	v_mfma_f32_16x16x32_bf16 v[94:97], v[118:121], v[166:169], v[94:97]
	v_mfma_f32_16x16x32_bf16 v[90:93], v[134:137], v[166:169], v[90:93]
	v_mfma_f32_16x16x32_bf16 v[78:81], v[118:121], v[174:177], v[78:81]
	v_mfma_f32_16x16x32_bf16 v[74:77], v[134:137], v[174:177], v[74:77]
	s_setprio 0
	s_barrier
	s_mov_b32 m0, s22
	ds_read_b128 v[178:181], v237
	ds_read_b128 v[182:185], v237 offset:1024
	ds_read_b128 v[186:189], v237 offset:2048
	ds_read_b128 v[190:193], v237 offset:3072
	global_load_lds_dwordx4 v196, s[14:15]
	s_mov_b32 m0, s23
	s_nop 0
	global_load_lds_dwordx4 v200, s[14:15]
	s_barrier
; #define PG8_STAGE(bufoff, gbase, voff) do { _Pragma("unroll") for (int _i = 0; _i < 2; ++_i) \
;         __builtin_amdgcn_global_load_lds((const unsigned*)((const char*)(gbase) + (voff)[_i]), (LAS unsigned*)(lds + (bufoff) + ldsw + _i * 8192), 16, 0, 0); } while (0)
; #define PG8_LDA(dst, b, h) do { _Pragma("unroll") for (int m = 0; m < 4; ++m) _Pragma("unroll") for (int k = 0; k < 2; ++k) dst[m][k] = *(const LAS bf16x8*)(lds + PG8_SA(b, h) + aoff + m * 2048 + k * 1024); } while (0)
; #define PG8_LDB(dst, b, h) do { _Pragma("unroll") for (int n = 0; n < 2; ++n) _Pragma("unroll") for (int k = 0; k < 2; ++k) dst[n][k] = *(const LAS bf16x8*)(lds + PG8_SB(b, h) + boff + n * 2048 + k * 1024); } while (0)
; #define PG8_MMA(ai, bj, At, Bt) do { __builtin_amdgcn_s_setprio(1); _Pragma("unroll") for (int m = 0; m < 4; ++m) _Pragma("unroll") for (int n = 0; n < 2; ++n) _Pragma("unroll") for (int k = 0; k < 2; ++k) \
;         acc[ai][bj][m][n] = __builtin_amdgcn_mfma_f32_16x16x32_bf16(Bt[n][k], At[m][k], acc[ai][bj][m][n], 0, 0, 0); __builtin_amdgcn_s_setprio(0); } while (0)
; #define PG8_WAIT_V(n) asm volatile("s_waitcnt vmcnt(" #n ")" ::: "memory")
; #define PG8_WAIT_L(n) asm volatile("s_waitcnt lgkmcnt(" #n ")" ::: "memory")
; #define PG8_BAR __builtin_amdgcn_s_barrier()
; #define PG8_SCHED __builtin_amdgcn_sched_barrier(0)
; template <class Epi, class Sched>
; __device__ __forceinline__ void gemm_phase(LAS unsigned char* lds_in, const int lda, const int ldb, const Sched& S, const Epi& E, const int WID) {
;     ...
;             PG8_BAR; PG8_WAIT_L(0); PG8_MMA(0, 1, At, B1); PG8_BAR;
;             PG8_LDA(At, 0, 1); PG8_STAGE(PG8_SA(0, 0), a2, voffA);
;             PG8_BAR; PG8_WAIT_L(0); PG8_MMA(1, 0, At, B0); PG8_BAR; PG8_SCHED;
;             PG8_STAGE(PG8_SB(0, 1), b2 + hstepB, voffB);
;             PG8_WAIT_V(6); PG8_BAR; PG8_MMA(1, 1, At, B1); PG8_BAR;
;             PG8_LDB(B0, 1, 0); PG8_SCHED; PG8_LDA(At, 1, 0); PG8_STAGE(PG8_SA(0, 1), a2 + hstepA, voffA);
;             PG8_WAIT_L(8); PG8_BAR; PG8_WAIT_L(0); PG8_MMA(0, 0, At, B0); PG8_BAR; PG8_SCHED;
	s_waitcnt lgkmcnt(0)
	s_setprio 1
	s_waitcnt lgkmcnt(0)
	v_mfma_f32_16x16x32_bf16 v[126:129], v[178:181], v[138:141], v[126:129]
	v_mfma_f32_16x16x32_bf16 v[122:125], v[186:189], v[138:141], v[122:125]
	v_mfma_f32_16x16x32_bf16 v[102:105], v[178:181], v[146:149], v[102:105]
	v_mfma_f32_16x16x32_bf16 v[98:101], v[186:189], v[146:149], v[98:101]
	v_mfma_f32_16x16x32_bf16 v[86:89], v[178:181], v[162:165], v[86:89]
	v_mfma_f32_16x16x32_bf16 v[82:85], v[186:189], v[162:165], v[82:85]
	v_mfma_f32_16x16x32_bf16 v[70:73], v[178:181], v[170:173], v[70:73]
	v_mfma_f32_16x16x32_bf16 v[66:69], v[186:189], v[170:173], v[66:69]
	v_mfma_f32_16x16x32_bf16 v[126:129], v[182:185], v[142:145], v[126:129]
	v_mfma_f32_16x16x32_bf16 v[122:125], v[190:193], v[142:145], v[122:125]
	v_mfma_f32_16x16x32_bf16 v[102:105], v[182:185], v[158:161], v[102:105]
	v_mfma_f32_16x16x32_bf16 v[98:101], v[190:193], v[158:161], v[98:101]
	v_mfma_f32_16x16x32_bf16 v[86:89], v[182:185], v[166:169], v[86:89]
	v_mfma_f32_16x16x32_bf16 v[82:85], v[190:193], v[166:169], v[82:85]
	v_mfma_f32_16x16x32_bf16 v[70:73], v[182:185], v[174:177], v[70:73]
	v_mfma_f32_16x16x32_bf16 v[66:69], v[190:193], v[174:177], v[66:69]
	s_setprio 0
	s_mov_b32 m0, s35
	s_barrier
	ds_read_b128 v[138:141], v253 offset:16384
	ds_read_b128 v[142:145], v253 offset:17408
	ds_read_b128 v[146:149], v253 offset:18432
	ds_read_b128 v[158:161], v253 offset:19456
	ds_read_b128 v[162:165], v253 offset:20480
	ds_read_b128 v[166:169], v253 offset:21504
	ds_read_b128 v[170:173], v253 offset:22528
	ds_read_b128 v[174:177], v253 offset:23552
	global_load_lds_dwordx4 v194, s[16:17]
	s_mov_b32 m0, s46
	s_nop 0
	global_load_lds_dwordx4 v198, s[16:17]
	s_barrier
	s_waitcnt lgkmcnt(0)
	s_setprio 1
	s_waitcnt lgkmcnt(0)
	v_mfma_f32_16x16x32_bf16 v[62:65], v[114:117], v[138:141], v[62:65]
	v_mfma_f32_16x16x32_bf16 v[58:61], v[130:133], v[138:141], v[58:61]
	v_mfma_f32_16x16x32_bf16 v[46:49], v[114:117], v[146:149], v[46:49]
	v_mfma_f32_16x16x32_bf16 v[42:45], v[130:133], v[146:149], v[42:45]
	v_mfma_f32_16x16x32_bf16 v[30:33], v[114:117], v[162:165], v[30:33]
	v_mfma_f32_16x16x32_bf16 v[26:29], v[130:133], v[162:165], v[26:29]
	v_mfma_f32_16x16x32_bf16 v[14:17], v[114:117], v[170:173], v[14:17]
	v_mfma_f32_16x16x32_bf16 v[10:13], v[130:133], v[170:173], v[10:13]
	v_mfma_f32_16x16x32_bf16 v[62:65], v[118:121], v[142:145], v[62:65]
	v_mfma_f32_16x16x32_bf16 v[58:61], v[134:137], v[142:145], v[58:61]
	v_mfma_f32_16x16x32_bf16 v[46:49], v[118:121], v[158:161], v[46:49]
	v_mfma_f32_16x16x32_bf16 v[42:45], v[134:137], v[158:161], v[42:45]
	v_mfma_f32_16x16x32_bf16 v[30:33], v[118:121], v[166:169], v[30:33]
	v_mfma_f32_16x16x32_bf16 v[26:29], v[134:137], v[166:169], v[26:29]
	v_mfma_f32_16x16x32_bf16 v[14:17], v[118:121], v[174:177], v[14:17]
	v_mfma_f32_16x16x32_bf16 v[10:13], v[134:137], v[174:177], v[10:13]
	s_setprio 0
	s_barrier
	s_add_u32 s66, s14, 0x80000
	s_addc_u32 s67, s15, 0
	s_mov_b32 m0, s48
	s_nop 0
	global_load_lds_dwordx4 v196, s[66:67]
	s_mov_b32 m0, s49
	s_nop 0
	global_load_lds_dwordx4 v200, s[66:67]
	s_waitcnt vmcnt(6)
	s_barrier
	s_setprio 1
	v_mfma_f32_16x16x32_bf16 v[54:57], v[178:181], v[138:141], v[54:57]
	v_mfma_f32_16x16x32_bf16 v[50:53], v[186:189], v[138:141], v[50:53]
	v_mfma_f32_16x16x32_bf16 v[38:41], v[178:181], v[146:149], v[38:41]
	v_mfma_f32_16x16x32_bf16 v[34:37], v[186:189], v[146:149], v[34:37]
	v_mfma_f32_16x16x32_bf16 v[22:25], v[178:181], v[162:165], v[22:25]
	v_mfma_f32_16x16x32_bf16 v[18:21], v[186:189], v[162:165], v[18:21]
	v_mfma_f32_16x16x32_bf16 v[6:9], v[178:181], v[170:173], v[6:9]
	v_mfma_f32_16x16x32_bf16 v[2:5], v[186:189], v[170:173], v[2:5]
	v_mfma_f32_16x16x32_bf16 v[54:57], v[182:185], v[142:145], v[54:57]
	v_mfma_f32_16x16x32_bf16 v[50:53], v[190:193], v[142:145], v[50:53]
	v_mfma_f32_16x16x32_bf16 v[38:41], v[182:185], v[158:161], v[38:41]
	v_mfma_f32_16x16x32_bf16 v[34:37], v[190:193], v[158:161], v[34:37]
	v_mfma_f32_16x16x32_bf16 v[22:25], v[182:185], v[166:169], v[22:25]
	v_mfma_f32_16x16x32_bf16 v[18:21], v[190:193], v[166:169], v[18:21]
	v_mfma_f32_16x16x32_bf16 v[6:9], v[182:185], v[174:177], v[6:9]
	v_mfma_f32_16x16x32_bf16 v[2:5], v[190:193], v[174:177], v[2:5]
	s_setprio 0
	s_barrier
	ds_read_b128 v[114:117], v238
	ds_read_b128 v[118:121], v238 offset:1024
	ds_read_b128 v[130:133], v238 offset:2048
	ds_read_b128 v[134:137], v238 offset:3072
	s_add_u32 s16, s16, 0x80000
	s_addc_u32 s17, s17, 0
	s_mov_b32 m0, s50
	ds_read_b128 v[138:141], v253 offset:32768
	ds_read_b128 v[142:145], v253 offset:33792
	ds_read_b128 v[146:149], v253 offset:34816
	ds_read_b128 v[158:161], v253 offset:35840
	ds_read_b128 v[162:165], v253 offset:36864
	ds_read_b128 v[166:169], v253 offset:37888
	ds_read_b128 v[170:173], v253 offset:38912
	ds_read_b128 v[174:177], v253 offset:39936
	global_load_lds_dwordx4 v194, s[16:17]
	s_mov_b32 m0, s51
	s_nop 0
	global_load_lds_dwordx4 v198, s[16:17]
	s_waitcnt lgkmcnt(8)
	s_barrier
	s_waitcnt lgkmcnt(0)
	s_setprio 1
	s_waitcnt lgkmcnt(0)
	v_mfma_f32_16x16x32_bf16 v[154:157], v[114:117], v[138:141], v[154:157]
	v_mfma_f32_16x16x32_bf16 v[150:153], v[130:133], v[138:141], v[150:153]
	v_mfma_f32_16x16x32_bf16 v[110:113], v[114:117], v[146:149], v[110:113]
	v_mfma_f32_16x16x32_bf16 v[106:109], v[130:133], v[146:149], v[106:109]
	v_mfma_f32_16x16x32_bf16 v[94:97], v[114:117], v[162:165], v[94:97]
	v_mfma_f32_16x16x32_bf16 v[90:93], v[130:133], v[162:165], v[90:93]
	v_mfma_f32_16x16x32_bf16 v[78:81], v[114:117], v[170:173], v[78:81]
	v_mfma_f32_16x16x32_bf16 v[74:77], v[130:133], v[170:173], v[74:77]
	v_mfma_f32_16x16x32_bf16 v[154:157], v[118:121], v[142:145], v[154:157]
	v_mfma_f32_16x16x32_bf16 v[150:153], v[134:137], v[142:145], v[150:153]
	v_mfma_f32_16x16x32_bf16 v[110:113], v[118:121], v[158:161], v[110:113]
	v_mfma_f32_16x16x32_bf16 v[106:109], v[134:137], v[158:161], v[106:109]
	v_mfma_f32_16x16x32_bf16 v[94:97], v[118:121], v[166:169], v[94:97]
	v_mfma_f32_16x16x32_bf16 v[90:93], v[134:137], v[166:169], v[90:93]
	v_mfma_f32_16x16x32_bf16 v[78:81], v[118:121], v[174:177], v[78:81]
	v_mfma_f32_16x16x32_bf16 v[74:77], v[134:137], v[174:177], v[74:77]
	s_setprio 0
	s_barrier
; #define PG8_STAGE(bufoff, gbase, voff) do { _Pragma("unroll") for (int _i = 0; _i < 2; ++_i) \
;         __builtin_amdgcn_global_load_lds((const unsigned*)((const char*)(gbase) + (voff)[_i]), (LAS unsigned*)(lds + (bufoff) + ldsw + _i * 8192), 16, 0, 0); } while (0)
; #define PG8_LDA(dst, b, h) do { _Pragma("unroll") for (int m = 0; m < 4; ++m) _Pragma("unroll") for (int k = 0; k < 2; ++k) dst[m][k] = *(const LAS bf16x8*)(lds + PG8_SA(b, h) + aoff + m * 2048 + k * 1024); } while (0)
; #define PG8_LDB(dst, b, h) do { _Pragma("unroll") for (int n = 0; n < 2; ++n) _Pragma("unroll") for (int k = 0; k < 2; ++k) dst[n][k] = *(const LAS bf16x8*)(lds + PG8_SB(b, h) + boff + n * 2048 + k * 1024); } while (0)
; #define PG8_MMA(ai, bj, At, Bt) do { __builtin_amdgcn_s_setprio(1); _Pragma("unroll") for (int m = 0; m < 4; ++m) _Pragma("unroll") for (int n = 0; n < 2; ++n) _Pragma("unroll") for (int k = 0; k < 2; ++k) \
;         acc[ai][bj][m][n] = __builtin_amdgcn_mfma_f32_16x16x32_bf16(Bt[n][k], At[m][k], acc[ai][bj][m][n], 0, 0, 0); __builtin_amdgcn_s_setprio(0); } while (0)
; #define PG8_WAIT_V(n) asm volatile("s_waitcnt vmcnt(" #n ")" ::: "memory")
; #define PG8_WAIT_L(n) asm volatile("s_waitcnt lgkmcnt(" #n ")" ::: "memory")
; #define PG8_BAR __builtin_amdgcn_s_barrier()
; #define PG8_SCHED __builtin_amdgcn_sched_barrier(0)
; template <class Epi, class Sched>
; __device__ __forceinline__ void gemm_phase(LAS unsigned char* lds_in, const int lda, const int ldb, const Sched& S, const Epi& E, const int WID) {
;     ...
;             PG8_LDB(B1, 1, 1); PG8_STAGE(PG8_SB(1, 0), b3, voffB);
;             PG8_BAR; PG8_WAIT_L(0); PG8_MMA(0, 1, At, B1); PG8_BAR;
;             PG8_LDA(At, 1, 1); PG8_STAGE(PG8_SA(1, 0), a3, voffA);
;             PG8_BAR; PG8_WAIT_L(0); PG8_MMA(1, 0, At, B0); PG8_BAR; PG8_SCHED;
;             PG8_STAGE(PG8_SB(1, 1), b3 + hstepB, voffB);
;             PG8_WAIT_V(6); PG8_BAR; PG8_MMA(1, 1, At, B1); PG8_BAR;
	s_mov_b32 m0, s70
	s_add_u32 s100, s14, 0x80
	s_addc_u32 s101, s15, 0
	ds_read_b128 v[178:181], v239
	ds_read_b128 v[182:185], v239 offset:1024
	ds_read_b128 v[186:189], v239 offset:2048
	ds_read_b128 v[190:193], v239 offset:3072
	global_load_lds_dwordx4 v196, s[100:101]
	s_add_u32 s100, s14, 0x80
	s_addc_u32 s101, s15, 0
	s_mov_b32 m0, s78
	s_nop 0
	global_load_lds_dwordx4 v200, s[100:101]
	s_barrier
	s_waitcnt lgkmcnt(0)
	s_setprio 1
	s_waitcnt lgkmcnt(0)
	v_mfma_f32_16x16x32_bf16 v[126:129], v[178:181], v[138:141], v[126:129]
	v_mfma_f32_16x16x32_bf16 v[122:125], v[186:189], v[138:141], v[122:125]
	v_mfma_f32_16x16x32_bf16 v[102:105], v[178:181], v[146:149], v[102:105]
	v_mfma_f32_16x16x32_bf16 v[98:101], v[186:189], v[146:149], v[98:101]
	v_mfma_f32_16x16x32_bf16 v[86:89], v[178:181], v[162:165], v[86:89]
	v_mfma_f32_16x16x32_bf16 v[82:85], v[186:189], v[162:165], v[82:85]
	v_mfma_f32_16x16x32_bf16 v[70:73], v[178:181], v[170:173], v[70:73]
	v_mfma_f32_16x16x32_bf16 v[66:69], v[186:189], v[170:173], v[66:69]
	v_mfma_f32_16x16x32_bf16 v[126:129], v[182:185], v[142:145], v[126:129]
	v_mfma_f32_16x16x32_bf16 v[122:125], v[190:193], v[142:145], v[122:125]
	v_mfma_f32_16x16x32_bf16 v[102:105], v[182:185], v[158:161], v[102:105]
	v_mfma_f32_16x16x32_bf16 v[98:101], v[190:193], v[158:161], v[98:101]
	v_mfma_f32_16x16x32_bf16 v[86:89], v[182:185], v[166:169], v[86:89]
	v_mfma_f32_16x16x32_bf16 v[82:85], v[190:193], v[166:169], v[82:85]
	v_mfma_f32_16x16x32_bf16 v[70:73], v[182:185], v[174:177], v[70:73]
	v_mfma_f32_16x16x32_bf16 v[66:69], v[190:193], v[174:177], v[66:69]
	s_setprio 0
	s_mov_b32 m0, s79
	s_add_u32 s100, s16, 0xfff80080
	s_addc_u32 s101, s17, -1
	s_barrier
	ds_read_b128 v[138:141], v253 offset:49152
	ds_read_b128 v[142:145], v253 offset:50176
	ds_read_b128 v[146:149], v253 offset:51200
	ds_read_b128 v[158:161], v253 offset:52224
	ds_read_b128 v[162:165], v253 offset:53248
	ds_read_b128 v[166:169], v253 offset:54272
	ds_read_b128 v[170:173], v253 offset:55296
	ds_read_b128 v[174:177], v253 offset:56320
	global_load_lds_dwordx4 v194, s[100:101]
	s_add_u32 s100, s16, 0xfff80080
	s_addc_u32 s101, s17, -1
	s_mov_b32 m0, s90
	s_nop 0
	global_load_lds_dwordx4 v198, s[100:101]
	s_barrier
	s_waitcnt lgkmcnt(0)
	s_setprio 1
	s_waitcnt lgkmcnt(0)
	v_mfma_f32_16x16x32_bf16 v[62:65], v[114:117], v[138:141], v[62:65]
	v_mfma_f32_16x16x32_bf16 v[58:61], v[130:133], v[138:141], v[58:61]
	v_mfma_f32_16x16x32_bf16 v[46:49], v[114:117], v[146:149], v[46:49]
	v_mfma_f32_16x16x32_bf16 v[42:45], v[130:133], v[146:149], v[42:45]
	v_mfma_f32_16x16x32_bf16 v[30:33], v[114:117], v[162:165], v[30:33]
	v_mfma_f32_16x16x32_bf16 v[26:29], v[130:133], v[162:165], v[26:29]
	v_mfma_f32_16x16x32_bf16 v[14:17], v[114:117], v[170:173], v[14:17]
	v_mfma_f32_16x16x32_bf16 v[10:13], v[130:133], v[170:173], v[10:13]
	v_mfma_f32_16x16x32_bf16 v[62:65], v[118:121], v[142:145], v[62:65]
	v_mfma_f32_16x16x32_bf16 v[58:61], v[134:137], v[142:145], v[58:61]
	v_mfma_f32_16x16x32_bf16 v[46:49], v[118:121], v[158:161], v[46:49]
	v_mfma_f32_16x16x32_bf16 v[42:45], v[134:137], v[158:161], v[42:45]
	v_mfma_f32_16x16x32_bf16 v[30:33], v[118:121], v[166:169], v[30:33]
	v_mfma_f32_16x16x32_bf16 v[26:29], v[134:137], v[166:169], v[26:29]
	v_mfma_f32_16x16x32_bf16 v[14:17], v[118:121], v[174:177], v[14:17]
	v_mfma_f32_16x16x32_bf16 v[10:13], v[134:137], v[174:177], v[10:13]
	s_setprio 0
	s_barrier
	s_add_u32 s14, s14, 0x80080
	s_addc_u32 s15, s15, 0
	s_mov_b32 m0, s92
	s_nop 0
	global_load_lds_dwordx4 v196, s[14:15]
	s_mov_b32 m0, s93
	s_nop 0
	global_load_lds_dwordx4 v200, s[14:15]
	s_waitcnt vmcnt(6)
	s_barrier
	s_setprio 1
	v_mfma_f32_16x16x32_bf16 v[54:57], v[178:181], v[138:141], v[54:57]
	v_mfma_f32_16x16x32_bf16 v[50:53], v[186:189], v[138:141], v[50:53]
	v_mfma_f32_16x16x32_bf16 v[38:41], v[178:181], v[146:149], v[38:41]
	v_mfma_f32_16x16x32_bf16 v[34:37], v[186:189], v[146:149], v[34:37]
	v_mfma_f32_16x16x32_bf16 v[22:25], v[178:181], v[162:165], v[22:25]
	v_mfma_f32_16x16x32_bf16 v[18:21], v[186:189], v[162:165], v[18:21]
	v_mfma_f32_16x16x32_bf16 v[6:9], v[178:181], v[170:173], v[6:9]
	v_mfma_f32_16x16x32_bf16 v[2:5], v[186:189], v[170:173], v[2:5]
	v_mfma_f32_16x16x32_bf16 v[54:57], v[182:185], v[142:145], v[54:57]
	v_mfma_f32_16x16x32_bf16 v[50:53], v[190:193], v[142:145], v[50:53]
	v_mfma_f32_16x16x32_bf16 v[38:41], v[182:185], v[158:161], v[38:41]
	v_mfma_f32_16x16x32_bf16 v[34:37], v[190:193], v[158:161], v[34:37]
	v_mfma_f32_16x16x32_bf16 v[22:25], v[182:185], v[166:169], v[22:25]
	v_mfma_f32_16x16x32_bf16 v[18:21], v[190:193], v[166:169], v[18:21]
	v_mfma_f32_16x16x32_bf16 v[6:9], v[182:185], v[174:177], v[6:9]
	v_mfma_f32_16x16x32_bf16 v[2:5], v[190:193], v[174:177], v[2:5]
	s_setprio 0
	s_add_i32 s97, s97, 2
	s_add_u32 s12, s12, 0x100
	s_addc_u32 s13, s13, 0
	s_add_u32 s5, s5, 0x100
	s_addc_u32 s11, s11, 0
	s_cmp_gt_u32 s97, 29
	s_cbranch_scc0 .LBB0_301
; __device__ __forceinline__ u32x4 pack8(const f32x4 a, const f32x4 b) { u32x4 w; w.x = cvt_pk_bf16(a[0], a[1]); w.y = cvt_pk_bf16(a[2], a[3]); w.z = cvt_pk_bf16(b[0], b[1]); w.w = cvt_pk_bf16(b[2], b[3]); return w; }
; __device__ __forceinline__ void unpack8(const u32x4 w, f32x4& a, f32x4& b) { a[0] = bf_lo(w.x); a[1] = bf_hi(w.x); a[2] = bf_lo(w.y); a[3] = bf_hi(w.y); b[0] = bf_lo(w.z); b[1] = bf_hi(w.z); b[2] = bf_lo(w.w); b[3] = bf_hi(w.w); }
;     __device__ __forceinline__ void operator()(const AccT& acc, const Unit& u, int wr, int wc, int fr, int fq) const {
;         int row0 = u.pm * 256 + wr * 64 + fr, col0 = u.pn * 256 + wc * 32 + 8 * fq;
;         asm volatile("" : "+v"(row0), "+v"(col0));
;         u32x4 bw[2][4][2];
; #pragma unroll
;         for (int ai = 0; ai < 2; ++ai)
; #pragma unroll
;             for (int m = 0; m < 4; ++m)
; #pragma unroll
;                 for (int bj = 0; bj < 2; ++bj) bw[ai][m][bj] = *(const u32x4*)(Hb + (size_t)(row0 + ai * 128 + m * 16) * 2048 + col0 + bj * 128);
; #pragma unroll
;         for (int ai = 0; ai < 2; ++ai) {
; #pragma unroll
;             for (int m = 0; m < 4; ++m) {
;                 const int row = row0 + ai * 128 + m * 16; const size_t off = (size_t)row * 2048 + col0; float ss = 0.f;
; #pragma unroll
;                 for (int bj = 0; bj < 2; ++bj) {
;                     f32x4 b0, b1; unpack8(bw[ai][m][bj], b0, b1);
;                     const f32x4 o0 = b0 + acc[ai][bj][m][0], o1 = b1 + acc[ai][bj][m][1];
;                     if (outF) { *(f32x4*)(outF + off + bj * 128) = o0; *(f32x4*)(outF + off + bj * 128 + 4) = o1; }
;                     else { *(u32x4*)(Hb + off + bj * 128) = pack8(o0, o1);
;                         ss += (o0[0] * o0[0] + o0[1] * o0[1]) + (o0[2] * o0[2] + o0[3] * o0[3]) + (o1[0] * o1[0] + o1[1] * o1[1]) + (o1[2] * o1[2] + o1[3] * o1[3]); }
;                 }
;                 if (!outF) { ss += __shfl_xor(ss, 16); ss += __shfl_xor(ss, 32); if (fq == 0) atomicAdd(SS + row, ss); }
	v_lshl_add_u32 v236, s10, 8, v1
	v_lshl_or_b32 v206, s96, 8, v252
	s_nop 0
	v_ashrrev_i32_e32 v207, 31, v206
	v_lshlrev_b64 v[238:239], 1, v[206:207]
	v_ashrrev_i32_e32 v237, 31, v236
	v_lshl_add_u64 v[118:119], s[28:29], 0, v[238:239]
	v_lshlrev_b64 v[240:241], 12, v[236:237]
	v_lshl_add_u64 v[114:115], v[118:119], 0, v[240:241]
	global_load_dwordx4 v[190:193], v[114:115], off
	global_load_dwordx4 v[186:189], v[114:115], off offset:256
	v_add_u32_e32 v232, 16, v236
	v_ashrrev_i32_e32 v233, 31, v232
	v_add_u32_e32 v228, 32, v236
	v_lshlrev_b64 v[234:235], 12, v[232:233]
	v_ashrrev_i32_e32 v229, 31, v228
	v_add_u32_e32 v224, 48, v236
	v_lshl_add_u64 v[114:115], v[118:119], 0, v[234:235]
	v_lshlrev_b64 v[230:231], 12, v[228:229]
	v_ashrrev_i32_e32 v225, 31, v224
	v_add_u32_e32 v220, 0x80, v236
	global_load_dwordx4 v[182:185], v[114:115], off
	global_load_dwordx4 v[178:181], v[114:115], off offset:256
	v_lshl_add_u64 v[114:115], v[118:119], 0, v[230:231]
	v_lshlrev_b64 v[226:227], 12, v[224:225]
	v_ashrrev_i32_e32 v221, 31, v220
	v_add_u32_e32 v216, 0x90, v236
	global_load_dwordx4 v[174:177], v[114:115], off
	global_load_dwordx4 v[170:173], v[114:115], off offset:256
	v_lshl_add_u64 v[114:115], v[118:119], 0, v[226:227]
	v_lshlrev_b64 v[222:223], 12, v[220:221]
	v_ashrrev_i32_e32 v217, 31, v216
	v_add_u32_e32 v212, 0xa0, v236
	v_add_u32_e32 v208, 0xb0, v236
	global_load_dwordx4 v[166:169], v[114:115], off
	global_load_dwordx4 v[162:165], v[114:115], off offset:256
	v_lshl_add_u64 v[114:115], v[118:119], 0, v[222:223]
	v_lshlrev_b64 v[218:219], 12, v[216:217]
	v_ashrrev_i32_e32 v213, 31, v212
	v_ashrrev_i32_e32 v209, 31, v208
	global_load_dwordx4 v[158:161], v[114:115], off
	global_load_dwordx4 v[146:149], v[114:115], off offset:256
	v_lshl_add_u64 v[114:115], v[118:119], 0, v[218:219]
	v_lshlrev_b64 v[214:215], 12, v[212:213]
	v_lshlrev_b64 v[210:211], 12, v[208:209]
	global_load_dwordx4 v[142:145], v[114:115], off
	global_load_dwordx4 v[138:141], v[114:115], off offset:256
	v_lshl_add_u64 v[114:115], v[118:119], 0, v[214:215]
	v_lshl_add_u64 v[118:119], v[118:119], 0, v[210:211]
	global_load_dwordx4 v[130:133], v[114:115], off
	s_nop 0
	global_load_dwordx4 v[114:117], v[114:115], off offset:256
	s_nop 0
	global_load_dwordx4 v[134:137], v[118:119], off
	s_nop 0
	global_load_dwordx4 v[118:121], v[118:119], off offset:256
	v_lshl_add_u64 v[240:241], s[28:29], 0, v[240:241]
	v_lshl_add_u64 v[238:239], v[240:241], 0, v[238:239]
	s_waitcnt vmcnt(0)
	v_lshlrev_b32_e32 v244, 16, v190
	v_and_b32_e32 v245, 0xffff0000, v190
	v_lshlrev_b32_e32 v190, 16, v191
	v_and_b32_e32 v191, 0xffff0000, v191
	v_lshlrev_b32_e32 v246, 16, v192
	v_and_b32_e32 v247, 0xffff0000, v192
	v_lshlrev_b32_e32 v192, 16, v193
	v_and_b32_e32 v193, 0xffff0000, v193
	v_pk_add_f32 v[156:157], v[156:157], v[190:191]
	v_pk_add_f32 v[154:155], v[154:155], v[244:245]
	v_pk_add_f32 v[190:191], v[152:153], v[192:193]
	v_pk_add_f32 v[192:193], v[150:151], v[246:247]
	v_cvt_pk_bf16_f32 v150, v154, v155
	v_cvt_pk_bf16_f32 v151, v156, v157
	v_cvt_pk_bf16_f32 v153, v190, v191
	s_nop 0
	v_cvt_pk_bf16_f32 v152, v192, v193
	global_store_dwordx4 v[238:239], v[150:153], off
	s_nop 1
	v_mul_f32_e32 v150, v155, v155
	v_mul_f32_e32 v151, v157, v157
	v_fmac_f32_e32 v150, v154, v154
	v_fmac_f32_e32 v151, v156, v156
	v_add_f32_e32 v150, v150, v151
	v_mul_f32_e32 v151, v193, v193
	v_fmac_f32_e32 v151, v192, v192
	v_add_f32_e32 v150, v151, v150
	v_mul_f32_e32 v151, v191, v191
	v_fmac_f32_e32 v151, v190, v190
	v_add_f32_e32 v190, v151, v150
	v_lshlrev_b32_e32 v150, 16, v186
	v_and_b32_e32 v151, 0xffff0000, v186
	v_lshlrev_b32_e32 v152, 16, v187
	v_and_b32_e32 v153, 0xffff0000, v187
	v_lshlrev_b32_e32 v154, 16, v188
	v_and_b32_e32 v155, 0xffff0000, v188
	v_lshlrev_b32_e32 v156, 16, v189
	v_and_b32_e32 v157, 0xffff0000, v189
	v_pk_add_f32 v[128:129], v[128:129], v[152:153]
	v_pk_add_f32 v[126:127], v[126:127], v[150:151]
	v_pk_add_f32 v[152:153], v[122:123], v[154:155]
	v_cvt_pk_bf16_f32 v122, v126, v127
	v_cvt_pk_bf16_f32 v123, v128, v129
	v_pk_add_f32 v[150:151], v[124:125], v[156:157]
	v_cvt_pk_bf16_f32 v124, v152, v153
	s_nop 0
	v_cvt_pk_bf16_f32 v125, v150, v151
	global_store_dwordx4 v[238:239], v[122:125], off offset:256
	s_nop 1
	v_mul_f32_e32 v122, v127, v127
	v_mul_f32_e32 v123, v129, v129
	v_fmac_f32_e32 v122, v126, v126
	v_fmac_f32_e32 v123, v128, v128
	v_add_f32_e32 v122, v122, v123
	v_mul_f32_e32 v123, v153, v153
	v_fmac_f32_e32 v123, v152, v152
	v_add_f32_e32 v122, v123, v122
	v_mul_f32_e32 v123, v151, v151
	v_fmac_f32_e32 v123, v150, v150
	v_add_f32_e32 v122, v123, v122
	v_and_b32_e32 v124, 64, v248
	v_add_f32_e32 v123, v190, v122
	v_xor_b32_e32 v122, 16, v248
	v_add_u32_e32 v125, 64, v124
	v_cmp_lt_i32_e32 vcc, v122, v125
	s_nop 1
	v_cndmask_b32_e32 v122, v248, v122, vcc
	v_lshlrev_b32_e32 v122, 2, v122
	ds_bpermute_b32 v124, v122, v123
	s_waitcnt lgkmcnt(0)
	v_add_f32_e32 v124, v123, v124
	v_xor_b32_e32 v123, 32, v248
	v_cmp_lt_i32_e32 vcc, v123, v125
	s_nop 1
	v_cndmask_b32_e32 v123, v248, v123, vcc
	v_lshlrev_b32_e32 v123, 2, v123
	ds_bpermute_b32 v125, v123, v124
	s_and_saveexec_b64 s[10:11], s[0:1]
	s_cbranch_execz .LBB0_304
	v_readlane_b32 s12, v254, 42
	v_readlane_b32 s13, v254, 43
	s_waitcnt lgkmcnt(0)
	v_add_f32_e32 v124, v124, v125
	v_lshl_add_u64 v[126:127], v[236:237], 2, s[12:13]
	global_atomic_add_f32 v[126:127], v124, off

; #define PG8_STAGE(bufoff, gbase, voff) do { _Pragma("unroll") for (int _i = 0; _i < 2; ++_i) \
;         __builtin_amdgcn_global_load_lds((const unsigned*)((const char*)(gbase) + (voff)[_i]), (LAS unsigned*)(lds + (bufoff) + ldsw + _i * 8192), 16, 0, 0); } while (0)
; #define PG8_LDA(dst, b, h) do { _Pragma("unroll") for (int m = 0; m < 4; ++m) _Pragma("unroll") for (int k = 0; k < 2; ++k) dst[m][k] = *(const LAS bf16x8*)(lds + PG8_SA(b, h) + aoff + m * 2048 + k * 1024); } while (0)
; #define PG8_LDB(dst, b, h) do { _Pragma("unroll") for (int n = 0; n < 2; ++n) _Pragma("unroll") for (int k = 0; k < 2; ++k) dst[n][k] = *(const LAS bf16x8*)(lds + PG8_SB(b, h) + boff + n * 2048 + k * 1024); } while (0)
; #define PG8_MMA(ai, bj, At, Bt) do { __builtin_amdgcn_s_setprio(1); _Pragma("unroll") for (int m = 0; m < 4; ++m) _Pragma("unroll") for (int n = 0; n < 2; ++n) _Pragma("unroll") for (int k = 0; k < 2; ++k) \
;         acc[ai][bj][m][n] = __builtin_amdgcn_mfma_f32_16x16x32_bf16(Bt[n][k], At[m][k], acc[ai][bj][m][n], 0, 0, 0); __builtin_amdgcn_s_setprio(0); } while (0)
; #define PG8_WAIT_V(n) asm volatile("s_waitcnt vmcnt(" #n ")" ::: "memory")
; #define PG8_BAR __builtin_amdgcn_s_barrier()
; template <class Epi, class Sched>
; __device__ __forceinline__ void gemm_phase(LAS unsigned char* lds_in, const int lda, const int ldb, const Sched& S, const Epi& E, const int WID) {
;     ...
;         for (int t = tb; t < te; t += 2) {
;             const bool last = (t == nt - 2);
;             const char* a1 = cA + (size_t)(t + 1) * kstep;
;             const char* a2 = last ? nA : cA + (size_t)(t + 2) * kstep; const char* b2 = last ? nB : cB + (size_t)(t + 2) * kstep;
;             const char* a3 = a2 + kstep; const char* b3 = b2 + kstep;
;             PG8_LDB(B0, 0, 0); PG8_SCHED; PG8_LDA(At, 0, 0); PG8_STAGE(PG8_SA(1, 1), a1 + hstepA, voffA);
;             PG8_WAIT_L(8); PG8_BAR; PG8_WAIT_L(0); PG8_MMA(0, 0, At, B0); PG8_BAR; PG8_SCHED;
;             PG8_LDB(B1, 0, 1); PG8_STAGE(PG8_SB(0, 0), b2, voffB);
;             PG8_BAR; PG8_WAIT_L(0); PG8_MMA(0, 1, At, B1); PG8_BAR;
;             PG8_LDA(At, 0, 1); PG8_STAGE(PG8_SA(0, 0), a2, voffA);
;             PG8_BAR; PG8_WAIT_L(0); PG8_MMA(1, 0, At, B0); PG8_BAR; PG8_SCHED;
;             PG8_STAGE(PG8_SB(0, 1), b2 + hstepB, voffB);
;             PG8_WAIT_V(6); PG8_BAR; PG8_MMA(1, 1, At, B1); PG8_BAR;
.LBB0_344:
	s_barrier
	v_add_u32_e32 v1, s23, v211
	ds_read_b128 v[134:137], v1
	ds_read_b128 v[138:141], v1 offset:1024
	ds_read_b128 v[142:145], v1 offset:2048
	ds_read_b128 v[146:149], v1 offset:3072
	s_add_i32 vcc_lo, vcc_lo, 2
	s_add_u32 s16, s14, s70
	s_addc_u32 s17, s15, 0
	s_add_u32 s66, s12, s70
	s_addc_u32 s67, s13, 0
	s_cmp_eq_u32 s70, s10
	s_cselect_b32 s19, s3, s17
	s_cselect_b32 s18, s2, s16
	s_cselect_b32 s17, s5, s67
	s_cselect_b32 s16, s4, s66
	v_lshl_add_u64 v[178:179], v[132:133], 0, s[70:71]
	s_add_i32 m0, s47, 0xc000
	ds_read_b128 v[150:153], v213
	ds_read_b128 v[154:157], v213 offset:1024
	ds_read_b128 v[158:161], v213 offset:2048
	ds_read_b128 v[162:165], v213 offset:3072
	ds_read_b128 v[166:169], v213 offset:4096
	ds_read_b128 v[170:173], v213 offset:5120
	ds_read_b128 v[174:177], v213 offset:6144
	ds_read_b128 v[200:203], v213 offset:7168
	global_load_lds_dwordx4 v[178:179], off
	v_lshl_add_u64 v[178:179], v[2:3], 0, s[70:71]
	s_add_i32 m0, s47, 0xe000
	s_nop 0
	global_load_lds_dwordx4 v[178:179], off
	s_waitcnt lgkmcnt(8)
	s_barrier
	s_waitcnt lgkmcnt(0)
	s_setprio 1
	s_waitcnt lgkmcnt(0)
	v_mfma_f32_16x16x32_bf16 v[128:131], v[134:137], v[150:153], v[128:131]
	v_mfma_f32_16x16x32_bf16 v[124:127], v[142:145], v[150:153], v[124:127]
	v_mfma_f32_16x16x32_bf16 v[112:115], v[134:137], v[158:161], v[112:115]
	v_mfma_f32_16x16x32_bf16 v[108:111], v[142:145], v[158:161], v[108:111]
	v_mfma_f32_16x16x32_bf16 v[96:99], v[134:137], v[166:169], v[96:99]
	v_mfma_f32_16x16x32_bf16 v[92:95], v[142:145], v[166:169], v[92:95]
	v_mfma_f32_16x16x32_bf16 v[80:83], v[134:137], v[174:177], v[80:83]
	v_mfma_f32_16x16x32_bf16 v[76:79], v[142:145], v[174:177], v[76:79]
	v_mfma_f32_16x16x32_bf16 v[128:131], v[138:141], v[154:157], v[128:131]
	v_mfma_f32_16x16x32_bf16 v[124:127], v[146:149], v[154:157], v[124:127]
	v_mfma_f32_16x16x32_bf16 v[112:115], v[138:141], v[162:165], v[112:115]
	v_mfma_f32_16x16x32_bf16 v[108:111], v[146:149], v[162:165], v[108:111]
	v_mfma_f32_16x16x32_bf16 v[96:99], v[138:141], v[170:173], v[96:99]
	v_mfma_f32_16x16x32_bf16 v[92:95], v[146:149], v[170:173], v[92:95]
	v_mfma_f32_16x16x32_bf16 v[80:83], v[138:141], v[200:203], v[80:83]
	v_mfma_f32_16x16x32_bf16 v[76:79], v[146:149], v[200:203], v[76:79]
	s_setprio 0
	s_barrier
	s_mov_b32 m0, s35
	v_add_u32_e32 v1, s50, v211
	ds_read_b128 v[204:207], v1
	ds_read_b128 v[214:217], v1 offset:1024
	ds_read_b128 v[218:221], v1 offset:2048
	ds_read_b128 v[222:225], v1 offset:3072
	global_load_lds_dwordx4 v186, s[16:17]
	s_mov_b32 m0, s46
	s_nop 0
	global_load_lds_dwordx4 v190, s[16:17]
	s_barrier
	s_waitcnt lgkmcnt(0)
	s_setprio 1
	s_waitcnt lgkmcnt(0)
	v_mfma_f32_16x16x32_bf16 v[120:123], v[204:207], v[150:153], v[120:123]
	v_mfma_f32_16x16x32_bf16 v[116:119], v[218:221], v[150:153], v[116:119]
	v_mfma_f32_16x16x32_bf16 v[104:107], v[204:207], v[158:161], v[104:107]
	v_mfma_f32_16x16x32_bf16 v[100:103], v[218:221], v[158:161], v[100:103]
	v_mfma_f32_16x16x32_bf16 v[88:91], v[204:207], v[166:169], v[88:91]
	v_mfma_f32_16x16x32_bf16 v[84:87], v[218:221], v[166:169], v[84:87]
	v_mfma_f32_16x16x32_bf16 v[72:75], v[204:207], v[174:177], v[72:75]
	v_mfma_f32_16x16x32_bf16 v[68:71], v[218:221], v[174:177], v[68:71]
	v_mfma_f32_16x16x32_bf16 v[120:123], v[214:217], v[154:157], v[120:123]
	v_mfma_f32_16x16x32_bf16 v[116:119], v[222:225], v[154:157], v[116:119]
	v_mfma_f32_16x16x32_bf16 v[104:107], v[214:217], v[162:165], v[104:107]
	v_mfma_f32_16x16x32_bf16 v[100:103], v[222:225], v[162:165], v[100:103]
	v_mfma_f32_16x16x32_bf16 v[88:91], v[214:217], v[170:173], v[88:91]
	v_mfma_f32_16x16x32_bf16 v[84:87], v[222:225], v[170:173], v[84:87]
	v_mfma_f32_16x16x32_bf16 v[72:75], v[214:217], v[200:203], v[72:75]
	v_mfma_f32_16x16x32_bf16 v[68:71], v[222:225], v[200:203], v[68:71]
	s_setprio 0
	s_mov_b32 m0, s47
	s_barrier
	ds_read_b128 v[150:153], v213 offset:16384
	ds_read_b128 v[154:157], v213 offset:17408
	ds_read_b128 v[158:161], v213 offset:18432
	ds_read_b128 v[162:165], v213 offset:19456
	ds_read_b128 v[166:169], v213 offset:20480
	ds_read_b128 v[170:173], v213 offset:21504
	ds_read_b128 v[174:177], v213 offset:22528
	ds_read_b128 v[200:203], v213 offset:23552
	global_load_lds_dwordx4 v184, s[18:19]
	s_mov_b32 m0, s49
	s_nop 0
	global_load_lds_dwordx4 v188, s[18:19]
	s_barrier
	s_waitcnt lgkmcnt(0)
	s_setprio 1
	s_waitcnt lgkmcnt(0)
	v_mfma_f32_16x16x32_bf16 v[64:67], v[134:137], v[150:153], v[64:67]
	v_mfma_f32_16x16x32_bf16 v[60:63], v[142:145], v[150:153], v[60:63]
	v_mfma_f32_16x16x32_bf16 v[48:51], v[134:137], v[158:161], v[48:51]
	v_mfma_f32_16x16x32_bf16 v[44:47], v[142:145], v[158:161], v[44:47]
	v_mfma_f32_16x16x32_bf16 v[32:35], v[134:137], v[166:169], v[32:35]
	v_mfma_f32_16x16x32_bf16 v[28:31], v[142:145], v[166:169], v[28:31]
	v_mfma_f32_16x16x32_bf16 v[16:19], v[134:137], v[174:177], v[16:19]
	v_mfma_f32_16x16x32_bf16 v[12:15], v[142:145], v[174:177], v[12:15]
	v_mfma_f32_16x16x32_bf16 v[64:67], v[138:141], v[154:157], v[64:67]
	v_mfma_f32_16x16x32_bf16 v[60:63], v[146:149], v[154:157], v[60:63]
	v_mfma_f32_16x16x32_bf16 v[48:51], v[138:141], v[162:165], v[48:51]
	v_mfma_f32_16x16x32_bf16 v[44:47], v[146:149], v[162:165], v[44:47]
	v_mfma_f32_16x16x32_bf16 v[32:35], v[138:141], v[170:173], v[32:35]
	v_mfma_f32_16x16x32_bf16 v[28:31], v[146:149], v[170:173], v[28:31]
	v_mfma_f32_16x16x32_bf16 v[16:19], v[138:141], v[200:203], v[16:19]
	v_mfma_f32_16x16x32_bf16 v[12:15], v[146:149], v[200:203], v[12:15]
	s_setprio 0
	s_barrier
	s_add_u32 s66, s16, 0xa0000
	s_addc_u32 s67, s17, 0
	s_mov_b32 m0, s51
	s_nop 0
	global_load_lds_dwordx4 v186, s[66:67]
	s_mov_b32 m0, s65
	s_nop 0
	global_load_lds_dwordx4 v190, s[66:67]
	s_waitcnt vmcnt(6)
	s_barrier
; #define PG8_STAGE(bufoff, gbase, voff) do { _Pragma("unroll") for (int _i = 0; _i < 2; ++_i) \
;         __builtin_amdgcn_global_load_lds((const unsigned*)((const char*)(gbase) + (voff)[_i]), (LAS unsigned*)(lds + (bufoff) + ldsw + _i * 8192), 16, 0, 0); } while (0)
; #define PG8_LDA(dst, b, h) do { _Pragma("unroll") for (int m = 0; m < 4; ++m) _Pragma("unroll") for (int k = 0; k < 2; ++k) dst[m][k] = *(const LAS bf16x8*)(lds + PG8_SA(b, h) + aoff + m * 2048 + k * 1024); } while (0)
; #define PG8_LDB(dst, b, h) do { _Pragma("unroll") for (int n = 0; n < 2; ++n) _Pragma("unroll") for (int k = 0; k < 2; ++k) dst[n][k] = *(const LAS bf16x8*)(lds + PG8_SB(b, h) + boff + n * 2048 + k * 1024); } while (0)
; #define PG8_MMA(ai, bj, At, Bt) do { __builtin_amdgcn_s_setprio(1); _Pragma("unroll") for (int m = 0; m < 4; ++m) _Pragma("unroll") for (int n = 0; n < 2; ++n) _Pragma("unroll") for (int k = 0; k < 2; ++k) \
;         acc[ai][bj][m][n] = __builtin_amdgcn_mfma_f32_16x16x32_bf16(Bt[n][k], At[m][k], acc[ai][bj][m][n], 0, 0, 0); __builtin_amdgcn_s_setprio(0); } while (0)
; #define PG8_WAIT_V(n) asm volatile("s_waitcnt vmcnt(" #n ")" ::: "memory")
; #define PG8_WAIT_L(n) asm volatile("s_waitcnt lgkmcnt(" #n ")" ::: "memory")
; #define PG8_BAR __builtin_amdgcn_s_barrier()
; #define PG8_SCHED __builtin_amdgcn_sched_barrier(0)
; template <class Epi, class Sched>
; __device__ __forceinline__ void gemm_phase(LAS unsigned char* lds_in, const int lda, const int ldb, const Sched& S, const Epi& E, const int WID) {
;     ...
;             PG8_WAIT_V(6); PG8_BAR; PG8_MMA(1, 1, At, B1); PG8_BAR;
;             PG8_LDB(B0, 1, 0); PG8_SCHED; PG8_LDA(At, 1, 0); PG8_STAGE(PG8_SA(0, 1), a2 + hstepA, voffA);
;             PG8_WAIT_L(8); PG8_BAR; PG8_WAIT_L(0); PG8_MMA(0, 0, At, B0); PG8_BAR; PG8_SCHED;
;             PG8_LDB(B1, 1, 1); PG8_STAGE(PG8_SB(1, 0), b3, voffB);
;             PG8_BAR; PG8_WAIT_L(0); PG8_MMA(0, 1, At, B1); PG8_BAR;
	s_setprio 1
	v_mfma_f32_16x16x32_bf16 v[56:59], v[204:207], v[150:153], v[56:59]
	v_mfma_f32_16x16x32_bf16 v[52:55], v[218:221], v[150:153], v[52:55]
	v_mfma_f32_16x16x32_bf16 v[40:43], v[204:207], v[158:161], v[40:43]
	v_mfma_f32_16x16x32_bf16 v[36:39], v[218:221], v[158:161], v[36:39]
	v_mfma_f32_16x16x32_bf16 v[24:27], v[204:207], v[166:169], v[24:27]
	v_mfma_f32_16x16x32_bf16 v[20:23], v[218:221], v[166:169], v[20:23]
	v_mfma_f32_16x16x32_bf16 v[8:11], v[204:207], v[174:177], v[8:11]
	v_mfma_f32_16x16x32_bf16 v[4:7], v[218:221], v[174:177], v[4:7]
	v_mfma_f32_16x16x32_bf16 v[56:59], v[214:217], v[154:157], v[56:59]
	v_mfma_f32_16x16x32_bf16 v[52:55], v[222:225], v[154:157], v[52:55]
	v_mfma_f32_16x16x32_bf16 v[40:43], v[214:217], v[162:165], v[40:43]
	v_mfma_f32_16x16x32_bf16 v[36:39], v[222:225], v[162:165], v[36:39]
	v_mfma_f32_16x16x32_bf16 v[24:27], v[214:217], v[170:173], v[24:27]
	v_mfma_f32_16x16x32_bf16 v[20:23], v[222:225], v[170:173], v[20:23]
	v_mfma_f32_16x16x32_bf16 v[8:11], v[214:217], v[200:203], v[8:11]
	v_mfma_f32_16x16x32_bf16 v[4:7], v[222:225], v[200:203], v[4:7]
	s_setprio 0
	v_add_u32_e32 v1, s90, v211
	s_barrier
	ds_read_b128 v[134:137], v1
	ds_read_b128 v[138:141], v1 offset:1024
	ds_read_b128 v[142:145], v1 offset:2048
	ds_read_b128 v[146:149], v1 offset:3072
	s_add_u32 s18, s18, 0xa0000
	s_addc_u32 s19, s19, 0
	s_mov_b32 m0, s78
	ds_read_b128 v[150:153], v213 offset:32768
	ds_read_b128 v[154:157], v213 offset:33792
	ds_read_b128 v[158:161], v213 offset:34816
	ds_read_b128 v[162:165], v213 offset:35840
	ds_read_b128 v[166:169], v213 offset:36864
	ds_read_b128 v[170:173], v213 offset:37888
	ds_read_b128 v[174:177], v213 offset:38912
	ds_read_b128 v[200:203], v213 offset:39936
	global_load_lds_dwordx4 v184, s[18:19]
	s_mov_b32 m0, s79
	s_nop 0
	global_load_lds_dwordx4 v188, s[18:19]
	s_waitcnt lgkmcnt(8)
	s_barrier
	s_waitcnt lgkmcnt(0)
	s_setprio 1
	s_waitcnt lgkmcnt(0)
	v_mfma_f32_16x16x32_bf16 v[128:131], v[134:137], v[150:153], v[128:131]
	v_mfma_f32_16x16x32_bf16 v[124:127], v[142:145], v[150:153], v[124:127]
	v_mfma_f32_16x16x32_bf16 v[112:115], v[134:137], v[158:161], v[112:115]
	v_mfma_f32_16x16x32_bf16 v[108:111], v[142:145], v[158:161], v[108:111]
	v_mfma_f32_16x16x32_bf16 v[96:99], v[134:137], v[166:169], v[96:99]
	v_mfma_f32_16x16x32_bf16 v[92:95], v[142:145], v[166:169], v[92:95]
	v_mfma_f32_16x16x32_bf16 v[80:83], v[134:137], v[174:177], v[80:83]
	v_mfma_f32_16x16x32_bf16 v[76:79], v[142:145], v[174:177], v[76:79]
	v_mfma_f32_16x16x32_bf16 v[128:131], v[138:141], v[154:157], v[128:131]
	v_mfma_f32_16x16x32_bf16 v[124:127], v[146:149], v[154:157], v[124:127]
	v_mfma_f32_16x16x32_bf16 v[112:115], v[138:141], v[162:165], v[112:115]
	v_mfma_f32_16x16x32_bf16 v[108:111], v[146:149], v[162:165], v[108:111]
	v_mfma_f32_16x16x32_bf16 v[96:99], v[138:141], v[170:173], v[96:99]
	v_mfma_f32_16x16x32_bf16 v[92:95], v[146:149], v[170:173], v[92:95]
	v_mfma_f32_16x16x32_bf16 v[80:83], v[138:141], v[200:203], v[80:83]
	v_mfma_f32_16x16x32_bf16 v[76:79], v[146:149], v[200:203], v[76:79]
	s_setprio 0
	s_barrier
	s_mov_b32 m0, s91
	v_add_u32_e32 v1, s21, v211
	s_add_u32 s100, s16, 0x80
	s_addc_u32 s101, s17, 0
	ds_read_b128 v[204:207], v1
	ds_read_b128 v[214:217], v1 offset:1024
	ds_read_b128 v[218:221], v1 offset:2048
	ds_read_b128 v[222:225], v1 offset:3072
	global_load_lds_dwordx4 v186, s[100:101]
	s_add_u32 s100, s16, 0x80
	s_addc_u32 s101, s17, 0
	s_mov_b32 m0, s92
	s_nop 0
	global_load_lds_dwordx4 v190, s[100:101]
	s_barrier
; #define PG8_STAGE(bufoff, gbase, voff) do { _Pragma("unroll") for (int _i = 0; _i < 2; ++_i) \
;         __builtin_amdgcn_global_load_lds((const unsigned*)((const char*)(gbase) + (voff)[_i]), (LAS unsigned*)(lds + (bufoff) + ldsw + _i * 8192), 16, 0, 0); } while (0)
; #define PG8_LDA(dst, b, h) do { _Pragma("unroll") for (int m = 0; m < 4; ++m) _Pragma("unroll") for (int k = 0; k < 2; ++k) dst[m][k] = *(const LAS bf16x8*)(lds + PG8_SA(b, h) + aoff + m * 2048 + k * 1024); } while (0)
; #define PG8_MMA(ai, bj, At, Bt) do { __builtin_amdgcn_s_setprio(1); _Pragma("unroll") for (int m = 0; m < 4; ++m) _Pragma("unroll") for (int n = 0; n < 2; ++n) _Pragma("unroll") for (int k = 0; k < 2; ++k) \
;         acc[ai][bj][m][n] = __builtin_amdgcn_mfma_f32_16x16x32_bf16(Bt[n][k], At[m][k], acc[ai][bj][m][n], 0, 0, 0); __builtin_amdgcn_s_setprio(0); } while (0)
; #define PG8_WAIT_V(n) asm volatile("s_waitcnt vmcnt(" #n ")" ::: "memory")
; #define PG8_WAIT_L(n) asm volatile("s_waitcnt lgkmcnt(" #n ")" ::: "memory")
; #define PG8_BAR __builtin_amdgcn_s_barrier()
; #define PG8_SCHED __builtin_amdgcn_sched_barrier(0)
; template <class Epi, class Sched>
; __device__ __forceinline__ void gemm_phase(LAS unsigned char* lds_in, const int lda, const int ldb, const Sched& S, const Epi& E, const int WID) {
;     ...
;             PG8_BAR; PG8_WAIT_L(0); PG8_MMA(0, 1, At, B1); PG8_BAR;
;             PG8_LDA(At, 1, 1); PG8_STAGE(PG8_SA(1, 0), a3, voffA);
;             PG8_BAR; PG8_WAIT_L(0); PG8_MMA(1, 0, At, B0); PG8_BAR; PG8_SCHED;
;             PG8_STAGE(PG8_SB(1, 1), b3 + hstepB, voffB);
;             PG8_WAIT_V(6); PG8_BAR; PG8_MMA(1, 1, At, B1); PG8_BAR;
;         }
	s_waitcnt lgkmcnt(0)
	s_setprio 1
	s_waitcnt lgkmcnt(0)
	v_mfma_f32_16x16x32_bf16 v[120:123], v[204:207], v[150:153], v[120:123]
	v_mfma_f32_16x16x32_bf16 v[116:119], v[218:221], v[150:153], v[116:119]
	v_mfma_f32_16x16x32_bf16 v[104:107], v[204:207], v[158:161], v[104:107]
	v_mfma_f32_16x16x32_bf16 v[100:103], v[218:221], v[158:161], v[100:103]
	v_mfma_f32_16x16x32_bf16 v[88:91], v[204:207], v[166:169], v[88:91]
	v_mfma_f32_16x16x32_bf16 v[84:87], v[218:221], v[166:169], v[84:87]
	v_mfma_f32_16x16x32_bf16 v[72:75], v[204:207], v[174:177], v[72:75]
	v_mfma_f32_16x16x32_bf16 v[68:71], v[218:221], v[174:177], v[68:71]
	v_mfma_f32_16x16x32_bf16 v[120:123], v[214:217], v[154:157], v[120:123]
	v_mfma_f32_16x16x32_bf16 v[116:119], v[222:225], v[154:157], v[116:119]
	v_mfma_f32_16x16x32_bf16 v[104:107], v[214:217], v[162:165], v[104:107]
	v_mfma_f32_16x16x32_bf16 v[100:103], v[222:225], v[162:165], v[100:103]
	v_mfma_f32_16x16x32_bf16 v[88:91], v[214:217], v[170:173], v[88:91]
	v_mfma_f32_16x16x32_bf16 v[84:87], v[222:225], v[170:173], v[84:87]
	v_mfma_f32_16x16x32_bf16 v[72:75], v[214:217], v[200:203], v[72:75]
	v_mfma_f32_16x16x32_bf16 v[68:71], v[222:225], v[200:203], v[68:71]
	s_setprio 0
	s_mov_b32 m0, s93
	s_add_u32 s100, s18, 0xfff60080
	s_addc_u32 s101, s19, -1
	s_barrier
	ds_read_b128 v[150:153], v213 offset:49152
	ds_read_b128 v[154:157], v213 offset:50176
	ds_read_b128 v[158:161], v213 offset:51200
	ds_read_b128 v[162:165], v213 offset:52224
	ds_read_b128 v[166:169], v213 offset:53248
	ds_read_b128 v[170:173], v213 offset:54272
	ds_read_b128 v[174:177], v213 offset:55296
	ds_read_b128 v[200:203], v213 offset:56320
	global_load_lds_dwordx4 v184, s[100:101]
	s_add_u32 s100, s18, 0xfff60080
	s_addc_u32 s101, s19, -1
	s_mov_b32 m0, s20
	s_nop 0
	global_load_lds_dwordx4 v188, s[100:101]
	s_barrier
	s_waitcnt lgkmcnt(0)
	s_setprio 1
	s_waitcnt lgkmcnt(0)
	v_mfma_f32_16x16x32_bf16 v[64:67], v[134:137], v[150:153], v[64:67]
	v_mfma_f32_16x16x32_bf16 v[60:63], v[142:145], v[150:153], v[60:63]
	v_mfma_f32_16x16x32_bf16 v[48:51], v[134:137], v[158:161], v[48:51]
	v_mfma_f32_16x16x32_bf16 v[44:47], v[142:145], v[158:161], v[44:47]
	v_mfma_f32_16x16x32_bf16 v[32:35], v[134:137], v[166:169], v[32:35]
	v_mfma_f32_16x16x32_bf16 v[28:31], v[142:145], v[166:169], v[28:31]
	v_mfma_f32_16x16x32_bf16 v[16:19], v[134:137], v[174:177], v[16:19]
	v_mfma_f32_16x16x32_bf16 v[12:15], v[142:145], v[174:177], v[12:15]
	v_mfma_f32_16x16x32_bf16 v[64:67], v[138:141], v[154:157], v[64:67]
	v_mfma_f32_16x16x32_bf16 v[60:63], v[146:149], v[154:157], v[60:63]
	v_mfma_f32_16x16x32_bf16 v[48:51], v[138:141], v[162:165], v[48:51]
	v_mfma_f32_16x16x32_bf16 v[44:47], v[146:149], v[162:165], v[44:47]
	v_mfma_f32_16x16x32_bf16 v[32:35], v[138:141], v[170:173], v[32:35]
	v_mfma_f32_16x16x32_bf16 v[28:31], v[146:149], v[170:173], v[28:31]
	v_mfma_f32_16x16x32_bf16 v[16:19], v[138:141], v[200:203], v[16:19]
	v_mfma_f32_16x16x32_bf16 v[12:15], v[146:149], v[200:203], v[12:15]
	s_setprio 0
	s_barrier
	s_add_u32 s16, s16, 0xa0080
	s_addc_u32 s17, s17, 0
	s_mov_b32 m0, s48
	s_nop 0
	global_load_lds_dwordx4 v186, s[16:17]
	s_mov_b32 m0, s22
	s_nop 0
	global_load_lds_dwordx4 v190, s[16:17]
	s_waitcnt vmcnt(6)
	s_barrier
	s_setprio 1
	v_mfma_f32_16x16x32_bf16 v[56:59], v[204:207], v[150:153], v[56:59]
	v_mfma_f32_16x16x32_bf16 v[52:55], v[218:221], v[150:153], v[52:55]
	v_mfma_f32_16x16x32_bf16 v[40:43], v[204:207], v[158:161], v[40:43]
	v_mfma_f32_16x16x32_bf16 v[36:39], v[218:221], v[158:161], v[36:39]
	v_mfma_f32_16x16x32_bf16 v[24:27], v[204:207], v[166:169], v[24:27]
	v_mfma_f32_16x16x32_bf16 v[20:23], v[218:221], v[166:169], v[20:23]
	v_mfma_f32_16x16x32_bf16 v[8:11], v[204:207], v[174:177], v[8:11]
	v_mfma_f32_16x16x32_bf16 v[4:7], v[218:221], v[174:177], v[4:7]
	v_mfma_f32_16x16x32_bf16 v[56:59], v[214:217], v[154:157], v[56:59]
	v_mfma_f32_16x16x32_bf16 v[52:55], v[222:225], v[154:157], v[52:55]
	v_mfma_f32_16x16x32_bf16 v[40:43], v[214:217], v[162:165], v[40:43]
	v_mfma_f32_16x16x32_bf16 v[36:39], v[222:225], v[162:165], v[36:39]
	v_mfma_f32_16x16x32_bf16 v[24:27], v[214:217], v[170:173], v[24:27]
	v_mfma_f32_16x16x32_bf16 v[20:23], v[222:225], v[170:173], v[20:23]
	v_mfma_f32_16x16x32_bf16 v[8:11], v[214:217], v[200:203], v[8:11]
	v_mfma_f32_16x16x32_bf16 v[4:7], v[222:225], v[200:203], v[4:7]
	s_setprio 0
	s_add_u32 s14, s14, 0x100
	s_addc_u32 s15, s15, 0
	s_add_u32 s12, s12, 0x100
	s_addc_u32 s13, s13, 0
	s_add_u32 s10, s10, 0xffffff00
	s_addc_u32 s11, s11, -1
	v_lshl_add_u64 v[132:133], v[132:133], 0, s[74:75]
	s_cmp_ge_u32 vcc_lo, vcc_hi
	v_lshl_add_u64 v[2:3], v[2:3], 0, s[74:75]
	s_cbranch_scc0 .LBB0_344
	s_branch .LBB0_339

; #define PG8_STAGE(bufoff, gbase, voff) do { _Pragma("unroll") for (int _i = 0; _i < 2; ++_i) \
;         __builtin_amdgcn_global_load_lds((const unsigned*)((const char*)(gbase) + (voff)[_i]), (LAS unsigned*)(lds + (bufoff) + ldsw + _i * 8192), 16, 0, 0); } while (0)
; #define PG8_LDA(dst, b, h) do { _Pragma("unroll") for (int m = 0; m < 4; ++m) _Pragma("unroll") for (int k = 0; k < 2; ++k) dst[m][k] = *(const LAS bf16x8*)(lds + PG8_SA(b, h) + aoff + m * 2048 + k * 1024); } while (0)
; #define PG8_LDB(dst, b, h) do { _Pragma("unroll") for (int n = 0; n < 2; ++n) _Pragma("unroll") for (int k = 0; k < 2; ++k) dst[n][k] = *(const LAS bf16x8*)(lds + PG8_SB(b, h) + boff + n * 2048 + k * 1024); } while (0)
; #define PG8_MMA(ai, bj, At, Bt) do { __builtin_amdgcn_s_setprio(1); _Pragma("unroll") for (int m = 0; m < 4; ++m) _Pragma("unroll") for (int n = 0; n < 2; ++n) _Pragma("unroll") for (int k = 0; k < 2; ++k) \
;         acc[ai][bj][m][n] = __builtin_amdgcn_mfma_f32_16x16x32_bf16(Bt[n][k], At[m][k], acc[ai][bj][m][n], 0, 0, 0); __builtin_amdgcn_s_setprio(0); } while (0)
; #define PG8_WAIT_L(n) asm volatile("s_waitcnt lgkmcnt(" #n ")" ::: "memory")
; #define PG8_BAR __builtin_amdgcn_s_barrier()
; #define PG8_SCHED __builtin_amdgcn_sched_barrier(0)
; template <class Epi, class Sched>
; __device__ __forceinline__ void gemm_phase(LAS unsigned char* lds_in, const int lda, const int ldb, const Sched& S, const Epi& E, const int WID) {
;     ...
;             PG8_LDB(B0, 0, 0); PG8_SCHED; PG8_LDA(At, 0, 0); PG8_STAGE(PG8_SA(1, 1), a1 + hstepA, voffA);
;             PG8_WAIT_L(8); PG8_BAR; PG8_WAIT_L(0); PG8_MMA(0, 0, At, B0); PG8_BAR; PG8_SCHED;
;     ...
; #pragma unroll
;         for (int a = 0; a < 2; ++a)
; #pragma unroll
;             for (int b = 0; b < 2; ++b)
; #pragma unroll
;                 for (int m = 0; m < 4; ++m)
; #pragma unroll
;                     for (int n = 0; n < 2; ++n) acc[a][b][m][n] = (f32x4){0.f, 0.f, 0.f, 0.f};
.LBB0_921:
	s_add_u32 s14, s14, 0x80080
	s_addc_u32 s15, s15, 0
	s_add_u32 s7, s16, 0x100
	v_mov_b32_e32 v2, 0
	s_addc_u32 s13, s17, 0
	s_mov_b32 vcc_lo, -2
	v_mov_b32_e32 v3, v2
	v_mov_b32_e32 v4, v2
	v_mov_b32_e32 v5, v2
	v_mov_b32_e32 v6, v2
	v_mov_b32_e32 v7, v2
	v_mov_b32_e32 v8, v2
	v_mov_b32_e32 v9, v2
	v_mov_b32_e32 v10, v2
	v_mov_b32_e32 v11, v2
	v_mov_b32_e32 v12, v2
	v_mov_b32_e32 v13, v2
	v_mov_b32_e32 v14, v2
	v_mov_b32_e32 v15, v2
	v_mov_b32_e32 v16, v2
	v_mov_b32_e32 v17, v2
	v_mov_b32_e32 v18, v2
	v_mov_b32_e32 v19, v2
	v_mov_b32_e32 v20, v2
	v_mov_b32_e32 v21, v2
	v_mov_b32_e32 v22, v2
	v_mov_b32_e32 v23, v2
	v_mov_b32_e32 v24, v2
	v_mov_b32_e32 v25, v2
	v_mov_b32_e32 v26, v2
	v_mov_b32_e32 v27, v2
	v_mov_b32_e32 v28, v2
	v_mov_b32_e32 v29, v2
	v_mov_b32_e32 v30, v2
	v_mov_b32_e32 v31, v2
	v_mov_b32_e32 v32, v2
	v_mov_b32_e32 v33, v2
	v_mov_b32_e32 v58, v2
	v_mov_b32_e32 v59, v2
	v_mov_b32_e32 v60, v2
	v_mov_b32_e32 v61, v2
	v_mov_b32_e32 v66, v2
	v_mov_b32_e32 v67, v2
	v_mov_b32_e32 v68, v2
	v_mov_b32_e32 v69, v2
	v_mov_b32_e32 v74, v2
	v_mov_b32_e32 v75, v2
	v_mov_b32_e32 v76, v2
	v_mov_b32_e32 v77, v2
	v_mov_b32_e32 v78, v2
	v_mov_b32_e32 v79, v2
	v_mov_b32_e32 v80, v2
	v_mov_b32_e32 v81, v2
	v_mov_b32_e32 v82, v2
	v_mov_b32_e32 v83, v2
	v_mov_b32_e32 v84, v2
	v_mov_b32_e32 v85, v2
	v_mov_b32_e32 v86, v2
	v_mov_b32_e32 v87, v2
	v_mov_b32_e32 v88, v2
	v_mov_b32_e32 v89, v2
	v_mov_b32_e32 v90, v2
	v_mov_b32_e32 v91, v2
	v_mov_b32_e32 v92, v2
	v_mov_b32_e32 v93, v2
	v_mov_b32_e32 v94, v2
	v_mov_b32_e32 v95, v2
	v_mov_b32_e32 v96, v2
	v_mov_b32_e32 v97, v2
	v_mov_b32_e32 v34, v2
	v_mov_b32_e32 v35, v2
	v_mov_b32_e32 v36, v2
	v_mov_b32_e32 v37, v2
	v_mov_b32_e32 v38, v2
	v_mov_b32_e32 v39, v2
	v_mov_b32_e32 v40, v2
	v_mov_b32_e32 v41, v2
	v_mov_b32_e32 v42, v2
	v_mov_b32_e32 v43, v2
	v_mov_b32_e32 v44, v2
	v_mov_b32_e32 v45, v2
	v_mov_b32_e32 v46, v2
	v_mov_b32_e32 v47, v2
	v_mov_b32_e32 v48, v2
	v_mov_b32_e32 v49, v2
	v_mov_b32_e32 v50, v2
	v_mov_b32_e32 v51, v2
	v_mov_b32_e32 v52, v2
	v_mov_b32_e32 v53, v2
	v_mov_b32_e32 v54, v2
	v_mov_b32_e32 v55, v2
	v_mov_b32_e32 v56, v2
	v_mov_b32_e32 v57, v2
	v_mov_b32_e32 v62, v2
	v_mov_b32_e32 v63, v2
	v_mov_b32_e32 v64, v2
	v_mov_b32_e32 v65, v2
	v_mov_b32_e32 v70, v2
	v_mov_b32_e32 v71, v2
	v_mov_b32_e32 v72, v2
	v_mov_b32_e32 v73, v2
	v_mov_b32_e32 v98, v2
	v_mov_b32_e32 v99, v2
	v_mov_b32_e32 v100, v2
	v_mov_b32_e32 v101, v2
	v_mov_b32_e32 v102, v2
	v_mov_b32_e32 v103, v2
	v_mov_b32_e32 v104, v2
	v_mov_b32_e32 v105, v2
	v_mov_b32_e32 v106, v2
	v_mov_b32_e32 v107, v2
	v_mov_b32_e32 v108, v2
	v_mov_b32_e32 v109, v2
	v_mov_b32_e32 v110, v2
	v_mov_b32_e32 v111, v2
	v_mov_b32_e32 v112, v2
	v_mov_b32_e32 v113, v2
	v_mov_b32_e32 v114, v2
	v_mov_b32_e32 v115, v2
	v_mov_b32_e32 v116, v2
	v_mov_b32_e32 v117, v2
	v_mov_b32_e32 v118, v2
	v_mov_b32_e32 v119, v2
	v_mov_b32_e32 v120, v2
	v_mov_b32_e32 v121, v2
	v_mov_b32_e32 v122, v2
	v_mov_b32_e32 v123, v2
	v_mov_b32_e32 v124, v2
	v_mov_b32_e32 v125, v2
	v_mov_b32_e32 v126, v2
	v_mov_b32_e32 v127, v2
	v_mov_b32_e32 v128, v2
	v_mov_b32_e32 v129, v2
	v_add_u32_e32 v236, s3, v150
	v_add_u32_e32 v237, s35, v150
	v_add_u32_e32 v238, s50, v150
	v_add_u32_e32 v239, s90, v150
.LBB0_922:
	s_barrier
	ds_read_b128 v[142:145], v236
	ds_read_b128 v[146:149], v236 offset:1024
	ds_read_b128 v[154:157], v236 offset:2048
	ds_read_b128 v[158:161], v236 offset:3072
	s_add_u32 s16, s14, 0xfff80080
	s_addc_u32 s17, s15, -1
	s_cmp_eq_u32 vcc_lo, 28
	s_cselect_b32 s19, s9, s17
	s_cselect_b32 s18, s8, s16
	s_cselect_b32 s17, s11, s13
	s_cselect_b32 s16, s10, s7
	s_add_i32 m0, s22, 0xc000
	ds_read_b128 v[162:165], v152
	ds_read_b128 v[166:169], v152 offset:1024
	ds_read_b128 v[170:173], v152 offset:2048
	ds_read_b128 v[174:177], v152 offset:3072
	ds_read_b128 v[178:181], v152 offset:4096
	ds_read_b128 v[182:185], v152 offset:5120
	ds_read_b128 v[186:189], v152 offset:6144
	ds_read_b128 v[190:193], v152 offset:7168
	global_load_lds_dwordx4 v138, s[14:15]
	s_add_i32 m0, s22, 0xe000
	s_nop 0
	global_load_lds_dwordx4 v140, s[14:15]
	s_waitcnt lgkmcnt(8)
	s_barrier
	s_waitcnt lgkmcnt(0)
	s_setprio 1
	s_waitcnt lgkmcnt(0)
	v_mfma_f32_16x16x32_bf16 v[126:129], v[142:145], v[162:165], v[126:129]
	v_mfma_f32_16x16x32_bf16 v[122:125], v[154:157], v[162:165], v[122:125]
	v_mfma_f32_16x16x32_bf16 v[118:121], v[142:145], v[170:173], v[118:121]
	v_mfma_f32_16x16x32_bf16 v[114:117], v[154:157], v[170:173], v[114:117]
	v_mfma_f32_16x16x32_bf16 v[110:113], v[142:145], v[178:181], v[110:113]
	v_mfma_f32_16x16x32_bf16 v[106:109], v[154:157], v[178:181], v[106:109]
	v_mfma_f32_16x16x32_bf16 v[102:105], v[142:145], v[186:189], v[102:105]
	v_mfma_f32_16x16x32_bf16 v[98:101], v[154:157], v[186:189], v[98:101]
	v_mfma_f32_16x16x32_bf16 v[126:129], v[146:149], v[166:169], v[126:129]
	v_mfma_f32_16x16x32_bf16 v[122:125], v[158:161], v[166:169], v[122:125]
	v_mfma_f32_16x16x32_bf16 v[118:121], v[146:149], v[174:177], v[118:121]
	v_mfma_f32_16x16x32_bf16 v[114:117], v[158:161], v[174:177], v[114:117]
	v_mfma_f32_16x16x32_bf16 v[110:113], v[146:149], v[182:185], v[110:113]
	v_mfma_f32_16x16x32_bf16 v[106:109], v[158:161], v[182:185], v[106:109]
	v_mfma_f32_16x16x32_bf16 v[102:105], v[146:149], v[190:193], v[102:105]
	v_mfma_f32_16x16x32_bf16 v[98:101], v[158:161], v[190:193], v[98:101]
	s_setprio 0
	s_barrier
	s_mov_b32 m0, s20
	ds_read_b128 v[194:197], v237
	ds_read_b128 v[198:201], v237 offset:1024
	ds_read_b128 v[202:205], v237 offset:2048
	ds_read_b128 v[206:209], v237 offset:3072
	global_load_lds_dwordx4 v132, s[16:17]
	s_mov_b32 m0, s21
	s_nop 0
	global_load_lds_dwordx4 v136, s[16:17]
	s_barrier
; #define PG8_STAGE(bufoff, gbase, voff) do { _Pragma("unroll") for (int _i = 0; _i < 2; ++_i) \
;         __builtin_amdgcn_global_load_lds((const unsigned*)((const char*)(gbase) + (voff)[_i]), (LAS unsigned*)(lds + (bufoff) + ldsw + _i * 8192), 16, 0, 0); } while (0)
; #define PG8_LDA(dst, b, h) do { _Pragma("unroll") for (int m = 0; m < 4; ++m) _Pragma("unroll") for (int k = 0; k < 2; ++k) dst[m][k] = *(const LAS bf16x8*)(lds + PG8_SA(b, h) + aoff + m * 2048 + k * 1024); } while (0)
; #define PG8_LDB(dst, b, h) do { _Pragma("unroll") for (int n = 0; n < 2; ++n) _Pragma("unroll") for (int k = 0; k < 2; ++k) dst[n][k] = *(const LAS bf16x8*)(lds + PG8_SB(b, h) + boff + n * 2048 + k * 1024); } while (0)
; #define PG8_MMA(ai, bj, At, Bt) do { __builtin_amdgcn_s_setprio(1); _Pragma("unroll") for (int m = 0; m < 4; ++m) _Pragma("unroll") for (int n = 0; n < 2; ++n) _Pragma("unroll") for (int k = 0; k < 2; ++k) \
;         acc[ai][bj][m][n] = __builtin_amdgcn_mfma_f32_16x16x32_bf16(Bt[n][k], At[m][k], acc[ai][bj][m][n], 0, 0, 0); __builtin_amdgcn_s_setprio(0); } while (0)
; #define PG8_WAIT_V(n) asm volatile("s_waitcnt vmcnt(" #n ")" ::: "memory")
; #define PG8_WAIT_L(n) asm volatile("s_waitcnt lgkmcnt(" #n ")" ::: "memory")
; #define PG8_BAR __builtin_amdgcn_s_barrier()
; #define PG8_SCHED __builtin_amdgcn_sched_barrier(0)
; template <class Epi, class Sched>
; __device__ __forceinline__ void gemm_phase(LAS unsigned char* lds_in, const int lda, const int ldb, const Sched& S, const Epi& E, const int WID) {
;     ...
;             PG8_LDB(B1, 0, 1); PG8_STAGE(PG8_SB(0, 0), b2, voffB);
;             PG8_BAR; PG8_WAIT_L(0); PG8_MMA(0, 1, At, B1); PG8_BAR;
;             PG8_LDA(At, 0, 1); PG8_STAGE(PG8_SA(0, 0), a2, voffA);
;             PG8_BAR; PG8_WAIT_L(0); PG8_MMA(1, 0, At, B0); PG8_BAR; PG8_SCHED;
;             PG8_STAGE(PG8_SB(0, 1), b2 + hstepB, voffB);
;             PG8_WAIT_V(6); PG8_BAR; PG8_MMA(1, 1, At, B1); PG8_BAR;
;             PG8_LDB(B0, 1, 0); PG8_SCHED; PG8_LDA(At, 1, 0); PG8_STAGE(PG8_SA(0, 1), a2 + hstepA, voffA);
;             PG8_WAIT_L(8); PG8_BAR; PG8_WAIT_L(0); PG8_MMA(0, 0, At, B0); PG8_BAR; PG8_SCHED;
	s_waitcnt lgkmcnt(0)
	s_setprio 1
	s_waitcnt lgkmcnt(0)
	v_mfma_f32_16x16x32_bf16 v[70:73], v[194:197], v[162:165], v[70:73]
	v_mfma_f32_16x16x32_bf16 v[62:65], v[202:205], v[162:165], v[62:65]
	v_mfma_f32_16x16x32_bf16 v[54:57], v[194:197], v[170:173], v[54:57]
	v_mfma_f32_16x16x32_bf16 v[50:53], v[202:205], v[170:173], v[50:53]
	v_mfma_f32_16x16x32_bf16 v[46:49], v[194:197], v[178:181], v[46:49]
	v_mfma_f32_16x16x32_bf16 v[42:45], v[202:205], v[178:181], v[42:45]
	v_mfma_f32_16x16x32_bf16 v[38:41], v[194:197], v[186:189], v[38:41]
	v_mfma_f32_16x16x32_bf16 v[34:37], v[202:205], v[186:189], v[34:37]
	v_mfma_f32_16x16x32_bf16 v[70:73], v[198:201], v[166:169], v[70:73]
	v_mfma_f32_16x16x32_bf16 v[62:65], v[206:209], v[166:169], v[62:65]
	v_mfma_f32_16x16x32_bf16 v[54:57], v[198:201], v[174:177], v[54:57]
	v_mfma_f32_16x16x32_bf16 v[50:53], v[206:209], v[174:177], v[50:53]
	v_mfma_f32_16x16x32_bf16 v[46:49], v[198:201], v[182:185], v[46:49]
	v_mfma_f32_16x16x32_bf16 v[42:45], v[206:209], v[182:185], v[42:45]
	v_mfma_f32_16x16x32_bf16 v[38:41], v[198:201], v[190:193], v[38:41]
	v_mfma_f32_16x16x32_bf16 v[34:37], v[206:209], v[190:193], v[34:37]
	s_setprio 0
	s_mov_b32 m0, s22
	s_barrier
	ds_read_b128 v[162:165], v152 offset:16384
	ds_read_b128 v[166:169], v152 offset:17408
	ds_read_b128 v[170:173], v152 offset:18432
	ds_read_b128 v[174:177], v152 offset:19456
	ds_read_b128 v[178:181], v152 offset:20480
	ds_read_b128 v[182:185], v152 offset:21504
	ds_read_b128 v[186:189], v152 offset:22528
	ds_read_b128 v[190:193], v152 offset:23552
	global_load_lds_dwordx4 v130, s[18:19]
	s_mov_b32 m0, s23
	s_nop 0
	global_load_lds_dwordx4 v134, s[18:19]
	s_barrier
	s_waitcnt lgkmcnt(0)
	s_setprio 1
	s_waitcnt lgkmcnt(0)
	v_mfma_f32_16x16x32_bf16 v[94:97], v[142:145], v[162:165], v[94:97]
	v_mfma_f32_16x16x32_bf16 v[90:93], v[154:157], v[162:165], v[90:93]
	v_mfma_f32_16x16x32_bf16 v[86:89], v[142:145], v[170:173], v[86:89]
	v_mfma_f32_16x16x32_bf16 v[82:85], v[154:157], v[170:173], v[82:85]
	v_mfma_f32_16x16x32_bf16 v[78:81], v[142:145], v[178:181], v[78:81]
	v_mfma_f32_16x16x32_bf16 v[74:77], v[154:157], v[178:181], v[74:77]
	v_mfma_f32_16x16x32_bf16 v[66:69], v[142:145], v[186:189], v[66:69]
	v_mfma_f32_16x16x32_bf16 v[58:61], v[154:157], v[186:189], v[58:61]
	v_mfma_f32_16x16x32_bf16 v[94:97], v[146:149], v[166:169], v[94:97]
	v_mfma_f32_16x16x32_bf16 v[90:93], v[158:161], v[166:169], v[90:93]
	v_mfma_f32_16x16x32_bf16 v[86:89], v[146:149], v[174:177], v[86:89]
	v_mfma_f32_16x16x32_bf16 v[82:85], v[158:161], v[174:177], v[82:85]
	v_mfma_f32_16x16x32_bf16 v[78:81], v[146:149], v[182:185], v[78:81]
	v_mfma_f32_16x16x32_bf16 v[74:77], v[158:161], v[182:185], v[74:77]
	v_mfma_f32_16x16x32_bf16 v[66:69], v[146:149], v[190:193], v[66:69]
	v_mfma_f32_16x16x32_bf16 v[58:61], v[158:161], v[190:193], v[58:61]
	s_setprio 0
	s_barrier
	s_add_u32 s66, s16, 0x400000
	s_addc_u32 s67, s17, 0
	s_mov_b32 m0, s46
	s_nop 0
	global_load_lds_dwordx4 v132, s[66:67]
	s_mov_b32 m0, s47
	s_nop 0
	global_load_lds_dwordx4 v136, s[66:67]
	s_waitcnt vmcnt(6)
	s_barrier
	s_setprio 1
	v_mfma_f32_16x16x32_bf16 v[30:33], v[194:197], v[162:165], v[30:33]
	v_mfma_f32_16x16x32_bf16 v[26:29], v[202:205], v[162:165], v[26:29]
	v_mfma_f32_16x16x32_bf16 v[22:25], v[194:197], v[170:173], v[22:25]
	v_mfma_f32_16x16x32_bf16 v[18:21], v[202:205], v[170:173], v[18:21]
	v_mfma_f32_16x16x32_bf16 v[14:17], v[194:197], v[178:181], v[14:17]
	v_mfma_f32_16x16x32_bf16 v[10:13], v[202:205], v[178:181], v[10:13]
	v_mfma_f32_16x16x32_bf16 v[6:9], v[194:197], v[186:189], v[6:9]
	v_mfma_f32_16x16x32_bf16 v[2:5], v[202:205], v[186:189], v[2:5]
	v_mfma_f32_16x16x32_bf16 v[30:33], v[198:201], v[166:169], v[30:33]
	v_mfma_f32_16x16x32_bf16 v[26:29], v[206:209], v[166:169], v[26:29]
	v_mfma_f32_16x16x32_bf16 v[22:25], v[198:201], v[174:177], v[22:25]
	v_mfma_f32_16x16x32_bf16 v[18:21], v[206:209], v[174:177], v[18:21]
	v_mfma_f32_16x16x32_bf16 v[14:17], v[198:201], v[182:185], v[14:17]
	v_mfma_f32_16x16x32_bf16 v[10:13], v[206:209], v[182:185], v[10:13]
	v_mfma_f32_16x16x32_bf16 v[6:9], v[198:201], v[190:193], v[6:9]
	v_mfma_f32_16x16x32_bf16 v[2:5], v[206:209], v[190:193], v[2:5]
	s_setprio 0
	s_barrier
	ds_read_b128 v[142:145], v238
	ds_read_b128 v[146:149], v238 offset:1024
	ds_read_b128 v[154:157], v238 offset:2048
	ds_read_b128 v[158:161], v238 offset:3072
	s_add_u32 s18, s18, 0x80000
	s_addc_u32 s19, s19, 0
	s_mov_b32 m0, s48
	ds_read_b128 v[162:165], v152 offset:32768
	ds_read_b128 v[166:169], v152 offset:33792
	ds_read_b128 v[170:173], v152 offset:34816
	ds_read_b128 v[174:177], v152 offset:35840
	ds_read_b128 v[178:181], v152 offset:36864
	ds_read_b128 v[182:185], v152 offset:37888
	ds_read_b128 v[186:189], v152 offset:38912
	ds_read_b128 v[190:193], v152 offset:39936
	global_load_lds_dwordx4 v130, s[18:19]
	s_mov_b32 m0, s49
	s_nop 0
	global_load_lds_dwordx4 v134, s[18:19]
	s_waitcnt lgkmcnt(8)
	s_barrier
	s_waitcnt lgkmcnt(0)
	s_setprio 1
	s_waitcnt lgkmcnt(0)
	v_mfma_f32_16x16x32_bf16 v[126:129], v[142:145], v[162:165], v[126:129]
	v_mfma_f32_16x16x32_bf16 v[122:125], v[154:157], v[162:165], v[122:125]
	v_mfma_f32_16x16x32_bf16 v[118:121], v[142:145], v[170:173], v[118:121]
	v_mfma_f32_16x16x32_bf16 v[114:117], v[154:157], v[170:173], v[114:117]
	v_mfma_f32_16x16x32_bf16 v[110:113], v[142:145], v[178:181], v[110:113]
	v_mfma_f32_16x16x32_bf16 v[106:109], v[154:157], v[178:181], v[106:109]
	v_mfma_f32_16x16x32_bf16 v[102:105], v[142:145], v[186:189], v[102:105]
	v_mfma_f32_16x16x32_bf16 v[98:101], v[154:157], v[186:189], v[98:101]
	v_mfma_f32_16x16x32_bf16 v[126:129], v[146:149], v[166:169], v[126:129]
	v_mfma_f32_16x16x32_bf16 v[122:125], v[158:161], v[166:169], v[122:125]
	v_mfma_f32_16x16x32_bf16 v[118:121], v[146:149], v[174:177], v[118:121]
	v_mfma_f32_16x16x32_bf16 v[114:117], v[158:161], v[174:177], v[114:117]
	v_mfma_f32_16x16x32_bf16 v[110:113], v[146:149], v[182:185], v[110:113]
	v_mfma_f32_16x16x32_bf16 v[106:109], v[158:161], v[182:185], v[106:109]
	v_mfma_f32_16x16x32_bf16 v[102:105], v[146:149], v[190:193], v[102:105]
	v_mfma_f32_16x16x32_bf16 v[98:101], v[158:161], v[190:193], v[98:101]
	s_setprio 0
	s_barrier
; #define PG8_STAGE(bufoff, gbase, voff) do { _Pragma("unroll") for (int _i = 0; _i < 2; ++_i) \
;         __builtin_amdgcn_global_load_lds((const unsigned*)((const char*)(gbase) + (voff)[_i]), (LAS unsigned*)(lds + (bufoff) + ldsw + _i * 8192), 16, 0, 0); } while (0)
; #define PG8_LDA(dst, b, h) do { _Pragma("unroll") for (int m = 0; m < 4; ++m) _Pragma("unroll") for (int k = 0; k < 2; ++k) dst[m][k] = *(const LAS bf16x8*)(lds + PG8_SA(b, h) + aoff + m * 2048 + k * 1024); } while (0)
; #define PG8_LDB(dst, b, h) do { _Pragma("unroll") for (int n = 0; n < 2; ++n) _Pragma("unroll") for (int k = 0; k < 2; ++k) dst[n][k] = *(const LAS bf16x8*)(lds + PG8_SB(b, h) + boff + n * 2048 + k * 1024); } while (0)
; #define PG8_WAIT_V(n) asm volatile("s_waitcnt vmcnt(" #n ")" ::: "memory")
; #define PG8_WAIT_L(n) asm volatile("s_waitcnt lgkmcnt(" #n ")" ::: "memory")
; #define PG8_BAR __builtin_amdgcn_s_barrier()
; #define PG8_SCHED __builtin_amdgcn_sched_barrier(0)
; template <class Epi, class Sched>
; __device__ __forceinline__ void gemm_phase(LAS unsigned char* lds_in, const int lda, const int ldb, const Sched& S, const Epi& E, const int WID) {
;     ...
;             PG8_WAIT_L(8); PG8_BAR; PG8_WAIT_L(0); PG8_MMA(0, 0, At, B0); PG8_BAR; PG8_SCHED;
;             PG8_LDB(B1, 1, 1); PG8_STAGE(PG8_SB(1, 0), b3, voffB);
;             PG8_BAR; PG8_WAIT_L(0); PG8_MMA(0, 1, At, B1); PG8_BAR;
;             PG8_LDA(At, 1, 1); PG8_STAGE(PG8_SA(1, 0), a3, voffA);
;             PG8_BAR; PG8_WAIT_L(0); PG8_MMA(1, 0, At, B0); PG8_BAR; PG8_SCHED;
;             PG8_STAGE(PG8_SB(1, 1), b3 + hstepB, voffB);
;             PG8_WAIT_V(6); PG8_BAR; PG8_MMA(1, 1, At, B1); PG8_BAR;
;         }
;     __device__ __forceinline__ void operator()(const AccT& acc, const Unit& u, int wr, int wc, int fr, int fq) const {
;         const int part = u.pm >> 3, s0 = (u.pm & 7) * 256 + wr * 64 + fr, pb = u.aux;
; #pragma unroll
;         for (int bj = 0; bj < 2; ++bj) {
;             const int dcol = (u.pn * 2 + bj) * 256 + part * 128 + wc * 32 + 8 * fq;
; #pragma unroll
;             for (int ai = 0; ai < 2; ++ai)
; #pragma unroll
;                 for (int m = 0; m < 4; ++m) {
;                     const size_t tok = (size_t)pb * 2048 + s0 + ai * 128 + m * 16;
;                     bf16_t* dst = sample ? (E + tok * 1024 + dcol) : (X + tok * XW + dcol);
	s_mov_b32 m0, s51
	s_add_u32 s100, s16, 0x80
	s_addc_u32 s101, s17, 0
	ds_read_b128 v[194:197], v239
	ds_read_b128 v[198:201], v239 offset:1024
	ds_read_b128 v[202:205], v239 offset:2048
	ds_read_b128 v[206:209], v239 offset:3072
	global_load_lds_dwordx4 v132, s[100:101]
	s_add_u32 s100, s16, 0x80
	s_addc_u32 s101, s17, 0
	s_mov_b32 m0, s65
	s_nop 0
	global_load_lds_dwordx4 v136, s[100:101]
	s_barrier
	s_waitcnt lgkmcnt(0)
	s_setprio 1
	s_waitcnt lgkmcnt(0)
	v_mfma_f32_16x16x32_bf16 v[70:73], v[194:197], v[162:165], v[70:73]
	v_mfma_f32_16x16x32_bf16 v[62:65], v[202:205], v[162:165], v[62:65]
	v_mfma_f32_16x16x32_bf16 v[54:57], v[194:197], v[170:173], v[54:57]
	v_mfma_f32_16x16x32_bf16 v[50:53], v[202:205], v[170:173], v[50:53]
	v_mfma_f32_16x16x32_bf16 v[46:49], v[194:197], v[178:181], v[46:49]
	v_mfma_f32_16x16x32_bf16 v[42:45], v[202:205], v[178:181], v[42:45]
	v_mfma_f32_16x16x32_bf16 v[38:41], v[194:197], v[186:189], v[38:41]
	v_mfma_f32_16x16x32_bf16 v[34:37], v[202:205], v[186:189], v[34:37]
	v_mfma_f32_16x16x32_bf16 v[70:73], v[198:201], v[166:169], v[70:73]
	v_mfma_f32_16x16x32_bf16 v[62:65], v[206:209], v[166:169], v[62:65]
	v_mfma_f32_16x16x32_bf16 v[54:57], v[198:201], v[174:177], v[54:57]
	v_mfma_f32_16x16x32_bf16 v[50:53], v[206:209], v[174:177], v[50:53]
	v_mfma_f32_16x16x32_bf16 v[46:49], v[198:201], v[182:185], v[46:49]
	v_mfma_f32_16x16x32_bf16 v[42:45], v[206:209], v[182:185], v[42:45]
	v_mfma_f32_16x16x32_bf16 v[38:41], v[198:201], v[190:193], v[38:41]
	v_mfma_f32_16x16x32_bf16 v[34:37], v[206:209], v[190:193], v[34:37]
	s_setprio 0
	s_mov_b32 m0, s78
	s_add_u32 s100, s18, 0xfff80080
	s_addc_u32 s101, s19, -1
	s_barrier
	ds_read_b128 v[162:165], v152 offset:49152
	ds_read_b128 v[166:169], v152 offset:50176
	ds_read_b128 v[170:173], v152 offset:51200
	ds_read_b128 v[174:177], v152 offset:52224
	ds_read_b128 v[178:181], v152 offset:53248
	ds_read_b128 v[182:185], v152 offset:54272
	ds_read_b128 v[186:189], v152 offset:55296
	ds_read_b128 v[190:193], v152 offset:56320
	global_load_lds_dwordx4 v130, s[100:101]
	s_add_u32 s100, s18, 0xfff80080
	s_addc_u32 s101, s19, -1
	s_mov_b32 m0, s79
	s_nop 0
	global_load_lds_dwordx4 v134, s[100:101]
	s_barrier
	s_waitcnt lgkmcnt(0)
	s_setprio 1
	s_waitcnt lgkmcnt(0)
	v_mfma_f32_16x16x32_bf16 v[94:97], v[142:145], v[162:165], v[94:97]
	v_mfma_f32_16x16x32_bf16 v[90:93], v[154:157], v[162:165], v[90:93]
	v_mfma_f32_16x16x32_bf16 v[86:89], v[142:145], v[170:173], v[86:89]
	v_mfma_f32_16x16x32_bf16 v[82:85], v[154:157], v[170:173], v[82:85]
	v_mfma_f32_16x16x32_bf16 v[78:81], v[142:145], v[178:181], v[78:81]
	v_mfma_f32_16x16x32_bf16 v[74:77], v[154:157], v[178:181], v[74:77]
	v_mfma_f32_16x16x32_bf16 v[66:69], v[142:145], v[186:189], v[66:69]
	v_mfma_f32_16x16x32_bf16 v[58:61], v[154:157], v[186:189], v[58:61]
	v_mfma_f32_16x16x32_bf16 v[94:97], v[146:149], v[166:169], v[94:97]
	v_mfma_f32_16x16x32_bf16 v[90:93], v[158:161], v[166:169], v[90:93]
	v_mfma_f32_16x16x32_bf16 v[86:89], v[146:149], v[174:177], v[86:89]
	v_mfma_f32_16x16x32_bf16 v[82:85], v[158:161], v[174:177], v[82:85]
	v_mfma_f32_16x16x32_bf16 v[78:81], v[146:149], v[182:185], v[78:81]
	v_mfma_f32_16x16x32_bf16 v[74:77], v[158:161], v[182:185], v[74:77]
	v_mfma_f32_16x16x32_bf16 v[66:69], v[146:149], v[190:193], v[66:69]
	v_mfma_f32_16x16x32_bf16 v[58:61], v[158:161], v[190:193], v[58:61]
	s_setprio 0
	s_barrier
	s_add_u32 s16, s16, 0x400080
	s_addc_u32 s17, s17, 0
	s_mov_b32 m0, s91
	s_nop 0
	global_load_lds_dwordx4 v132, s[16:17]
	s_mov_b32 m0, s92
	s_nop 0
	global_load_lds_dwordx4 v136, s[16:17]
	s_waitcnt vmcnt(6)
	s_barrier
	s_setprio 1
	v_mfma_f32_16x16x32_bf16 v[30:33], v[194:197], v[162:165], v[30:33]
	v_mfma_f32_16x16x32_bf16 v[26:29], v[202:205], v[162:165], v[26:29]
	v_mfma_f32_16x16x32_bf16 v[22:25], v[194:197], v[170:173], v[22:25]
	v_mfma_f32_16x16x32_bf16 v[18:21], v[202:205], v[170:173], v[18:21]
	v_mfma_f32_16x16x32_bf16 v[14:17], v[194:197], v[178:181], v[14:17]
	v_mfma_f32_16x16x32_bf16 v[10:13], v[202:205], v[178:181], v[10:13]
	v_mfma_f32_16x16x32_bf16 v[6:9], v[194:197], v[186:189], v[6:9]
	v_mfma_f32_16x16x32_bf16 v[2:5], v[202:205], v[186:189], v[2:5]
	v_mfma_f32_16x16x32_bf16 v[30:33], v[198:201], v[166:169], v[30:33]
	v_mfma_f32_16x16x32_bf16 v[26:29], v[206:209], v[166:169], v[26:29]
	v_mfma_f32_16x16x32_bf16 v[22:25], v[198:201], v[174:177], v[22:25]
	v_mfma_f32_16x16x32_bf16 v[18:21], v[206:209], v[174:177], v[18:21]
	v_mfma_f32_16x16x32_bf16 v[14:17], v[198:201], v[182:185], v[14:17]
	v_mfma_f32_16x16x32_bf16 v[10:13], v[206:209], v[182:185], v[10:13]
	v_mfma_f32_16x16x32_bf16 v[6:9], v[198:201], v[190:193], v[6:9]
	v_mfma_f32_16x16x32_bf16 v[2:5], v[206:209], v[190:193], v[2:5]
	s_setprio 0
	s_add_i32 vcc_lo, vcc_lo, 2
	s_add_u32 s14, s14, 0x100
	s_addc_u32 s15, s15, 0
	s_add_u32 s7, s7, 0x100
	s_addc_u32 s13, s13, 0
	s_cmp_gt_u32 vcc_lo, 29
	s_cbranch_scc0 .LBB0_922
	s_lshl_b32 s7, s97, 8
	s_and_b32 s7, s7, 0x700
	v_add_u32_e32 v142, s7, v1
	s_ashr_i32 s13, s12, 31
	s_lshl_b64 s[12:13], s[12:13], 11
	v_ashrrev_i32_e32 v143, 31, v142
	v_lshl_add_u64 v[144:145], s[12:13], 0, v[142:143]
	s_mov_b64 s[12:13], -1
	s_and_b64 vcc, exec, s[4:5]
	s_cbranch_vccz .LBB0_925
	v_mov_b64_e32 v[142:143], s[42:43]
	v_mad_u64_u32 v[148:149], s[12:13], v144, s57, v[142:143]
	v_mad_i32_i24 v149, v145, s57, v149
	s_mov_b64 s[12:13], 0

; #define PG8_STAGE(bufoff, gbase, voff) do { _Pragma("unroll") for (int _i = 0; _i < 2; ++_i) \
;         __builtin_amdgcn_global_load_lds((const unsigned*)((const char*)(gbase) + (voff)[_i]), (LAS unsigned*)(lds + (bufoff) + ldsw + _i * 8192), 16, 0, 0); } while (0)
; #define PG8_LDA(dst, b, h) do { _Pragma("unroll") for (int m = 0; m < 4; ++m) _Pragma("unroll") for (int k = 0; k < 2; ++k) dst[m][k] = *(const LAS bf16x8*)(lds + PG8_SA(b, h) + aoff + m * 2048 + k * 1024); } while (0)
; #define PG8_LDB(dst, b, h) do { _Pragma("unroll") for (int n = 0; n < 2; ++n) _Pragma("unroll") for (int k = 0; k < 2; ++k) dst[n][k] = *(const LAS bf16x8*)(lds + PG8_SB(b, h) + boff + n * 2048 + k * 1024); } while (0)
; #define PG8_MMA(ai, bj, At, Bt) do { __builtin_amdgcn_s_setprio(1); _Pragma("unroll") for (int m = 0; m < 4; ++m) _Pragma("unroll") for (int n = 0; n < 2; ++n) _Pragma("unroll") for (int k = 0; k < 2; ++k) \
;         acc[ai][bj][m][n] = __builtin_amdgcn_mfma_f32_16x16x32_bf16(Bt[n][k], At[m][k], acc[ai][bj][m][n], 0, 0, 0); __builtin_amdgcn_s_setprio(0); } while (0)
; #define PG8_WAIT_L(n) asm volatile("s_waitcnt lgkmcnt(" #n ")" ::: "memory")
; #define PG8_BAR __builtin_amdgcn_s_barrier()
; #define PG8_SCHED __builtin_amdgcn_sched_barrier(0)
; template <class Epi, class Sched>
; __device__ __forceinline__ void gemm_phase(LAS unsigned char* lds_in, const int lda, const int ldb, const Sched& S, const Epi& E, const int WID) {
;     ...
;             PG8_LDB(B0, 0, 0); PG8_SCHED; PG8_LDA(At, 0, 0); PG8_STAGE(PG8_SA(1, 1), a1 + hstepA, voffA);
;             PG8_WAIT_L(8); PG8_BAR; PG8_WAIT_L(0); PG8_MMA(0, 0, At, B0); PG8_BAR; PG8_SCHED;
;     ...
; #pragma unroll
;         for (int a = 0; a < 2; ++a)
; #pragma unroll
;             for (int b = 0; b < 2; ++b)
; #pragma unroll
;                 for (int m = 0; m < 4; ++m)
; #pragma unroll
;                     for (int n = 0; n < 2; ++n) acc[a][b][m][n] = (f32x4){0.f, 0.f, 0.f, 0.f};
.LBB0_1039:
	s_add_u32 s18, s18, 0x80080
	s_addc_u32 s19, s19, 0
	s_add_u32 s1, s20, 0x100
	v_mov_b32_e32 v2, 0
	s_addc_u32 s11, s21, 0
	s_mov_b32 s70, -2
	v_mov_b32_e32 v3, v2
	v_mov_b32_e32 v4, v2
	v_mov_b32_e32 v5, v2
	v_mov_b32_e32 v6, v2
	v_mov_b32_e32 v7, v2
	v_mov_b32_e32 v8, v2
	v_mov_b32_e32 v9, v2
	v_mov_b32_e32 v10, v2
	v_mov_b32_e32 v11, v2
	v_mov_b32_e32 v12, v2
	v_mov_b32_e32 v13, v2
	v_mov_b32_e32 v14, v2
	v_mov_b32_e32 v15, v2
	v_mov_b32_e32 v16, v2
	v_mov_b32_e32 v17, v2
	v_mov_b32_e32 v18, v2
	v_mov_b32_e32 v19, v2
	v_mov_b32_e32 v20, v2
	v_mov_b32_e32 v21, v2
	v_mov_b32_e32 v22, v2
	v_mov_b32_e32 v23, v2
	v_mov_b32_e32 v24, v2
	v_mov_b32_e32 v25, v2
	v_mov_b32_e32 v26, v2
	v_mov_b32_e32 v27, v2
	v_mov_b32_e32 v28, v2
	v_mov_b32_e32 v29, v2
	v_mov_b32_e32 v30, v2
	v_mov_b32_e32 v31, v2
	v_mov_b32_e32 v32, v2
	v_mov_b32_e32 v33, v2
	v_mov_b32_e32 v66, v2
	v_mov_b32_e32 v67, v2
	v_mov_b32_e32 v68, v2
	v_mov_b32_e32 v69, v2
	v_mov_b32_e32 v70, v2
	v_mov_b32_e32 v71, v2
	v_mov_b32_e32 v72, v2
	v_mov_b32_e32 v73, v2
	v_mov_b32_e32 v74, v2
	v_mov_b32_e32 v75, v2
	v_mov_b32_e32 v76, v2
	v_mov_b32_e32 v77, v2
	v_mov_b32_e32 v78, v2
	v_mov_b32_e32 v79, v2
	v_mov_b32_e32 v80, v2
	v_mov_b32_e32 v81, v2
	v_mov_b32_e32 v82, v2
	v_mov_b32_e32 v83, v2
	v_mov_b32_e32 v84, v2
	v_mov_b32_e32 v85, v2
	v_mov_b32_e32 v86, v2
	v_mov_b32_e32 v87, v2
	v_mov_b32_e32 v88, v2
	v_mov_b32_e32 v89, v2
	v_mov_b32_e32 v90, v2
	v_mov_b32_e32 v91, v2
	v_mov_b32_e32 v92, v2
	v_mov_b32_e32 v93, v2
	v_mov_b32_e32 v94, v2
	v_mov_b32_e32 v95, v2
	v_mov_b32_e32 v96, v2
	v_mov_b32_e32 v97, v2
	v_mov_b32_e32 v34, v2
	v_mov_b32_e32 v35, v2
	v_mov_b32_e32 v36, v2
	v_mov_b32_e32 v37, v2
	v_mov_b32_e32 v38, v2
	v_mov_b32_e32 v39, v2
	v_mov_b32_e32 v40, v2
	v_mov_b32_e32 v41, v2
	v_mov_b32_e32 v42, v2
	v_mov_b32_e32 v43, v2
	v_mov_b32_e32 v44, v2
	v_mov_b32_e32 v45, v2
	v_mov_b32_e32 v46, v2
	v_mov_b32_e32 v47, v2
	v_mov_b32_e32 v48, v2
	v_mov_b32_e32 v49, v2
	v_mov_b32_e32 v50, v2
	v_mov_b32_e32 v51, v2
	v_mov_b32_e32 v52, v2
	v_mov_b32_e32 v53, v2
	v_mov_b32_e32 v54, v2
	v_mov_b32_e32 v55, v2
	v_mov_b32_e32 v56, v2
	v_mov_b32_e32 v57, v2
	v_mov_b32_e32 v58, v2
	v_mov_b32_e32 v59, v2
	v_mov_b32_e32 v60, v2
	v_mov_b32_e32 v61, v2
	v_mov_b32_e32 v62, v2
	v_mov_b32_e32 v63, v2
	v_mov_b32_e32 v64, v2
	v_mov_b32_e32 v65, v2
	v_mov_b32_e32 v98, v2
	v_mov_b32_e32 v99, v2
	v_mov_b32_e32 v100, v2
	v_mov_b32_e32 v101, v2
	v_mov_b32_e32 v102, v2
	v_mov_b32_e32 v103, v2
	v_mov_b32_e32 v104, v2
	v_mov_b32_e32 v105, v2
	v_mov_b32_e32 v106, v2
	v_mov_b32_e32 v107, v2
	v_mov_b32_e32 v108, v2
	v_mov_b32_e32 v109, v2
	v_mov_b32_e32 v110, v2
	v_mov_b32_e32 v111, v2
	v_mov_b32_e32 v112, v2
	v_mov_b32_e32 v113, v2
	v_mov_b32_e32 v114, v2
	v_mov_b32_e32 v115, v2
	v_mov_b32_e32 v116, v2
	v_mov_b32_e32 v117, v2
	v_mov_b32_e32 v118, v2
	v_mov_b32_e32 v119, v2
	v_mov_b32_e32 v120, v2
	v_mov_b32_e32 v121, v2
	v_mov_b32_e32 v122, v2
	v_mov_b32_e32 v123, v2
	v_mov_b32_e32 v124, v2
	v_mov_b32_e32 v125, v2
	v_mov_b32_e32 v126, v2
	v_mov_b32_e32 v127, v2
	v_mov_b32_e32 v128, v2
	v_mov_b32_e32 v129, v2
	v_add_u32_e32 v236, s3, v174
	v_add_u32_e32 v237, s48, v174
	v_add_u32_e32 v238, s78, v174
	v_add_u32_e32 v239, s90, v174
.LBB0_1040:
	s_barrier
	ds_read_b128 v[130:133], v236
	ds_read_b128 v[134:137], v236 offset:1024
	ds_read_b128 v[138:141], v236 offset:2048
	ds_read_b128 v[142:145], v236 offset:3072
	s_add_u32 s20, s18, 0xfff80080
	s_addc_u32 s21, s19, -1
	s_cmp_eq_u32 s70, 28
	s_cselect_b32 s23, s13, s21
	s_cselect_b32 s22, s12, s20
	s_cselect_b32 s21, s15, s11
	s_cselect_b32 s20, s14, s1
	s_add_i32 m0, s46, 0xc000
	ds_read_b128 v[158:161], v176
	ds_read_b128 v[162:165], v176 offset:1024
	ds_read_b128 v[166:169], v176 offset:2048
	ds_read_b128 v[170:173], v176 offset:3072
	ds_read_b128 v[178:181], v176 offset:4096
	ds_read_b128 v[182:185], v176 offset:5120
	ds_read_b128 v[186:189], v176 offset:6144
	ds_read_b128 v[190:193], v176 offset:7168
	global_load_lds_dwordx4 v154, s[18:19]
	s_add_i32 m0, s46, 0xe000
	s_nop 0
	global_load_lds_dwordx4 v156, s[18:19]
	s_waitcnt lgkmcnt(8)
	s_barrier
	s_waitcnt lgkmcnt(0)
	s_setprio 1
	s_waitcnt lgkmcnt(0)
	v_mfma_f32_16x16x32_bf16 v[126:129], v[130:133], v[158:161], v[126:129]
	v_mfma_f32_16x16x32_bf16 v[122:125], v[138:141], v[158:161], v[122:125]
	v_mfma_f32_16x16x32_bf16 v[118:121], v[130:133], v[166:169], v[118:121]
	v_mfma_f32_16x16x32_bf16 v[114:117], v[138:141], v[166:169], v[114:117]
	v_mfma_f32_16x16x32_bf16 v[110:113], v[130:133], v[178:181], v[110:113]
	v_mfma_f32_16x16x32_bf16 v[106:109], v[138:141], v[178:181], v[106:109]
	v_mfma_f32_16x16x32_bf16 v[102:105], v[130:133], v[186:189], v[102:105]
	v_mfma_f32_16x16x32_bf16 v[98:101], v[138:141], v[186:189], v[98:101]
	v_mfma_f32_16x16x32_bf16 v[126:129], v[134:137], v[162:165], v[126:129]
	v_mfma_f32_16x16x32_bf16 v[122:125], v[142:145], v[162:165], v[122:125]
	v_mfma_f32_16x16x32_bf16 v[118:121], v[134:137], v[170:173], v[118:121]
	v_mfma_f32_16x16x32_bf16 v[114:117], v[142:145], v[170:173], v[114:117]
	v_mfma_f32_16x16x32_bf16 v[110:113], v[134:137], v[182:185], v[110:113]
	v_mfma_f32_16x16x32_bf16 v[106:109], v[142:145], v[182:185], v[106:109]
	v_mfma_f32_16x16x32_bf16 v[102:105], v[134:137], v[190:193], v[102:105]
	v_mfma_f32_16x16x32_bf16 v[98:101], v[142:145], v[190:193], v[98:101]
	s_setprio 0
	s_barrier
	s_mov_b32 m0, s17
	ds_read_b128 v[194:197], v237
	ds_read_b128 v[198:201], v237 offset:1024
	ds_read_b128 v[202:205], v237 offset:2048
	ds_read_b128 v[206:209], v237 offset:3072
	global_load_lds_dwordx4 v148, s[20:21]
	s_mov_b32 m0, s35
	s_nop 0
	global_load_lds_dwordx4 v152, s[20:21]
	s_barrier
; #define PG8_STAGE(bufoff, gbase, voff) do { _Pragma("unroll") for (int _i = 0; _i < 2; ++_i) \
;         __builtin_amdgcn_global_load_lds((const unsigned*)((const char*)(gbase) + (voff)[_i]), (LAS unsigned*)(lds + (bufoff) + ldsw + _i * 8192), 16, 0, 0); } while (0)
; #define PG8_LDA(dst, b, h) do { _Pragma("unroll") for (int m = 0; m < 4; ++m) _Pragma("unroll") for (int k = 0; k < 2; ++k) dst[m][k] = *(const LAS bf16x8*)(lds + PG8_SA(b, h) + aoff + m * 2048 + k * 1024); } while (0)
; #define PG8_LDB(dst, b, h) do { _Pragma("unroll") for (int n = 0; n < 2; ++n) _Pragma("unroll") for (int k = 0; k < 2; ++k) dst[n][k] = *(const LAS bf16x8*)(lds + PG8_SB(b, h) + boff + n * 2048 + k * 1024); } while (0)
; #define PG8_MMA(ai, bj, At, Bt) do { __builtin_amdgcn_s_setprio(1); _Pragma("unroll") for (int m = 0; m < 4; ++m) _Pragma("unroll") for (int n = 0; n < 2; ++n) _Pragma("unroll") for (int k = 0; k < 2; ++k) \
;         acc[ai][bj][m][n] = __builtin_amdgcn_mfma_f32_16x16x32_bf16(Bt[n][k], At[m][k], acc[ai][bj][m][n], 0, 0, 0); __builtin_amdgcn_s_setprio(0); } while (0)
; #define PG8_WAIT_V(n) asm volatile("s_waitcnt vmcnt(" #n ")" ::: "memory")
; #define PG8_WAIT_L(n) asm volatile("s_waitcnt lgkmcnt(" #n ")" ::: "memory")
; #define PG8_BAR __builtin_amdgcn_s_barrier()
; #define PG8_SCHED __builtin_amdgcn_sched_barrier(0)
; template <class Epi, class Sched>
; __device__ __forceinline__ void gemm_phase(LAS unsigned char* lds_in, const int lda, const int ldb, const Sched& S, const Epi& E, const int WID) {
;     ...
;             PG8_LDB(B1, 0, 1); PG8_STAGE(PG8_SB(0, 0), b2, voffB);
;             PG8_BAR; PG8_WAIT_L(0); PG8_MMA(0, 1, At, B1); PG8_BAR;
;             PG8_LDA(At, 0, 1); PG8_STAGE(PG8_SA(0, 0), a2, voffA);
;             PG8_BAR; PG8_WAIT_L(0); PG8_MMA(1, 0, At, B0); PG8_BAR; PG8_SCHED;
;             PG8_STAGE(PG8_SB(0, 1), b2 + hstepB, voffB);
;             PG8_WAIT_V(6); PG8_BAR; PG8_MMA(1, 1, At, B1); PG8_BAR;
;             PG8_LDB(B0, 1, 0); PG8_SCHED; PG8_LDA(At, 1, 0); PG8_STAGE(PG8_SA(0, 1), a2 + hstepA, voffA);
;             PG8_WAIT_L(8); PG8_BAR; PG8_WAIT_L(0); PG8_MMA(0, 0, At, B0); PG8_BAR; PG8_SCHED;
	s_waitcnt lgkmcnt(0)
	s_setprio 1
	s_waitcnt lgkmcnt(0)
	v_mfma_f32_16x16x32_bf16 v[62:65], v[194:197], v[158:161], v[62:65]
	v_mfma_f32_16x16x32_bf16 v[58:61], v[202:205], v[158:161], v[58:61]
	v_mfma_f32_16x16x32_bf16 v[54:57], v[194:197], v[166:169], v[54:57]
	v_mfma_f32_16x16x32_bf16 v[50:53], v[202:205], v[166:169], v[50:53]
	v_mfma_f32_16x16x32_bf16 v[46:49], v[194:197], v[178:181], v[46:49]
	v_mfma_f32_16x16x32_bf16 v[42:45], v[202:205], v[178:181], v[42:45]
	v_mfma_f32_16x16x32_bf16 v[38:41], v[194:197], v[186:189], v[38:41]
	v_mfma_f32_16x16x32_bf16 v[34:37], v[202:205], v[186:189], v[34:37]
	v_mfma_f32_16x16x32_bf16 v[62:65], v[198:201], v[162:165], v[62:65]
	v_mfma_f32_16x16x32_bf16 v[58:61], v[206:209], v[162:165], v[58:61]
	v_mfma_f32_16x16x32_bf16 v[54:57], v[198:201], v[170:173], v[54:57]
	v_mfma_f32_16x16x32_bf16 v[50:53], v[206:209], v[170:173], v[50:53]
	v_mfma_f32_16x16x32_bf16 v[46:49], v[198:201], v[182:185], v[46:49]
	v_mfma_f32_16x16x32_bf16 v[42:45], v[206:209], v[182:185], v[42:45]
	v_mfma_f32_16x16x32_bf16 v[38:41], v[198:201], v[190:193], v[38:41]
	v_mfma_f32_16x16x32_bf16 v[34:37], v[206:209], v[190:193], v[34:37]
	s_setprio 0
	s_mov_b32 m0, s46
	s_barrier
	ds_read_b128 v[158:161], v176 offset:16384
	ds_read_b128 v[162:165], v176 offset:17408
	ds_read_b128 v[166:169], v176 offset:18432
	ds_read_b128 v[170:173], v176 offset:19456
	ds_read_b128 v[178:181], v176 offset:20480
	ds_read_b128 v[182:185], v176 offset:21504
	ds_read_b128 v[186:189], v176 offset:22528
	ds_read_b128 v[190:193], v176 offset:23552
	global_load_lds_dwordx4 v146, s[22:23]
	s_mov_b32 m0, s47
	s_nop 0
	global_load_lds_dwordx4 v150, s[22:23]
	s_barrier
	s_waitcnt lgkmcnt(0)
	s_setprio 1
	s_waitcnt lgkmcnt(0)
	v_mfma_f32_16x16x32_bf16 v[94:97], v[130:133], v[158:161], v[94:97]
	v_mfma_f32_16x16x32_bf16 v[90:93], v[138:141], v[158:161], v[90:93]
	v_mfma_f32_16x16x32_bf16 v[86:89], v[130:133], v[166:169], v[86:89]
	v_mfma_f32_16x16x32_bf16 v[82:85], v[138:141], v[166:169], v[82:85]
	v_mfma_f32_16x16x32_bf16 v[78:81], v[130:133], v[178:181], v[78:81]
	v_mfma_f32_16x16x32_bf16 v[74:77], v[138:141], v[178:181], v[74:77]
	v_mfma_f32_16x16x32_bf16 v[70:73], v[130:133], v[186:189], v[70:73]
	v_mfma_f32_16x16x32_bf16 v[66:69], v[138:141], v[186:189], v[66:69]
	v_mfma_f32_16x16x32_bf16 v[94:97], v[134:137], v[162:165], v[94:97]
	v_mfma_f32_16x16x32_bf16 v[90:93], v[142:145], v[162:165], v[90:93]
	v_mfma_f32_16x16x32_bf16 v[86:89], v[134:137], v[170:173], v[86:89]
	v_mfma_f32_16x16x32_bf16 v[82:85], v[142:145], v[170:173], v[82:85]
	v_mfma_f32_16x16x32_bf16 v[78:81], v[134:137], v[182:185], v[78:81]
	v_mfma_f32_16x16x32_bf16 v[74:77], v[142:145], v[182:185], v[74:77]
	v_mfma_f32_16x16x32_bf16 v[70:73], v[134:137], v[190:193], v[70:73]
	v_mfma_f32_16x16x32_bf16 v[66:69], v[142:145], v[190:193], v[66:69]
	s_setprio 0
	s_barrier
	s_add_u32 s96, s20, 0x80000
	s_addc_u32 s97, s21, 0
	s_mov_b32 m0, s49
	s_nop 0
	global_load_lds_dwordx4 v148, s[96:97]
	s_mov_b32 m0, s50
	s_nop 0
	global_load_lds_dwordx4 v152, s[96:97]
	s_waitcnt vmcnt(6)
	s_barrier
	s_setprio 1
	v_mfma_f32_16x16x32_bf16 v[30:33], v[194:197], v[158:161], v[30:33]
	v_mfma_f32_16x16x32_bf16 v[26:29], v[202:205], v[158:161], v[26:29]
	v_mfma_f32_16x16x32_bf16 v[22:25], v[194:197], v[166:169], v[22:25]
	v_mfma_f32_16x16x32_bf16 v[18:21], v[202:205], v[166:169], v[18:21]
	v_mfma_f32_16x16x32_bf16 v[14:17], v[194:197], v[178:181], v[14:17]
	v_mfma_f32_16x16x32_bf16 v[10:13], v[202:205], v[178:181], v[10:13]
	v_mfma_f32_16x16x32_bf16 v[6:9], v[194:197], v[186:189], v[6:9]
	v_mfma_f32_16x16x32_bf16 v[2:5], v[202:205], v[186:189], v[2:5]
	v_mfma_f32_16x16x32_bf16 v[30:33], v[198:201], v[162:165], v[30:33]
	v_mfma_f32_16x16x32_bf16 v[26:29], v[206:209], v[162:165], v[26:29]
	v_mfma_f32_16x16x32_bf16 v[22:25], v[198:201], v[170:173], v[22:25]
	v_mfma_f32_16x16x32_bf16 v[18:21], v[206:209], v[170:173], v[18:21]
	v_mfma_f32_16x16x32_bf16 v[14:17], v[198:201], v[182:185], v[14:17]
	v_mfma_f32_16x16x32_bf16 v[10:13], v[206:209], v[182:185], v[10:13]
	v_mfma_f32_16x16x32_bf16 v[6:9], v[198:201], v[190:193], v[6:9]
	v_mfma_f32_16x16x32_bf16 v[2:5], v[206:209], v[190:193], v[2:5]
	s_setprio 0
	s_barrier
	ds_read_b128 v[130:133], v238
	ds_read_b128 v[134:137], v238 offset:1024
	ds_read_b128 v[138:141], v238 offset:2048
	ds_read_b128 v[142:145], v238 offset:3072
	s_add_u32 s22, s22, 0x80000
	s_addc_u32 s23, s23, 0
	s_mov_b32 m0, s51
	ds_read_b128 v[158:161], v176 offset:32768
	ds_read_b128 v[162:165], v176 offset:33792
	ds_read_b128 v[166:169], v176 offset:34816
	ds_read_b128 v[170:173], v176 offset:35840
	ds_read_b128 v[178:181], v176 offset:36864
	ds_read_b128 v[182:185], v176 offset:37888
	ds_read_b128 v[186:189], v176 offset:38912
	ds_read_b128 v[190:193], v176 offset:39936
	global_load_lds_dwordx4 v146, s[22:23]
	s_mov_b32 m0, s65
	s_nop 0
	global_load_lds_dwordx4 v150, s[22:23]
	s_waitcnt lgkmcnt(8)
	s_barrier
	s_waitcnt lgkmcnt(0)
	s_setprio 1
	s_waitcnt lgkmcnt(0)
	v_mfma_f32_16x16x32_bf16 v[126:129], v[130:133], v[158:161], v[126:129]
	v_mfma_f32_16x16x32_bf16 v[122:125], v[138:141], v[158:161], v[122:125]
	v_mfma_f32_16x16x32_bf16 v[118:121], v[130:133], v[166:169], v[118:121]
	v_mfma_f32_16x16x32_bf16 v[114:117], v[138:141], v[166:169], v[114:117]
	v_mfma_f32_16x16x32_bf16 v[110:113], v[130:133], v[178:181], v[110:113]
	v_mfma_f32_16x16x32_bf16 v[106:109], v[138:141], v[178:181], v[106:109]
	v_mfma_f32_16x16x32_bf16 v[102:105], v[130:133], v[186:189], v[102:105]
	v_mfma_f32_16x16x32_bf16 v[98:101], v[138:141], v[186:189], v[98:101]
	v_mfma_f32_16x16x32_bf16 v[126:129], v[134:137], v[162:165], v[126:129]
	v_mfma_f32_16x16x32_bf16 v[122:125], v[142:145], v[162:165], v[122:125]
	v_mfma_f32_16x16x32_bf16 v[118:121], v[134:137], v[170:173], v[118:121]
	v_mfma_f32_16x16x32_bf16 v[114:117], v[142:145], v[170:173], v[114:117]
	v_mfma_f32_16x16x32_bf16 v[110:113], v[134:137], v[182:185], v[110:113]
	v_mfma_f32_16x16x32_bf16 v[106:109], v[142:145], v[182:185], v[106:109]
	v_mfma_f32_16x16x32_bf16 v[102:105], v[134:137], v[190:193], v[102:105]
	v_mfma_f32_16x16x32_bf16 v[98:101], v[142:145], v[190:193], v[98:101]
	s_setprio 0
	s_barrier
; #define PG8_STAGE(bufoff, gbase, voff) do { _Pragma("unroll") for (int _i = 0; _i < 2; ++_i) \
;         __builtin_amdgcn_global_load_lds((const unsigned*)((const char*)(gbase) + (voff)[_i]), (LAS unsigned*)(lds + (bufoff) + ldsw + _i * 8192), 16, 0, 0); } while (0)
; #define PG8_LDA(dst, b, h) do { _Pragma("unroll") for (int m = 0; m < 4; ++m) _Pragma("unroll") for (int k = 0; k < 2; ++k) dst[m][k] = *(const LAS bf16x8*)(lds + PG8_SA(b, h) + aoff + m * 2048 + k * 1024); } while (0)
; #define PG8_LDB(dst, b, h) do { _Pragma("unroll") for (int n = 0; n < 2; ++n) _Pragma("unroll") for (int k = 0; k < 2; ++k) dst[n][k] = *(const LAS bf16x8*)(lds + PG8_SB(b, h) + boff + n * 2048 + k * 1024); } while (0)
; #define PG8_MMA(ai, bj, At, Bt) do { __builtin_amdgcn_s_setprio(1); _Pragma("unroll") for (int m = 0; m < 4; ++m) _Pragma("unroll") for (int n = 0; n < 2; ++n) _Pragma("unroll") for (int k = 0; k < 2; ++k) \
;         acc[ai][bj][m][n] = __builtin_amdgcn_mfma_f32_16x16x32_bf16(Bt[n][k], At[m][k], acc[ai][bj][m][n], 0, 0, 0); __builtin_amdgcn_s_setprio(0); } while (0)
; #define PG8_WAIT_L(n) asm volatile("s_waitcnt lgkmcnt(" #n ")" ::: "memory")
; #define PG8_BAR __builtin_amdgcn_s_barrier()
; #define PG8_SCHED __builtin_amdgcn_sched_barrier(0)
; template <class Epi, class Sched>
; __device__ __forceinline__ void gemm_phase(LAS unsigned char* lds_in, const int lda, const int ldb, const Sched& S, const Epi& E, const int WID) {
;     ...
;             PG8_WAIT_L(8); PG8_BAR; PG8_WAIT_L(0); PG8_MMA(0, 0, At, B0); PG8_BAR; PG8_SCHED;
;             PG8_LDB(B1, 1, 1); PG8_STAGE(PG8_SB(1, 0), b3, voffB);
;             PG8_BAR; PG8_WAIT_L(0); PG8_MMA(0, 1, At, B1); PG8_BAR;
;             PG8_LDA(At, 1, 1); PG8_STAGE(PG8_SA(1, 0), a3, voffA);
;             PG8_BAR; PG8_WAIT_L(0); PG8_MMA(1, 0, At, B0); PG8_BAR; PG8_SCHED;
	s_mov_b32 m0, s79
	s_add_u32 s100, s20, 0x80
	s_addc_u32 s101, s21, 0
	ds_read_b128 v[194:197], v239
	ds_read_b128 v[198:201], v239 offset:1024
	ds_read_b128 v[202:205], v239 offset:2048
	ds_read_b128 v[206:209], v239 offset:3072
	global_load_lds_dwordx4 v148, s[100:101]
	s_add_u32 s100, s20, 0x80
	s_addc_u32 s101, s21, 0
	s_mov_b32 m0, s2
	s_nop 0
	global_load_lds_dwordx4 v152, s[100:101]
	s_barrier
	s_waitcnt lgkmcnt(0)
	s_setprio 1
	s_waitcnt lgkmcnt(0)
	v_mfma_f32_16x16x32_bf16 v[62:65], v[194:197], v[158:161], v[62:65]
	v_mfma_f32_16x16x32_bf16 v[58:61], v[202:205], v[158:161], v[58:61]
	v_mfma_f32_16x16x32_bf16 v[54:57], v[194:197], v[166:169], v[54:57]
	v_mfma_f32_16x16x32_bf16 v[50:53], v[202:205], v[166:169], v[50:53]
	v_mfma_f32_16x16x32_bf16 v[46:49], v[194:197], v[178:181], v[46:49]
	v_mfma_f32_16x16x32_bf16 v[42:45], v[202:205], v[178:181], v[42:45]
	v_mfma_f32_16x16x32_bf16 v[38:41], v[194:197], v[186:189], v[38:41]
	v_mfma_f32_16x16x32_bf16 v[34:37], v[202:205], v[186:189], v[34:37]
	v_mfma_f32_16x16x32_bf16 v[62:65], v[198:201], v[162:165], v[62:65]
	v_mfma_f32_16x16x32_bf16 v[58:61], v[206:209], v[162:165], v[58:61]
	v_mfma_f32_16x16x32_bf16 v[54:57], v[198:201], v[170:173], v[54:57]
	v_mfma_f32_16x16x32_bf16 v[50:53], v[206:209], v[170:173], v[50:53]
	v_mfma_f32_16x16x32_bf16 v[46:49], v[198:201], v[182:185], v[46:49]
	v_mfma_f32_16x16x32_bf16 v[42:45], v[206:209], v[182:185], v[42:45]
	v_mfma_f32_16x16x32_bf16 v[38:41], v[198:201], v[190:193], v[38:41]
	v_mfma_f32_16x16x32_bf16 v[34:37], v[206:209], v[190:193], v[34:37]
	s_setprio 0
	s_mov_b32 m0, s4
	s_add_u32 s100, s22, 0xfff80080
	s_addc_u32 s101, s23, -1
	s_barrier
	ds_read_b128 v[158:161], v176 offset:49152
	ds_read_b128 v[162:165], v176 offset:50176
	ds_read_b128 v[166:169], v176 offset:51200
	ds_read_b128 v[170:173], v176 offset:52224
	ds_read_b128 v[178:181], v176 offset:53248
	ds_read_b128 v[182:185], v176 offset:54272
	ds_read_b128 v[186:189], v176 offset:55296
	ds_read_b128 v[190:193], v176 offset:56320
	global_load_lds_dwordx4 v146, s[100:101]
	s_add_u32 s100, s22, 0xfff80080
	s_addc_u32 s101, s23, -1
	s_mov_b32 m0, s5
	s_nop 0
	global_load_lds_dwordx4 v150, s[100:101]
	s_barrier
	s_waitcnt lgkmcnt(0)
	s_setprio 1
	s_waitcnt lgkmcnt(0)
	v_mfma_f32_16x16x32_bf16 v[94:97], v[130:133], v[158:161], v[94:97]
	v_mfma_f32_16x16x32_bf16 v[90:93], v[138:141], v[158:161], v[90:93]
	v_mfma_f32_16x16x32_bf16 v[86:89], v[130:133], v[166:169], v[86:89]
	v_mfma_f32_16x16x32_bf16 v[82:85], v[138:141], v[166:169], v[82:85]
	v_mfma_f32_16x16x32_bf16 v[78:81], v[130:133], v[178:181], v[78:81]
	v_mfma_f32_16x16x32_bf16 v[74:77], v[138:141], v[178:181], v[74:77]
	v_mfma_f32_16x16x32_bf16 v[70:73], v[130:133], v[186:189], v[70:73]
	v_mfma_f32_16x16x32_bf16 v[66:69], v[138:141], v[186:189], v[66:69]
	v_mfma_f32_16x16x32_bf16 v[94:97], v[134:137], v[162:165], v[94:97]
	v_mfma_f32_16x16x32_bf16 v[90:93], v[142:145], v[162:165], v[90:93]
	v_mfma_f32_16x16x32_bf16 v[86:89], v[134:137], v[170:173], v[86:89]
	v_mfma_f32_16x16x32_bf16 v[82:85], v[142:145], v[170:173], v[82:85]
	v_mfma_f32_16x16x32_bf16 v[78:81], v[134:137], v[182:185], v[78:81]
	v_mfma_f32_16x16x32_bf16 v[74:77], v[142:145], v[182:185], v[74:77]
	v_mfma_f32_16x16x32_bf16 v[70:73], v[134:137], v[190:193], v[70:73]
	v_mfma_f32_16x16x32_bf16 v[66:69], v[142:145], v[190:193], v[66:69]
	s_setprio 0
	s_barrier
	s_add_u32 s20, s20, 0x80080
	s_addc_u32 s21, s21, 0
	s_mov_b32 m0, s91
	s_nop 0
	global_load_lds_dwordx4 v148, s[20:21]
	s_mov_b32 m0, s92
	s_nop 0
	global_load_lds_dwordx4 v152, s[20:21]
	s_waitcnt vmcnt(6)
	s_barrier
; __device__ __forceinline__ float rstd_of(float ss) { return rsqrtf(ss * (1.0f / DM) + EPS); }
; __device__ __forceinline__ u32x4 pack8(const f32x4 a, const f32x4 b) { u32x4 w; w.x = cvt_pk_bf16(a[0], a[1]); w.y = cvt_pk_bf16(a[2], a[3]); w.z = cvt_pk_bf16(b[0], b[1]); w.w = cvt_pk_bf16(b[2], b[3]); return w; }
; #define PG8_STAGE(bufoff, gbase, voff) do { _Pragma("unroll") for (int _i = 0; _i < 2; ++_i) \
;         __builtin_amdgcn_global_load_lds((const unsigned*)((const char*)(gbase) + (voff)[_i]), (LAS unsigned*)(lds + (bufoff) + ldsw + _i * 8192), 16, 0, 0); } while (0)
; #define PG8_MMA(ai, bj, At, Bt) do { __builtin_amdgcn_s_setprio(1); _Pragma("unroll") for (int m = 0; m < 4; ++m) _Pragma("unroll") for (int n = 0; n < 2; ++n) _Pragma("unroll") for (int k = 0; k < 2; ++k) \
;         acc[ai][bj][m][n] = __builtin_amdgcn_mfma_f32_16x16x32_bf16(Bt[n][k], At[m][k], acc[ai][bj][m][n], 0, 0, 0); __builtin_amdgcn_s_setprio(0); } while (0)
; template <class Epi, class Sched>
; __device__ __forceinline__ void gemm_phase(LAS unsigned char* lds_in, const int lda, const int ldb, const Sched& S, const Epi& E, const int WID) {
;     ...
;             PG8_BAR; PG8_WAIT_L(0); PG8_MMA(1, 0, At, B0); PG8_BAR; PG8_SCHED;
;             PG8_STAGE(PG8_SB(1, 1), b3 + hstepB, voffB);
;             PG8_WAIT_V(6); PG8_BAR; PG8_MMA(1, 1, At, B1); PG8_BAR;
;         }
;     __device__ __forceinline__ void operator()(const AccT& acc, const Unit& u, int wr, int wc, int fr, int fq) const {
;     ...
;             const bool scat = sample && u.pm < 2;
;             f32x4 rs0[2], rs1[2];
; #pragma unroll
;             for (int bj = 0; bj < 2; ++bj) { const f32x4 a = *(const f32x4*)(SS + col0 + bj * 128), b = *(const f32x4*)(SS + col0 + bj * 128 + 4);
; #pragma unroll
;                 for (int j = 0; j < 4; ++j) { rs0[bj][j] = rstd_of(a[j]); rs1[bj][j] = rstd_of(b[j]); } }
; #pragma unroll
;             for (int ai = 0; ai < 2; ++ai)
; #pragma unroll
;                 for (int m = 0; m < 4; ++m) {
;                     bf16_t* rp = TT + (size_t)(row0 + ai * 128 + m * 16) * CH;
; #pragma unroll
;                     for (int bj = 0; bj < 2; ++bj) {
;                         const u32x4 w = pack8(acc[ai][bj][m][0] * rs0[bj], acc[ai][bj][m][1] * rs1[bj]);
;                         const int tok = col0 + bj * 128;
;                         if (!scat) *(u32x4*)(rp + tok) = w;
	s_setprio 1
	v_mfma_f32_16x16x32_bf16 v[30:33], v[194:197], v[158:161], v[30:33]
	v_mfma_f32_16x16x32_bf16 v[26:29], v[202:205], v[158:161], v[26:29]
	v_mfma_f32_16x16x32_bf16 v[22:25], v[194:197], v[166:169], v[22:25]
	v_mfma_f32_16x16x32_bf16 v[18:21], v[202:205], v[166:169], v[18:21]
	v_mfma_f32_16x16x32_bf16 v[14:17], v[194:197], v[178:181], v[14:17]
	v_mfma_f32_16x16x32_bf16 v[10:13], v[202:205], v[178:181], v[10:13]
	v_mfma_f32_16x16x32_bf16 v[6:9], v[194:197], v[186:189], v[6:9]
	v_mfma_f32_16x16x32_bf16 v[2:5], v[202:205], v[186:189], v[2:5]
	v_mfma_f32_16x16x32_bf16 v[30:33], v[198:201], v[162:165], v[30:33]
	v_mfma_f32_16x16x32_bf16 v[26:29], v[206:209], v[162:165], v[26:29]
	v_mfma_f32_16x16x32_bf16 v[22:25], v[198:201], v[170:173], v[22:25]
	v_mfma_f32_16x16x32_bf16 v[18:21], v[206:209], v[170:173], v[18:21]
	v_mfma_f32_16x16x32_bf16 v[14:17], v[198:201], v[182:185], v[14:17]
	v_mfma_f32_16x16x32_bf16 v[10:13], v[206:209], v[182:185], v[10:13]
	v_mfma_f32_16x16x32_bf16 v[6:9], v[198:201], v[190:193], v[6:9]
	v_mfma_f32_16x16x32_bf16 v[2:5], v[206:209], v[190:193], v[2:5]
	s_setprio 0
	s_add_i32 s70, s70, 2
	s_add_u32 s18, s18, 0x100
	s_addc_u32 s19, s19, 0
	s_add_u32 s1, s1, 0x100
	s_addc_u32 s11, s11, 0
	s_cmp_gt_u32 s70, 29
	s_cbranch_scc0 .LBB0_1040
	s_lshl_b32 s11, s16, 8
	v_lshl_add_u32 v160, s0, 8, v1
	v_or_b32_e32 v158, s11, v175
	s_cmp_lg_u32 s94, 0
	v_ashrrev_i32_e32 v159, 31, v158
	v_ashrrev_i32_e32 v161, 31, v160
	s_cbranch_scc0 .LBB0_1107
	v_lshl_add_u64 v[134:135], v[158:159], 2, s[76:77]
	global_load_dwordx4 v[130:133], v[134:135], off offset:16
	global_load_dwordx4 v[136:139], v[134:135], off
	s_cmp_lt_i32 s0, 2
	s_mov_b32 s0, 0x358637bd
	v_mov_b64_e32 v[140:141], s[0:1]
	s_cselect_b64 s[18:19], -1, 0
	s_mov_b64 s[20:21], -1
	s_waitcnt vmcnt(0)
	v_pk_fma_f32 v[130:131], v[130:131], s[84:85], v[140:141] op_sel_hi:[1,0,0]
	v_pk_fma_f32 v[136:137], v[136:137], s[84:85], v[140:141] op_sel_hi:[1,0,0]
	s_nop 0
	v_mul_f32_e32 v142, 0x4b800000, v136
	v_cmp_gt_f32_e64 s[0:1], s38, v136
	v_cmp_gt_f32_e32 vcc, s38, v137
	s_nop 0
	v_cndmask_b32_e64 v136, v136, v142, s[0:1]
	v_mul_f32_e32 v142, 0x4b800000, v137
	v_cndmask_b32_e32 v137, v137, v142, vcc
	v_rsq_f32_e32 v136, v136
	v_rsq_f32_e32 v137, v137
	s_nop 0
	v_pk_mul_f32 v[142:143], v[136:137], s[88:89] op_sel_hi:[1,0]
	s_nop 0
	v_cndmask_b32_e64 v142, v136, v142, s[0:1]
	v_mul_f32_e32 v136, 0x4b800000, v130
	v_cmp_gt_f32_e64 s[0:1], s38, v130
	v_cndmask_b32_e32 v143, v137, v143, vcc
	v_cmp_gt_f32_e32 vcc, s38, v131
	v_cndmask_b32_e64 v130, v130, v136, s[0:1]
	v_mul_f32_e32 v136, 0x4b800000, v131
	v_cndmask_b32_e32 v131, v131, v136, vcc
	v_rsq_f32_e32 v130, v130
	v_rsq_f32_e32 v131, v131
	s_nop 0
	v_pk_mul_f32 v[136:137], v[130:131], s[88:89] op_sel_hi:[1,0]
	s_nop 0
	v_cndmask_b32_e32 v145, v131, v137, vcc
	v_cndmask_b32_e64 v144, v130, v136, s[0:1]
	v_pk_fma_f32 v[130:131], v[138:139], s[84:85], v[140:141] op_sel_hi:[1,0,0]
	v_lshlrev_b64 v[138:139], 15, v[160:161]
	v_mul_f32_e32 v136, 0x4b800000, v130
	v_cmp_gt_f32_e64 s[0:1], s38, v130
	v_cmp_gt_f32_e32 vcc, s38, v131
	v_lshl_add_u64 v[166:167], s[86:87], 0, v[138:139]
	v_cndmask_b32_e64 v130, v130, v136, s[0:1]
	v_mul_f32_e32 v136, 0x4b800000, v131
	v_cndmask_b32_e32 v131, v131, v136, vcc
	v_rsq_f32_e32 v130, v130
	v_rsq_f32_e32 v131, v131
	v_pk_mul_f32 v[138:139], v[126:127], v[142:143]
	v_pk_mul_f32 v[168:169], v[122:123], v[144:145]
	v_cvt_pk_bf16_f32 v138, v138, v139
	v_pk_mul_f32 v[136:137], v[130:131], s[88:89] op_sel_hi:[1,0]
	s_nop 0
	v_cndmask_b32_e32 v163, v131, v137, vcc
	v_cndmask_b32_e64 v162, v130, v136, s[0:1]
	v_pk_fma_f32 v[130:131], v[132:133], s[84:85], v[140:141] op_sel_hi:[1,0,0]
	v_pk_mul_f32 v[140:141], v[128:129], v[162:163]
	v_mul_f32_e32 v132, 0x4b800000, v130
	v_cmp_gt_f32_e64 s[0:1], s38, v130
	v_cmp_gt_f32_e32 vcc, s38, v131
	v_cvt_pk_bf16_f32 v139, v140, v141
	v_cvt_pk_bf16_f32 v140, v168, v169
	v_lshl_add_u64 v[168:169], v[158:159], 1, v[166:167]
	v_cndmask_b32_e64 v130, v130, v132, s[0:1]
	v_mul_f32_e32 v132, 0x4b800000, v131
	v_cndmask_b32_e32 v131, v131, v132, vcc
	v_rsq_f32_e32 v130, v130
	v_rsq_f32_e32 v131, v131
	s_nop 0
	v_pk_mul_f32 v[132:133], v[130:131], s[88:89] op_sel_hi:[1,0]
	s_nop 0
	v_cndmask_b32_e32 v165, v131, v133, vcc
	v_cndmask_b32_e64 v164, v130, v132, s[0:1]
	global_load_dwordx4 v[130:133], v[134:135], off offset:528
	s_nop 0
	global_load_dwordx4 v[134:137], v[134:135], off offset:512
	v_readlane_b32 s0, v255, 10
	v_readlane_b32 s1, v255, 11
	s_and_b64 s[0:1], s[0:1], s[18:19]
	s_and_b64 vcc, exec, s[0:1]
	v_pk_mul_f32 v[170:171], v[124:125], v[164:165]
	s_nop 0
	v_cvt_pk_bf16_f32 v141, v170, v171
	s_cbranch_vccnz .LBB0_1044
	s_mov_b64 s[20:21], 0
	global_store_dwordx4 v[168:169], v[138:141], off
